# v29 with the staging write/load pairs placed earlier in the k-iteration (0.02..0.65 of the MFMA slots instead of 0.05..0.80)
# baseline (speedup 1.0000x reference)
; DI f32x4 mfma16(bf16x8 a, bf16x8 b, f32x4 c) { return __builtin_amdgcn_mfma_f32_16x16x32_bf16(a, b, c, 0, 0, 0); }
; template <int MI, int NJ, bool SWAP, class AP, class BP>
; DI void gemm_main(f32x4 (&acc)[MI][NJ], const AP& ap, int a_kstep, const BP& bp, int b_kstep, int nk, bf16_t* smem) {
;     ...
;   auto gload = [&](int kt) {
;     const bf16_t* ab = ap.base + (size_t)kt * a_kstep; const bf16_t* bb = bp.base + (size_t)kt * b_kstep;
; #pragma unroll
;     for (int i = 0; i < CA; ++i) ra[i] = *(const u32x4*)(ab + pa[i]);
; #pragma unroll
;     for (int i = 0; i < CB; ++i) rb[i] = *(const u32x4*)(bb + pb[i]);
;   };
;   auto sstore = [&](int buf) {
;     bf16_t* As = smem + buf * L::STAGE; bf16_t* Bs = As + L::A_ELEMS;
; #pragma unroll
;     for (int i = 0; i < CA; ++i) { const int c = tid + NTHR * i; *(u32x4*)(As + (c >> 3) * LDT + (c & 7) * 8) = oka[i] ? ra[i] : (u32x4){0u, 0u, 0u, 0u}; }
; #pragma unroll
;     for (int i = 0; i < CB; ++i) { const int c = tid + NTHR * i; *(u32x4*)(Bs + (c >> 3) * LDT + (c & 7) * 8) = rb[i]; }
;   };
;   gload(0); sstore(0); gload(nk > 1 ? 1 : 0); __syncthreads();
; #pragma unroll 1
;   for (int kt = 0; kt < nk; ++kt) {
;     const int buf = kt & 1;
;     sstore(buf ^ 1);
;     gload(kt + 2 < nk ? kt + 2 : nk - 1);
;     __builtin_amdgcn_sched_barrier(0);
;     const bf16_t* As = smem + buf * L::STAGE + (wm * 16 * MI + l15) * LDT + quad * 8;
;     const bf16_t* Bs = smem + buf * L::STAGE + L::A_ELEMS + (wn * 16 * NJ + l15) * LDT + quad * 8;
; #pragma unroll
;     for (int ks = 0; ks < 2; ++ks) {
;       if (MI * NJ >= 32 && ks == 1) asm volatile("" ::: "memory");
;       bf16x8 b[NJ];
; #pragma unroll
;       for (int j = 0; j < NJ; ++j) b[j] = *(const bf16x8*)(Bs + j * 16 * LDT + ks * 32);
; #pragma unroll
;       for (int i = 0; i < MI; ++i) {
;         const bf16x8 a = *(const bf16x8*)(As + i * 16 * LDT + ks * 32);
; #pragma unroll
;         for (int j = 0; j < NJ; ++j) acc[i][j] = SWAP ? mfma16(b[j], a, acc[i][j]) : mfma16(a, b[j], acc[i][j]);
;       }
;     }
;     __syncthreads();
.Lgm0_main:
	ds_read_b128 v[242:245], v176 offset:4608
	s_waitcnt lgkmcnt(4)
	v_mfma_f32_16x16x32_bf16 v[124:127], v[178:181], v[212:215], v[124:127]
	s_and_b32 s5, s4, 1
	s_min_u32 s6, s4, 13
	s_xor_b32 s7, s5, 1
	s_mul_i32 s7, s7, 0x12000
	v_add3_u32 v250, s7, v171, v169
	s_waitcnt vmcnt(7)
	ds_write_b128 v250, v[128:131]
	s_waitcnt lgkmcnt(4)
	v_mfma_f32_16x16x32_bf16 v[120:123], v[200:203], v[212:215], v[120:123]
	s_waitcnt lgkmcnt(3)
	v_mfma_f32_16x16x32_bf16 v[116:119], v[204:207], v[212:215], v[116:119]
	s_lshl_b32 s33, s6, 7
	s_add_u32 s6, s0, s33
	v_add3_u32 v251, s7, v173, v169
	v_add3_u32 v252, s7, v174, v169
	v_add3_u32 v253, s7, v175, v169
	s_addc_u32 s7, s1, 0
	v_lshl_add_u64 v[128:129], s[6:7], 0, v[160:161]
	s_nop 0
	global_load_dwordx4 v[128:131], v[128:129], off offset:256
	s_waitcnt lgkmcnt(2)
	v_mfma_f32_16x16x32_bf16 v[112:115], v[208:211], v[212:215], v[112:115]
	ds_read_b128 v[246:249], v176 offset:6912
	v_mfma_f32_16x16x32_bf16 v[108:111], v[178:181], v[216:219], v[108:111]
	v_mfma_f32_16x16x32_bf16 v[104:107], v[200:203], v[216:219], v[104:107]
	s_waitcnt vmcnt(7)
	ds_write_b128 v251, v[132:135]
	v_mfma_f32_16x16x32_bf16 v[100:103], v[204:207], v[216:219], v[100:103]
	v_mfma_f32_16x16x32_bf16 v[96:99], v[208:211], v[216:219], v[96:99]
	v_lshl_add_u64 v[132:133], s[6:7], 0, v[162:163]
	s_nop 0
	global_load_dwordx4 v[132:135], v[132:133], off offset:256
	ds_read_b128 v[212:215], v176 offset:9216
	s_waitcnt lgkmcnt(4)
	v_mfma_f32_16x16x32_bf16 v[92:95], v[178:181], v[242:245], v[92:95]
	v_mfma_f32_16x16x32_bf16 v[88:91], v[200:203], v[242:245], v[88:91]
	v_mfma_f32_16x16x32_bf16 v[84:87], v[204:207], v[242:245], v[84:87]
	s_waitcnt vmcnt(7)
	ds_write_b128 v252, v[136:139]
	v_mfma_f32_16x16x32_bf16 v[80:83], v[208:211], v[242:245], v[80:83]
	ds_read_b128 v[216:219], v176 offset:11520
	s_waitcnt lgkmcnt(4)
	v_mfma_f32_16x16x32_bf16 v[76:79], v[178:181], v[246:249], v[76:79]
	v_lshl_add_u64 v[136:137], s[6:7], 0, v[164:165]
	s_nop 0
	global_load_dwordx4 v[136:139], v[136:137], off offset:256
	v_mfma_f32_16x16x32_bf16 v[72:75], v[200:203], v[246:249], v[72:75]
	v_mfma_f32_16x16x32_bf16 v[68:71], v[204:207], v[246:249], v[68:71]
	v_mfma_f32_16x16x32_bf16 v[64:67], v[208:211], v[246:249], v[64:67]
	s_waitcnt vmcnt(7)
	ds_write_b128 v253, v[140:143]
	ds_read_b128 v[242:245], v176 offset:13824
	s_waitcnt lgkmcnt(4)
	v_mfma_f32_16x16x32_bf16 v[60:63], v[178:181], v[212:215], v[60:63]
	v_mfma_f32_16x16x32_bf16 v[56:59], v[200:203], v[212:215], v[56:59]
	v_lshl_add_u64 v[140:141], s[6:7], 0, v[166:167]
	s_nop 0
	global_load_dwordx4 v[140:143], v[140:141], off offset:256
	v_mfma_f32_16x16x32_bf16 v[52:55], v[204:207], v[212:215], v[52:55]
	v_mfma_f32_16x16x32_bf16 v[48:51], v[208:211], v[212:215], v[48:51]
	ds_read_b128 v[246:249], v176 offset:16128
	s_waitcnt lgkmcnt(3)
	v_mfma_f32_16x16x32_bf16 v[44:47], v[178:181], v[216:219], v[44:47]
	s_waitcnt vmcnt(7)
	ds_write_b128 v250, v[144:147] offset:36864
	v_mfma_f32_16x16x32_bf16 v[40:43], v[200:203], v[216:219], v[40:43]
	v_mfma_f32_16x16x32_bf16 v[36:39], v[204:207], v[216:219], v[36:39]
	s_add_u32 s6, s2, s33
	s_addc_u32 s7, s3, 0
	v_lshl_add_u64 v[144:145], s[6:7], 0, v[160:161]
	s_nop 0
	global_load_dwordx4 v[144:147], v[144:145], off offset:256
	v_mfma_f32_16x16x32_bf16 v[32:35], v[208:211], v[216:219], v[32:35]
	ds_read_b128 v[212:215], v176 offset:64
	s_waitcnt lgkmcnt(3)
	v_mfma_f32_16x16x32_bf16 v[28:31], v[178:181], v[242:245], v[28:31]
	v_mfma_f32_16x16x32_bf16 v[24:27], v[200:203], v[242:245], v[24:27]
	s_waitcnt vmcnt(7)
	ds_write_b128 v251, v[148:151] offset:36864
	v_mfma_f32_16x16x32_bf16 v[20:23], v[204:207], v[242:245], v[20:23]
	v_mfma_f32_16x16x32_bf16 v[16:19], v[208:211], v[242:245], v[16:19]
	v_lshl_add_u64 v[148:149], s[6:7], 0, v[162:163]
	s_nop 0
	global_load_dwordx4 v[148:151], v[148:149], off offset:256
	ds_read_b128 v[216:219], v176 offset:2368
	s_waitcnt lgkmcnt(4)
	v_mfma_f32_16x16x32_bf16 v[12:15], v[178:181], v[246:249], v[12:15]
	ds_read_b128 v[178:181], v182 offset:36928
	v_mfma_f32_16x16x32_bf16 v[8:11], v[200:203], v[246:249], v[8:11]
	ds_read_b128 v[200:203], v182 offset:39232
	v_mfma_f32_16x16x32_bf16 v[0:3], v[204:207], v[246:249], v[0:3]
	ds_read_b128 v[204:207], v182 offset:41536
	s_waitcnt vmcnt(7)
	ds_write_b128 v252, v[152:155] offset:36864
	v_mfma_f32_16x16x32_bf16 v[4:7], v[208:211], v[246:249], v[4:7]
	ds_read_b128 v[208:211], v182 offset:43840
	ds_read_b128 v[242:245], v176 offset:4672
	s_waitcnt lgkmcnt(5)
	v_mfma_f32_16x16x32_bf16 v[124:127], v[178:181], v[212:215], v[124:127]
	v_lshl_add_u64 v[152:153], s[6:7], 0, v[164:165]
	s_nop 0
	global_load_dwordx4 v[152:155], v[152:153], off offset:256
	s_waitcnt lgkmcnt(4)
	v_mfma_f32_16x16x32_bf16 v[120:123], v[200:203], v[212:215], v[120:123]
	s_waitcnt lgkmcnt(3)
	v_mfma_f32_16x16x32_bf16 v[116:119], v[204:207], v[212:215], v[116:119]
	s_waitcnt lgkmcnt(1)
	v_mfma_f32_16x16x32_bf16 v[112:115], v[208:211], v[212:215], v[112:115]
	s_waitcnt vmcnt(7)
	ds_write_b128 v253, v[156:159] offset:36864
	ds_read_b128 v[246:249], v176 offset:6976
	v_mfma_f32_16x16x32_bf16 v[108:111], v[178:181], v[216:219], v[108:111]
	v_mfma_f32_16x16x32_bf16 v[104:107], v[200:203], v[216:219], v[104:107]
	v_lshl_add_u64 v[156:157], s[6:7], 0, v[166:167]
	s_nop 0
	global_load_dwordx4 v[156:159], v[156:157], off offset:256
	v_mfma_f32_16x16x32_bf16 v[100:103], v[204:207], v[216:219], v[100:103]
	v_mfma_f32_16x16x32_bf16 v[96:99], v[208:211], v[216:219], v[96:99]
	ds_read_b128 v[212:215], v176 offset:9280
	s_waitcnt lgkmcnt(3)
	v_mfma_f32_16x16x32_bf16 v[92:95], v[178:181], v[242:245], v[92:95]
	v_mfma_f32_16x16x32_bf16 v[88:91], v[200:203], v[242:245], v[88:91]
	v_mfma_f32_16x16x32_bf16 v[84:87], v[204:207], v[242:245], v[84:87]
	v_mfma_f32_16x16x32_bf16 v[80:83], v[208:211], v[242:245], v[80:83]
	ds_read_b128 v[216:219], v176 offset:11584
	s_waitcnt lgkmcnt(2)
	v_mfma_f32_16x16x32_bf16 v[76:79], v[178:181], v[246:249], v[76:79]
	v_mfma_f32_16x16x32_bf16 v[72:75], v[200:203], v[246:249], v[72:75]
	v_mfma_f32_16x16x32_bf16 v[68:71], v[204:207], v[246:249], v[68:71]
	v_mfma_f32_16x16x32_bf16 v[64:67], v[208:211], v[246:249], v[64:67]
	ds_read_b128 v[242:245], v176 offset:13888
	s_waitcnt lgkmcnt(2)
	v_mfma_f32_16x16x32_bf16 v[60:63], v[178:181], v[212:215], v[60:63]
	v_mfma_f32_16x16x32_bf16 v[56:59], v[200:203], v[212:215], v[56:59]
	v_mfma_f32_16x16x32_bf16 v[52:55], v[204:207], v[212:215], v[52:55]
	v_mfma_f32_16x16x32_bf16 v[48:51], v[208:211], v[212:215], v[48:51]
	ds_read_b128 v[246:249], v176 offset:16192
	s_waitcnt lgkmcnt(2)
	v_mfma_f32_16x16x32_bf16 v[44:47], v[178:181], v[216:219], v[44:47]
	v_mfma_f32_16x16x32_bf16 v[40:43], v[200:203], v[216:219], v[40:43]
	v_mfma_f32_16x16x32_bf16 v[36:39], v[204:207], v[216:219], v[36:39]
	v_mfma_f32_16x16x32_bf16 v[32:35], v[208:211], v[216:219], v[32:35]
	s_add_i32 s4, s4, 1
	s_and_b32 s98, s4, 1
	s_mul_i32 s98, s98, 0x12000
	v_add3_u32 v182, s98, v168, v172
	v_add3_u32 v176, s98, v170, v172
	s_cmp_lg_u32 s4, 16
	s_waitcnt lgkmcnt(0)
	s_barrier
; DI f32x4 mfma16(bf16x8 a, bf16x8 b, f32x4 c) { return __builtin_amdgcn_mfma_f32_16x16x32_bf16(a, b, c, 0, 0, 0); }
; template <int MI, int NJ, bool SWAP, class AP, class BP>
; DI void gemm_main(f32x4 (&acc)[MI][NJ], const AP& ap, int a_kstep, const BP& bp, int b_kstep, int nk, bf16_t* smem) {
;     ...
;     const bf16_t* As = smem + buf * L::STAGE + (wm * 16 * MI + l15) * LDT + quad * 8;
;     const bf16_t* Bs = smem + buf * L::STAGE + L::A_ELEMS + (wn * 16 * NJ + l15) * LDT + quad * 8;
; #pragma unroll
;     for (int ks = 0; ks < 2; ++ks) {
;       if (MI * NJ >= 32 && ks == 1) asm volatile("" ::: "memory");
;       bf16x8 b[NJ];
; #pragma unroll
;       for (int j = 0; j < NJ; ++j) b[j] = *(const bf16x8*)(Bs + j * 16 * LDT + ks * 32);
; #pragma unroll
;       for (int i = 0; i < MI; ++i) {
;         const bf16x8 a = *(const bf16x8*)(As + i * 16 * LDT + ks * 32);
; #pragma unroll
;         for (int j = 0; j < NJ; ++j) acc[i][j] = SWAP ? mfma16(b[j], a, acc[i][j]) : mfma16(a, b[j], acc[i][j]);
;       }
;     }
;     __syncthreads();
	s_cbranch_scc0 .Lgm0_exit
	ds_read_b128 v[212:215], v176
	ds_read_b128 v[216:219], v176 offset:2304
	v_mfma_f32_16x16x32_bf16 v[28:31], v[178:181], v[242:245], v[28:31]
	v_mfma_f32_16x16x32_bf16 v[12:15], v[178:181], v[246:249], v[12:15]
	ds_read_b128 v[178:181], v182 offset:36864
	v_mfma_f32_16x16x32_bf16 v[24:27], v[200:203], v[242:245], v[24:27]
	v_mfma_f32_16x16x32_bf16 v[8:11], v[200:203], v[246:249], v[8:11]
	ds_read_b128 v[200:203], v182 offset:39168
	v_mfma_f32_16x16x32_bf16 v[20:23], v[204:207], v[242:245], v[20:23]
	v_mfma_f32_16x16x32_bf16 v[0:3], v[204:207], v[246:249], v[0:3]
	ds_read_b128 v[204:207], v182 offset:41472
	v_mfma_f32_16x16x32_bf16 v[16:19], v[208:211], v[242:245], v[16:19]
	v_mfma_f32_16x16x32_bf16 v[4:7], v[208:211], v[246:249], v[4:7]
	ds_read_b128 v[208:211], v182 offset:43776
	s_branch .Lgm0_main

; DI f32x4 mfma16(bf16x8 a, bf16x8 b, f32x4 c) { return __builtin_amdgcn_mfma_f32_16x16x32_bf16(a, b, c, 0, 0, 0); }
; template <int MI, int NJ, bool SWAP, class AP, class BP>
; DI void gemm_main(f32x4 (&acc)[MI][NJ], const AP& ap, int a_kstep, const BP& bp, int b_kstep, int nk, bf16_t* smem) {
;     ...
;   auto gload = [&](int kt) {
;     const bf16_t* ab = ap.base + (size_t)kt * a_kstep; const bf16_t* bb = bp.base + (size_t)kt * b_kstep;
; #pragma unroll
;     for (int i = 0; i < CA; ++i) ra[i] = *(const u32x4*)(ab + pa[i]);
; #pragma unroll
;     for (int i = 0; i < CB; ++i) rb[i] = *(const u32x4*)(bb + pb[i]);
;   };
;   auto sstore = [&](int buf) {
;     bf16_t* As = smem + buf * L::STAGE; bf16_t* Bs = As + L::A_ELEMS;
; #pragma unroll
;     for (int i = 0; i < CA; ++i) { const int c = tid + NTHR * i; *(u32x4*)(As + (c >> 3) * LDT + (c & 7) * 8) = oka[i] ? ra[i] : (u32x4){0u, 0u, 0u, 0u}; }
; #pragma unroll
;     for (int i = 0; i < CB; ++i) { const int c = tid + NTHR * i; *(u32x4*)(Bs + (c >> 3) * LDT + (c & 7) * 8) = rb[i]; }
;   };
;   gload(0); sstore(0); gload(nk > 1 ? 1 : 0); __syncthreads();
; #pragma unroll 1
;   for (int kt = 0; kt < nk; ++kt) {
;     const int buf = kt & 1;
;     sstore(buf ^ 1);
;     gload(kt + 2 < nk ? kt + 2 : nk - 1);
;     __builtin_amdgcn_sched_barrier(0);
;     const bf16_t* As = smem + buf * L::STAGE + (wm * 16 * MI + l15) * LDT + quad * 8;
;     const bf16_t* Bs = smem + buf * L::STAGE + L::A_ELEMS + (wn * 16 * NJ + l15) * LDT + quad * 8;
; #pragma unroll
;     for (int ks = 0; ks < 2; ++ks) {
;       if (MI * NJ >= 32 && ks == 1) asm volatile("" ::: "memory");
;       bf16x8 b[NJ];
; #pragma unroll
;       for (int j = 0; j < NJ; ++j) b[j] = *(const bf16x8*)(Bs + j * 16 * LDT + ks * 32);
; #pragma unroll
;       for (int i = 0; i < MI; ++i) {
;         const bf16x8 a = *(const bf16x8*)(As + i * 16 * LDT + ks * 32);
; #pragma unroll
;         for (int j = 0; j < NJ; ++j) acc[i][j] = SWAP ? mfma16(b[j], a, acc[i][j]) : mfma16(a, b[j], acc[i][j]);
;       }
;     }
;     __syncthreads();
.Lgm1_main:
	ds_read_b128 v[242:245], v176 offset:4608
	s_waitcnt lgkmcnt(4)
	v_mfma_f32_16x16x32_bf16 v[124:127], v[212:215], v[178:181], v[124:127]
	v_lshlrev_b32_e32 v250, 1, v168
	s_and_b32 s5, s4, 1
	s_min_u32 s6, s4, 13
	s_xor_b32 s7, s5, 1
	s_mul_i32 s7, s7, 0x12000
	v_add3_u32 v250, s7, v250, v170
	s_waitcnt vmcnt(7)
	ds_write_b128 v250, v[128:131]
	s_waitcnt lgkmcnt(4)
	v_mfma_f32_16x16x32_bf16 v[120:123], v[212:215], v[200:203], v[120:123]
	s_waitcnt lgkmcnt(3)
	v_mfma_f32_16x16x32_bf16 v[116:119], v[212:215], v[204:207], v[116:119]
	s_lshl_b32 s33, s6, 7
	s_add_u32 s6, s0, s33
	v_lshlrev_b32_e32 v251, 1, v171
	v_add3_u32 v251, s7, v251, v170
	v_lshlrev_b32_e32 v252, 1, v172
	v_add3_u32 v252, s7, v252, v170
	v_lshlrev_b32_e32 v253, 1, v173
	v_add3_u32 v253, s7, v253, v170
	s_addc_u32 s7, s1, 0
	v_lshl_add_u64 v[128:129], s[6:7], 0, v[160:161]
	s_nop 0
	global_load_dwordx4 v[128:131], v[128:129], off offset:256
	s_waitcnt lgkmcnt(2)
	v_mfma_f32_16x16x32_bf16 v[112:115], v[212:215], v[208:211], v[112:115]
	ds_read_b128 v[246:249], v176 offset:6912
	v_mfma_f32_16x16x32_bf16 v[108:111], v[216:219], v[178:181], v[108:111]
	v_mfma_f32_16x16x32_bf16 v[104:107], v[216:219], v[200:203], v[104:107]
	s_waitcnt vmcnt(7)
	ds_write_b128 v251, v[132:135]
	v_mfma_f32_16x16x32_bf16 v[100:103], v[216:219], v[204:207], v[100:103]
	v_mfma_f32_16x16x32_bf16 v[96:99], v[216:219], v[208:211], v[96:99]
	v_lshl_add_u64 v[132:133], s[6:7], 0, v[162:163]
	s_nop 0
	global_load_dwordx4 v[132:135], v[132:133], off offset:256
	ds_read_b128 v[212:215], v176 offset:9216
	s_waitcnt lgkmcnt(4)
	v_mfma_f32_16x16x32_bf16 v[92:95], v[242:245], v[178:181], v[92:95]
	v_mfma_f32_16x16x32_bf16 v[88:91], v[242:245], v[200:203], v[88:91]
	v_mfma_f32_16x16x32_bf16 v[84:87], v[242:245], v[204:207], v[84:87]
	s_waitcnt vmcnt(7)
	ds_write_b128 v252, v[136:139]
	v_mfma_f32_16x16x32_bf16 v[80:83], v[242:245], v[208:211], v[80:83]
	ds_read_b128 v[216:219], v176 offset:11520
	s_waitcnt lgkmcnt(4)
	v_mfma_f32_16x16x32_bf16 v[76:79], v[246:249], v[178:181], v[76:79]
	v_lshl_add_u64 v[136:137], s[6:7], 0, v[164:165]
	s_nop 0
	global_load_dwordx4 v[136:139], v[136:137], off offset:256
	v_mfma_f32_16x16x32_bf16 v[72:75], v[246:249], v[200:203], v[72:75]
	v_mfma_f32_16x16x32_bf16 v[68:71], v[246:249], v[204:207], v[68:71]
	v_mfma_f32_16x16x32_bf16 v[64:67], v[246:249], v[208:211], v[64:67]
	s_waitcnt vmcnt(7)
	ds_write_b128 v253, v[140:143]
	ds_read_b128 v[242:245], v176 offset:13824
	s_waitcnt lgkmcnt(4)
	v_mfma_f32_16x16x32_bf16 v[60:63], v[212:215], v[178:181], v[60:63]
	v_mfma_f32_16x16x32_bf16 v[56:59], v[212:215], v[200:203], v[56:59]
	v_lshl_add_u64 v[140:141], s[6:7], 0, v[166:167]
	s_nop 0
	global_load_dwordx4 v[140:143], v[140:141], off offset:256
	v_mfma_f32_16x16x32_bf16 v[52:55], v[212:215], v[204:207], v[52:55]
	v_mfma_f32_16x16x32_bf16 v[48:51], v[212:215], v[208:211], v[48:51]
	ds_read_b128 v[246:249], v176 offset:16128
	s_waitcnt lgkmcnt(3)
	v_mfma_f32_16x16x32_bf16 v[44:47], v[216:219], v[178:181], v[44:47]
	s_waitcnt vmcnt(7)
	ds_write_b128 v250, v[144:147] offset:36864
	v_mfma_f32_16x16x32_bf16 v[40:43], v[216:219], v[200:203], v[40:43]
	v_mfma_f32_16x16x32_bf16 v[36:39], v[216:219], v[204:207], v[36:39]
	s_add_u32 s6, s2, s33
	s_addc_u32 s7, s3, 0
	v_lshl_add_u64 v[144:145], s[6:7], 0, v[160:161]
	s_nop 0
	global_load_dwordx4 v[144:147], v[144:145], off offset:256
	v_mfma_f32_16x16x32_bf16 v[32:35], v[216:219], v[208:211], v[32:35]
	ds_read_b128 v[212:215], v176 offset:64
	s_waitcnt lgkmcnt(3)
	v_mfma_f32_16x16x32_bf16 v[28:31], v[242:245], v[178:181], v[28:31]
	v_mfma_f32_16x16x32_bf16 v[24:27], v[242:245], v[200:203], v[24:27]
	s_waitcnt vmcnt(7)
	ds_write_b128 v251, v[148:151] offset:36864
	v_mfma_f32_16x16x32_bf16 v[20:23], v[242:245], v[204:207], v[20:23]
	v_mfma_f32_16x16x32_bf16 v[16:19], v[242:245], v[208:211], v[16:19]
	v_lshl_add_u64 v[148:149], s[6:7], 0, v[162:163]
	s_nop 0
	global_load_dwordx4 v[148:151], v[148:149], off offset:256
	ds_read_b128 v[216:219], v176 offset:2368
	s_waitcnt lgkmcnt(4)
; DI f32x4 mfma16(bf16x8 a, bf16x8 b, f32x4 c) { return __builtin_amdgcn_mfma_f32_16x16x32_bf16(a, b, c, 0, 0, 0); }
; template <int MI, int NJ, bool SWAP, class AP, class BP>
; DI void gemm_main(f32x4 (&acc)[MI][NJ], const AP& ap, int a_kstep, const BP& bp, int b_kstep, int nk, bf16_t* smem) {
;     ...
;   auto gload = [&](int kt) {
;     const bf16_t* ab = ap.base + (size_t)kt * a_kstep; const bf16_t* bb = bp.base + (size_t)kt * b_kstep;
; #pragma unroll
;     for (int i = 0; i < CA; ++i) ra[i] = *(const u32x4*)(ab + pa[i]);
; #pragma unroll
;     for (int i = 0; i < CB; ++i) rb[i] = *(const u32x4*)(bb + pb[i]);
;   };
;   auto sstore = [&](int buf) {
;     bf16_t* As = smem + buf * L::STAGE; bf16_t* Bs = As + L::A_ELEMS;
; #pragma unroll
;     for (int i = 0; i < CA; ++i) { const int c = tid + NTHR * i; *(u32x4*)(As + (c >> 3) * LDT + (c & 7) * 8) = oka[i] ? ra[i] : (u32x4){0u, 0u, 0u, 0u}; }
; #pragma unroll
;     for (int i = 0; i < CB; ++i) { const int c = tid + NTHR * i; *(u32x4*)(Bs + (c >> 3) * LDT + (c & 7) * 8) = rb[i]; }
;   };
;   gload(0); sstore(0); gload(nk > 1 ? 1 : 0); __syncthreads();
; #pragma unroll 1
;   for (int kt = 0; kt < nk; ++kt) {
;     const int buf = kt & 1;
;     sstore(buf ^ 1);
;     gload(kt + 2 < nk ? kt + 2 : nk - 1);
;     __builtin_amdgcn_sched_barrier(0);
;     const bf16_t* As = smem + buf * L::STAGE + (wm * 16 * MI + l15) * LDT + quad * 8;
;     const bf16_t* Bs = smem + buf * L::STAGE + L::A_ELEMS + (wn * 16 * NJ + l15) * LDT + quad * 8;
; #pragma unroll
;     for (int ks = 0; ks < 2; ++ks) {
;       if (MI * NJ >= 32 && ks == 1) asm volatile("" ::: "memory");
;       bf16x8 b[NJ];
; #pragma unroll
;       for (int j = 0; j < NJ; ++j) b[j] = *(const bf16x8*)(Bs + j * 16 * LDT + ks * 32);
; #pragma unroll
;       for (int i = 0; i < MI; ++i) {
;         const bf16x8 a = *(const bf16x8*)(As + i * 16 * LDT + ks * 32);
; #pragma unroll
;         for (int j = 0; j < NJ; ++j) acc[i][j] = SWAP ? mfma16(b[j], a, acc[i][j]) : mfma16(a, b[j], acc[i][j]);
;       }
;     }
;     __syncthreads();
	v_mfma_f32_16x16x32_bf16 v[8:11], v[246:249], v[178:181], v[8:11]
	ds_read_b128 v[178:181], v182 offset:36928
	v_mfma_f32_16x16x32_bf16 v[4:7], v[246:249], v[200:203], v[4:7]
	ds_read_b128 v[200:203], v182 offset:39232
	v_mfma_f32_16x16x32_bf16 v[0:3], v[246:249], v[204:207], v[0:3]
	ds_read_b128 v[204:207], v182 offset:41536
	s_waitcnt vmcnt(7)
	ds_write_b128 v252, v[152:155] offset:36864
	v_mfma_f32_16x16x32_bf16 v[12:15], v[246:249], v[208:211], v[12:15]
	ds_read_b128 v[208:211], v182 offset:43840
	ds_read_b128 v[242:245], v176 offset:4672
	s_waitcnt lgkmcnt(5)
	v_mfma_f32_16x16x32_bf16 v[124:127], v[212:215], v[178:181], v[124:127]
	v_lshl_add_u64 v[152:153], s[6:7], 0, v[164:165]
	s_nop 0
	global_load_dwordx4 v[152:155], v[152:153], off offset:256
	s_waitcnt lgkmcnt(4)
	v_mfma_f32_16x16x32_bf16 v[120:123], v[212:215], v[200:203], v[120:123]
	s_waitcnt lgkmcnt(3)
	v_mfma_f32_16x16x32_bf16 v[116:119], v[212:215], v[204:207], v[116:119]
	s_waitcnt lgkmcnt(1)
	v_mfma_f32_16x16x32_bf16 v[112:115], v[212:215], v[208:211], v[112:115]
	s_waitcnt vmcnt(7)
	ds_write_b128 v253, v[156:159] offset:36864
	ds_read_b128 v[246:249], v176 offset:6976
	v_mfma_f32_16x16x32_bf16 v[108:111], v[216:219], v[178:181], v[108:111]
	v_mfma_f32_16x16x32_bf16 v[104:107], v[216:219], v[200:203], v[104:107]
	v_lshl_add_u64 v[156:157], s[6:7], 0, v[166:167]
	s_nop 0
	global_load_dwordx4 v[156:159], v[156:157], off offset:256
	v_mfma_f32_16x16x32_bf16 v[100:103], v[216:219], v[204:207], v[100:103]
	v_mfma_f32_16x16x32_bf16 v[96:99], v[216:219], v[208:211], v[96:99]
	ds_read_b128 v[212:215], v176 offset:9280
	s_waitcnt lgkmcnt(3)
	v_mfma_f32_16x16x32_bf16 v[92:95], v[242:245], v[178:181], v[92:95]
	v_mfma_f32_16x16x32_bf16 v[88:91], v[242:245], v[200:203], v[88:91]
	v_mfma_f32_16x16x32_bf16 v[84:87], v[242:245], v[204:207], v[84:87]
	v_mfma_f32_16x16x32_bf16 v[80:83], v[242:245], v[208:211], v[80:83]
	ds_read_b128 v[216:219], v176 offset:11584
	s_waitcnt lgkmcnt(2)
	v_mfma_f32_16x16x32_bf16 v[76:79], v[246:249], v[178:181], v[76:79]
	v_mfma_f32_16x16x32_bf16 v[72:75], v[246:249], v[200:203], v[72:75]
	v_mfma_f32_16x16x32_bf16 v[68:71], v[246:249], v[204:207], v[68:71]
	v_mfma_f32_16x16x32_bf16 v[64:67], v[246:249], v[208:211], v[64:67]
	ds_read_b128 v[242:245], v176 offset:13888
	s_waitcnt lgkmcnt(2)
	v_mfma_f32_16x16x32_bf16 v[60:63], v[212:215], v[178:181], v[60:63]
	v_mfma_f32_16x16x32_bf16 v[56:59], v[212:215], v[200:203], v[56:59]
	v_mfma_f32_16x16x32_bf16 v[52:55], v[212:215], v[204:207], v[52:55]
	v_mfma_f32_16x16x32_bf16 v[48:51], v[212:215], v[208:211], v[48:51]
	ds_read_b128 v[246:249], v176 offset:16192
	s_waitcnt lgkmcnt(2)
	v_mfma_f32_16x16x32_bf16 v[44:47], v[216:219], v[178:181], v[44:47]
	v_mfma_f32_16x16x32_bf16 v[40:43], v[216:219], v[200:203], v[40:43]
	v_mfma_f32_16x16x32_bf16 v[36:39], v[216:219], v[204:207], v[36:39]
	v_mfma_f32_16x16x32_bf16 v[32:35], v[216:219], v[208:211], v[32:35]
	s_add_i32 s4, s4, 1
	s_and_b32 s98, s4, 1
	s_mul_i32 s98, s98, 0x12000
	v_add3_u32 v176, s98, v174, v175
	v_add3_u32 v182, s98, v169, v175
	s_cmp_lg_u32 s4, 16
	s_waitcnt lgkmcnt(0)
	s_barrier
	s_cbranch_scc0 .Lgm1_exit
	ds_read_b128 v[212:215], v176
	ds_read_b128 v[216:219], v176 offset:2304
	v_mfma_f32_16x16x32_bf16 v[28:31], v[242:245], v[178:181], v[28:31]
	v_mfma_f32_16x16x32_bf16 v[8:11], v[246:249], v[178:181], v[8:11]
	ds_read_b128 v[178:181], v182 offset:36864
	v_mfma_f32_16x16x32_bf16 v[24:27], v[242:245], v[200:203], v[24:27]
	v_mfma_f32_16x16x32_bf16 v[4:7], v[246:249], v[200:203], v[4:7]
	ds_read_b128 v[200:203], v182 offset:39168
	v_mfma_f32_16x16x32_bf16 v[20:23], v[242:245], v[204:207], v[20:23]
	v_mfma_f32_16x16x32_bf16 v[0:3], v[246:249], v[204:207], v[0:3]
	ds_read_b128 v[204:207], v182 offset:41472
	v_mfma_f32_16x16x32_bf16 v[16:19], v[242:245], v[208:211], v[16:19]
	v_mfma_f32_16x16x32_bf16 v[12:15], v[246:249], v[208:211], v[12:15]
	ds_read_b128 v[208:211], v182 offset:43776
	s_branch .Lgm1_main

; DI f32x4 mfma16(bf16x8 a, bf16x8 b, f32x4 c) { return __builtin_amdgcn_mfma_f32_16x16x32_bf16(a, b, c, 0, 0, 0); }
; template <int MI, int NJ, bool SWAP, class AP, class BP>
; DI void gemm_main(f32x4 (&acc)[MI][NJ], const AP& ap, int a_kstep, const BP& bp, int b_kstep, int nk, bf16_t* smem) {
;     ...
;   auto gload = [&](int kt) {
;     const bf16_t* ab = ap.base + (size_t)kt * a_kstep; const bf16_t* bb = bp.base + (size_t)kt * b_kstep;
; #pragma unroll
;     for (int i = 0; i < CA; ++i) ra[i] = *(const u32x4*)(ab + pa[i]);
; #pragma unroll
;     for (int i = 0; i < CB; ++i) rb[i] = *(const u32x4*)(bb + pb[i]);
;   };
;   auto sstore = [&](int buf) {
;     bf16_t* As = smem + buf * L::STAGE; bf16_t* Bs = As + L::A_ELEMS;
; #pragma unroll
;     for (int i = 0; i < CA; ++i) { const int c = tid + NTHR * i; *(u32x4*)(As + (c >> 3) * LDT + (c & 7) * 8) = oka[i] ? ra[i] : (u32x4){0u, 0u, 0u, 0u}; }
; #pragma unroll
;     for (int i = 0; i < CB; ++i) { const int c = tid + NTHR * i; *(u32x4*)(Bs + (c >> 3) * LDT + (c & 7) * 8) = rb[i]; }
;   };
;   gload(0); sstore(0); gload(nk > 1 ? 1 : 0); __syncthreads();
; #pragma unroll 1
;   for (int kt = 0; kt < nk; ++kt) {
;     const int buf = kt & 1;
;     sstore(buf ^ 1);
;     gload(kt + 2 < nk ? kt + 2 : nk - 1);
;     __builtin_amdgcn_sched_barrier(0);
;     const bf16_t* As = smem + buf * L::STAGE + (wm * 16 * MI + l15) * LDT + quad * 8;
;     const bf16_t* Bs = smem + buf * L::STAGE + L::A_ELEMS + (wn * 16 * NJ + l15) * LDT + quad * 8;
; #pragma unroll
;     for (int ks = 0; ks < 2; ++ks) {
;       if (MI * NJ >= 32 && ks == 1) asm volatile("" ::: "memory");
;       bf16x8 b[NJ];
; #pragma unroll
;       for (int j = 0; j < NJ; ++j) b[j] = *(const bf16x8*)(Bs + j * 16 * LDT + ks * 32);
; #pragma unroll
;       for (int i = 0; i < MI; ++i) {
;         const bf16x8 a = *(const bf16x8*)(As + i * 16 * LDT + ks * 32);
; #pragma unroll
;         for (int j = 0; j < NJ; ++j) acc[i][j] = SWAP ? mfma16(b[j], a, acc[i][j]) : mfma16(a, b[j], acc[i][j]);
;       }
;     }
;     __syncthreads();
.Lgm2_main:
	ds_read_b128 v[242:245], v182 offset:4608
	s_waitcnt lgkmcnt(4)
	v_mfma_f32_16x16x32_bf16 v[156:159], v[178:181], v[198:201], v[156:159]
	s_and_b32 s33, s16, 1
	s_min_u32 s52, s16, 3
	s_xor_b32 s53, s33, 1
	s_mul_i32 s53, s53, 0x12000
	v_add3_u32 v250, s53, v173, v171
	s_waitcnt vmcnt(7)
	ds_write_b128 v250, v[112:115]
	s_waitcnt lgkmcnt(4)
	v_mfma_f32_16x16x32_bf16 v[152:155], v[186:189], v[198:201], v[152:155]
	s_waitcnt lgkmcnt(3)
	v_mfma_f32_16x16x32_bf16 v[148:151], v[190:193], v[198:201], v[148:151]
	s_lshl_b32 s54, s52, 7
	s_add_u32 s52, s0, s54
	v_add3_u32 v251, s53, v174, v171
	v_add3_u32 v252, s53, v175, v171
	v_add3_u32 v253, s53, v176, v171
	s_addc_u32 s53, s1, 0
	v_lshl_add_u64 v[112:113], s[52:53], 0, v[162:163]
	s_nop 0
	global_load_dwordx4 v[112:115], v[112:113], off offset:256
	s_waitcnt lgkmcnt(2)
	v_mfma_f32_16x16x32_bf16 v[144:147], v[194:197], v[198:201], v[144:147]
	ds_read_b128 v[246:249], v182 offset:6912
	v_mfma_f32_16x16x32_bf16 v[108:111], v[178:181], v[202:205], v[108:111]
	v_mfma_f32_16x16x32_bf16 v[104:107], v[186:189], v[202:205], v[104:107]
	s_waitcnt vmcnt(6)
	ds_write_b128 v251, v[116:119]
	v_mfma_f32_16x16x32_bf16 v[100:103], v[190:193], v[202:205], v[100:103]
	v_mfma_f32_16x16x32_bf16 v[96:99], v[194:197], v[202:205], v[96:99]
	v_lshl_add_u64 v[116:117], s[52:53], 0, v[164:165]
	s_nop 0
	global_load_dwordx4 v[116:119], v[116:117], off offset:256
	ds_read_b128 v[198:201], v182 offset:9216
	s_waitcnt lgkmcnt(4)
	v_mfma_f32_16x16x32_bf16 v[92:95], v[178:181], v[242:245], v[92:95]
	v_mfma_f32_16x16x32_bf16 v[88:91], v[186:189], v[242:245], v[88:91]
	v_mfma_f32_16x16x32_bf16 v[84:87], v[190:193], v[242:245], v[84:87]
	s_waitcnt vmcnt(6)
	ds_write_b128 v252, v[120:123]
	v_mfma_f32_16x16x32_bf16 v[80:83], v[194:197], v[242:245], v[80:83]
	ds_read_b128 v[202:205], v182 offset:11520
	s_waitcnt lgkmcnt(4)
	v_mfma_f32_16x16x32_bf16 v[76:79], v[178:181], v[246:249], v[76:79]
	v_lshl_add_u64 v[120:121], s[52:53], 0, v[166:167]
	s_nop 0
	global_load_dwordx4 v[120:123], v[120:121], off offset:256
	v_mfma_f32_16x16x32_bf16 v[72:75], v[186:189], v[246:249], v[72:75]
	v_mfma_f32_16x16x32_bf16 v[68:71], v[190:193], v[246:249], v[68:71]
	v_mfma_f32_16x16x32_bf16 v[64:67], v[194:197], v[246:249], v[64:67]
	s_waitcnt vmcnt(6)
	ds_write_b128 v253, v[124:127]
	ds_read_b128 v[242:245], v182 offset:13824
	s_waitcnt lgkmcnt(4)
	v_mfma_f32_16x16x32_bf16 v[60:63], v[178:181], v[198:201], v[60:63]
	v_mfma_f32_16x16x32_bf16 v[56:59], v[186:189], v[198:201], v[56:59]
	v_lshl_add_u64 v[124:125], s[52:53], 0, v[168:169]
	s_nop 0
	global_load_dwordx4 v[124:127], v[124:125], off offset:256
	v_mfma_f32_16x16x32_bf16 v[52:55], v[190:193], v[198:201], v[52:55]
	v_mfma_f32_16x16x32_bf16 v[48:51], v[194:197], v[198:201], v[48:51]
	ds_read_b128 v[246:249], v182 offset:16128
	s_waitcnt lgkmcnt(3)
	v_mfma_f32_16x16x32_bf16 v[44:47], v[178:181], v[202:205], v[44:47]
	ds_write_b128 v250, v[128:131] offset:36864
	v_mfma_f32_16x16x32_bf16 v[40:43], v[186:189], v[202:205], v[40:43]
	v_mfma_f32_16x16x32_bf16 v[36:39], v[190:193], v[202:205], v[36:39]
	s_add_u32 s52, s2, s54
	s_addc_u32 s53, s3, 0
	v_lshl_add_u64 v[128:129], s[52:53], 0, v[162:163]
	s_nop 0
	global_load_dwordx4 v[128:131], v[128:129], off offset:256
	v_mfma_f32_16x16x32_bf16 v[32:35], v[194:197], v[202:205], v[32:35]
	ds_read_b128 v[198:201], v182 offset:64
	s_waitcnt lgkmcnt(3)
	v_mfma_f32_16x16x32_bf16 v[28:31], v[178:181], v[242:245], v[28:31]
	v_mfma_f32_16x16x32_bf16 v[24:27], v[186:189], v[242:245], v[24:27]
	s_waitcnt vmcnt(7)
	ds_write_b128 v251, v[132:135] offset:36864
	v_mfma_f32_16x16x32_bf16 v[20:23], v[190:193], v[242:245], v[20:23]
	v_mfma_f32_16x16x32_bf16 v[16:19], v[194:197], v[242:245], v[16:19]
	v_lshl_add_u64 v[132:133], s[52:53], 0, v[164:165]
	s_nop 0
	global_load_dwordx4 v[132:135], v[132:133], off offset:256
	ds_read_b128 v[202:205], v182 offset:2368
	s_waitcnt lgkmcnt(4)
; DI f32x4 mfma16(bf16x8 a, bf16x8 b, f32x4 c) { return __builtin_amdgcn_mfma_f32_16x16x32_bf16(a, b, c, 0, 0, 0); }
; template <int MI, int NJ, bool SWAP, class AP, class BP>
; DI void gemm_main(f32x4 (&acc)[MI][NJ], const AP& ap, int a_kstep, const BP& bp, int b_kstep, int nk, bf16_t* smem) {
;     ...
;   auto gload = [&](int kt) {
;     const bf16_t* ab = ap.base + (size_t)kt * a_kstep; const bf16_t* bb = bp.base + (size_t)kt * b_kstep;
; #pragma unroll
;     for (int i = 0; i < CA; ++i) ra[i] = *(const u32x4*)(ab + pa[i]);
; #pragma unroll
;     for (int i = 0; i < CB; ++i) rb[i] = *(const u32x4*)(bb + pb[i]);
;   };
;   auto sstore = [&](int buf) {
;     bf16_t* As = smem + buf * L::STAGE; bf16_t* Bs = As + L::A_ELEMS;
; #pragma unroll
;     for (int i = 0; i < CA; ++i) { const int c = tid + NTHR * i; *(u32x4*)(As + (c >> 3) * LDT + (c & 7) * 8) = oka[i] ? ra[i] : (u32x4){0u, 0u, 0u, 0u}; }
; #pragma unroll
;     for (int i = 0; i < CB; ++i) { const int c = tid + NTHR * i; *(u32x4*)(Bs + (c >> 3) * LDT + (c & 7) * 8) = rb[i]; }
;   };
;   gload(0); sstore(0); gload(nk > 1 ? 1 : 0); __syncthreads();
; #pragma unroll 1
;   for (int kt = 0; kt < nk; ++kt) {
;     const int buf = kt & 1;
;     sstore(buf ^ 1);
;     gload(kt + 2 < nk ? kt + 2 : nk - 1);
;     __builtin_amdgcn_sched_barrier(0);
;     const bf16_t* As = smem + buf * L::STAGE + (wm * 16 * MI + l15) * LDT + quad * 8;
;     const bf16_t* Bs = smem + buf * L::STAGE + L::A_ELEMS + (wn * 16 * NJ + l15) * LDT + quad * 8;
; #pragma unroll
;     for (int ks = 0; ks < 2; ++ks) {
;       if (MI * NJ >= 32 && ks == 1) asm volatile("" ::: "memory");
;       bf16x8 b[NJ];
; #pragma unroll
;       for (int j = 0; j < NJ; ++j) b[j] = *(const bf16x8*)(Bs + j * 16 * LDT + ks * 32);
; #pragma unroll
;       for (int i = 0; i < MI; ++i) {
;         const bf16x8 a = *(const bf16x8*)(As + i * 16 * LDT + ks * 32);
; #pragma unroll
;         for (int j = 0; j < NJ; ++j) acc[i][j] = SWAP ? mfma16(b[j], a, acc[i][j]) : mfma16(a, b[j], acc[i][j]);
;       }
;     }
;     __syncthreads();
	v_mfma_f32_16x16x32_bf16 v[8:11], v[178:181], v[246:249], v[8:11]
	ds_read_b128 v[178:181], v183 offset:36928
	v_mfma_f32_16x16x32_bf16 v[4:7], v[186:189], v[246:249], v[4:7]
	ds_read_b128 v[186:189], v183 offset:39232
	v_mfma_f32_16x16x32_bf16 v[0:3], v[190:193], v[246:249], v[0:3]
	ds_read_b128 v[190:193], v183 offset:41536
	s_waitcnt vmcnt(7)
	ds_write_b128 v252, v[136:139] offset:36864
	v_mfma_f32_16x16x32_bf16 v[12:15], v[194:197], v[246:249], v[12:15]
	ds_read_b128 v[194:197], v183 offset:43840
	ds_read_b128 v[242:245], v182 offset:4672
	s_waitcnt lgkmcnt(5)
	v_mfma_f32_16x16x32_bf16 v[156:159], v[178:181], v[198:201], v[156:159]
	v_lshl_add_u64 v[136:137], s[52:53], 0, v[166:167]
	s_nop 0
	global_load_dwordx4 v[136:139], v[136:137], off offset:256
	s_waitcnt lgkmcnt(4)
	v_mfma_f32_16x16x32_bf16 v[152:155], v[186:189], v[198:201], v[152:155]
	s_waitcnt lgkmcnt(3)
	v_mfma_f32_16x16x32_bf16 v[148:151], v[190:193], v[198:201], v[148:151]
	s_waitcnt lgkmcnt(1)
	v_mfma_f32_16x16x32_bf16 v[144:147], v[194:197], v[198:201], v[144:147]
	s_waitcnt vmcnt(7)
	ds_write_b128 v253, v[140:143] offset:36864
	ds_read_b128 v[246:249], v182 offset:6976
	v_mfma_f32_16x16x32_bf16 v[108:111], v[178:181], v[202:205], v[108:111]
	v_mfma_f32_16x16x32_bf16 v[104:107], v[186:189], v[202:205], v[104:107]
	v_lshl_add_u64 v[140:141], s[52:53], 0, v[168:169]
	s_nop 0
	global_load_dwordx4 v[140:143], v[140:141], off offset:256
	v_mfma_f32_16x16x32_bf16 v[100:103], v[190:193], v[202:205], v[100:103]
	v_mfma_f32_16x16x32_bf16 v[96:99], v[194:197], v[202:205], v[96:99]
	ds_read_b128 v[198:201], v182 offset:9280
	s_waitcnt lgkmcnt(3)
	v_mfma_f32_16x16x32_bf16 v[92:95], v[178:181], v[242:245], v[92:95]
	v_mfma_f32_16x16x32_bf16 v[88:91], v[186:189], v[242:245], v[88:91]
	v_mfma_f32_16x16x32_bf16 v[84:87], v[190:193], v[242:245], v[84:87]
	v_mfma_f32_16x16x32_bf16 v[80:83], v[194:197], v[242:245], v[80:83]
	ds_read_b128 v[202:205], v182 offset:11584
	s_waitcnt lgkmcnt(2)
	v_mfma_f32_16x16x32_bf16 v[76:79], v[178:181], v[246:249], v[76:79]
	v_mfma_f32_16x16x32_bf16 v[72:75], v[186:189], v[246:249], v[72:75]
	v_mfma_f32_16x16x32_bf16 v[68:71], v[190:193], v[246:249], v[68:71]
	v_mfma_f32_16x16x32_bf16 v[64:67], v[194:197], v[246:249], v[64:67]
	ds_read_b128 v[242:245], v182 offset:13888
	s_waitcnt lgkmcnt(2)
	v_mfma_f32_16x16x32_bf16 v[60:63], v[178:181], v[198:201], v[60:63]
	v_mfma_f32_16x16x32_bf16 v[56:59], v[186:189], v[198:201], v[56:59]
	v_mfma_f32_16x16x32_bf16 v[52:55], v[190:193], v[198:201], v[52:55]
	v_mfma_f32_16x16x32_bf16 v[48:51], v[194:197], v[198:201], v[48:51]
	ds_read_b128 v[246:249], v182 offset:16192
	s_waitcnt lgkmcnt(2)
	v_mfma_f32_16x16x32_bf16 v[44:47], v[178:181], v[202:205], v[44:47]
	v_mfma_f32_16x16x32_bf16 v[40:43], v[186:189], v[202:205], v[40:43]
	v_mfma_f32_16x16x32_bf16 v[36:39], v[190:193], v[202:205], v[36:39]
	v_mfma_f32_16x16x32_bf16 v[32:35], v[194:197], v[202:205], v[32:35]
	s_add_i32 s16, s16, 1
	s_and_b32 s98, s16, 1
	s_mul_i32 s98, s98, 0x12000
	v_add3_u32 v183, s98, v160, v177
	v_add3_u32 v182, s98, v172, v177
	s_cmp_lg_u32 s16, 6
	s_waitcnt lgkmcnt(0)
	s_barrier
	s_cbranch_scc0 .Lgm2_exit
	ds_read_b128 v[198:201], v182
	ds_read_b128 v[202:205], v182 offset:2304
	v_mfma_f32_16x16x32_bf16 v[28:31], v[178:181], v[242:245], v[28:31]
	v_mfma_f32_16x16x32_bf16 v[8:11], v[178:181], v[246:249], v[8:11]
	ds_read_b128 v[178:181], v183 offset:36864
	v_mfma_f32_16x16x32_bf16 v[24:27], v[186:189], v[242:245], v[24:27]
	v_mfma_f32_16x16x32_bf16 v[4:7], v[186:189], v[246:249], v[4:7]
	ds_read_b128 v[186:189], v183 offset:39168
	v_mfma_f32_16x16x32_bf16 v[20:23], v[190:193], v[242:245], v[20:23]
	v_mfma_f32_16x16x32_bf16 v[0:3], v[190:193], v[246:249], v[0:3]
	ds_read_b128 v[190:193], v183 offset:41472
	v_mfma_f32_16x16x32_bf16 v[16:19], v[194:197], v[242:245], v[16:19]
	v_mfma_f32_16x16x32_bf16 v[12:15], v[194:197], v[246:249], v[12:15]
	ds_read_b128 v[194:197], v183 offset:43776
	s_branch .Lgm2_main

; DI f32x4 mfma16(bf16x8 a, bf16x8 b, f32x4 c) { return __builtin_amdgcn_mfma_f32_16x16x32_bf16(a, b, c, 0, 0, 0); }
; template <int MI, int NJ, bool SWAP, class AP, class BP>
; DI void gemm_main(f32x4 (&acc)[MI][NJ], const AP& ap, int a_kstep, const BP& bp, int b_kstep, int nk, bf16_t* smem) {
;     ...
;   auto gload = [&](int kt) {
;     const bf16_t* ab = ap.base + (size_t)kt * a_kstep; const bf16_t* bb = bp.base + (size_t)kt * b_kstep;
; #pragma unroll
;     for (int i = 0; i < CA; ++i) ra[i] = *(const u32x4*)(ab + pa[i]);
; #pragma unroll
;     for (int i = 0; i < CB; ++i) rb[i] = *(const u32x4*)(bb + pb[i]);
;   };
;   auto sstore = [&](int buf) {
;     bf16_t* As = smem + buf * L::STAGE; bf16_t* Bs = As + L::A_ELEMS;
; #pragma unroll
;     for (int i = 0; i < CA; ++i) { const int c = tid + NTHR * i; *(u32x4*)(As + (c >> 3) * LDT + (c & 7) * 8) = oka[i] ? ra[i] : (u32x4){0u, 0u, 0u, 0u}; }
; #pragma unroll
;     for (int i = 0; i < CB; ++i) { const int c = tid + NTHR * i; *(u32x4*)(Bs + (c >> 3) * LDT + (c & 7) * 8) = rb[i]; }
;   };
;   gload(0); sstore(0); gload(nk > 1 ? 1 : 0); __syncthreads();
; #pragma unroll 1
;   for (int kt = 0; kt < nk; ++kt) {
;     const int buf = kt & 1;
;     sstore(buf ^ 1);
;     gload(kt + 2 < nk ? kt + 2 : nk - 1);
;     __builtin_amdgcn_sched_barrier(0);
;     const bf16_t* As = smem + buf * L::STAGE + (wm * 16 * MI + l15) * LDT + quad * 8;
;     const bf16_t* Bs = smem + buf * L::STAGE + L::A_ELEMS + (wn * 16 * NJ + l15) * LDT + quad * 8;
; #pragma unroll
;     for (int ks = 0; ks < 2; ++ks) {
;       if (MI * NJ >= 32 && ks == 1) asm volatile("" ::: "memory");
;       bf16x8 b[NJ];
; #pragma unroll
;       for (int j = 0; j < NJ; ++j) b[j] = *(const bf16x8*)(Bs + j * 16 * LDT + ks * 32);
; #pragma unroll
;       for (int i = 0; i < MI; ++i) {
;         const bf16x8 a = *(const bf16x8*)(As + i * 16 * LDT + ks * 32);
; #pragma unroll
;         for (int j = 0; j < NJ; ++j) acc[i][j] = SWAP ? mfma16(b[j], a, acc[i][j]) : mfma16(a, b[j], acc[i][j]);
;       }
;     }
;     __syncthreads();
.Lgm3_main:
	ds_read_b128 v[242:245], v182 offset:4608
	s_waitcnt lgkmcnt(4)
	v_mfma_f32_16x16x32_bf16 v[156:159], v[178:181], v[198:201], v[156:159]
	v_lshlrev_b32_e32 v250, 1, v160
	s_and_b32 s54, s33, 1
	s_xor_b32 s52, s54, 1
	s_mul_i32 s52, s52, 0x12000
	v_add3_u32 v250, s52, v250, v172
	s_waitcnt vmcnt(7)
	ds_write_b128 v250, v[112:115]
	s_waitcnt lgkmcnt(4)
	v_mfma_f32_16x16x32_bf16 v[152:155], v[186:189], v[198:201], v[152:155]
	s_waitcnt lgkmcnt(3)
	v_mfma_f32_16x16x32_bf16 v[148:151], v[190:193], v[198:201], v[148:151]
	s_cmp_eq_u32 s33, 0
	s_cselect_b32 s55, s48, 0x180
	v_lshlrev_b32_e32 v251, 1, v173
	v_add3_u32 v251, s52, v251, v172
	v_lshlrev_b32_e32 v252, 1, v174
	v_add3_u32 v252, s52, v252, v172
	v_lshlrev_b32_e32 v253, 1, v175
	v_add3_u32 v253, s52, v253, v172
	s_add_u32 s52, s0, s55
	s_addc_u32 s53, s1, 0
	v_lshl_add_u64 v[112:113], s[52:53], 0, v[162:163]
	s_nop 0
	global_load_dwordx4 v[112:115], v[112:113], off
	s_waitcnt lgkmcnt(2)
	v_mfma_f32_16x16x32_bf16 v[144:147], v[194:197], v[198:201], v[144:147]
	ds_read_b128 v[246:249], v182 offset:6912
	v_mfma_f32_16x16x32_bf16 v[108:111], v[178:181], v[202:205], v[108:111]
	v_mfma_f32_16x16x32_bf16 v[104:107], v[186:189], v[202:205], v[104:107]
	s_waitcnt vmcnt(7)
	ds_write_b128 v251, v[116:119]
	v_mfma_f32_16x16x32_bf16 v[100:103], v[190:193], v[202:205], v[100:103]
	v_mfma_f32_16x16x32_bf16 v[96:99], v[194:197], v[202:205], v[96:99]
	v_lshl_add_u64 v[116:117], s[52:53], 0, v[164:165]
	s_nop 0
	global_load_dwordx4 v[116:119], v[116:117], off
	ds_read_b128 v[198:201], v182 offset:9216
	s_waitcnt lgkmcnt(4)
	v_mfma_f32_16x16x32_bf16 v[92:95], v[178:181], v[242:245], v[92:95]
	v_mfma_f32_16x16x32_bf16 v[88:91], v[186:189], v[242:245], v[88:91]
	v_mfma_f32_16x16x32_bf16 v[84:87], v[190:193], v[242:245], v[84:87]
	s_waitcnt vmcnt(7)
	ds_write_b128 v252, v[120:123]
	v_mfma_f32_16x16x32_bf16 v[80:83], v[194:197], v[242:245], v[80:83]
	ds_read_b128 v[202:205], v182 offset:11520
	s_waitcnt lgkmcnt(4)
	v_mfma_f32_16x16x32_bf16 v[76:79], v[178:181], v[246:249], v[76:79]
	v_lshl_add_u64 v[120:121], s[52:53], 0, v[166:167]
	s_nop 0
	global_load_dwordx4 v[120:123], v[120:121], off
	v_mfma_f32_16x16x32_bf16 v[72:75], v[186:189], v[246:249], v[72:75]
	v_mfma_f32_16x16x32_bf16 v[68:71], v[190:193], v[246:249], v[68:71]
	v_mfma_f32_16x16x32_bf16 v[64:67], v[194:197], v[246:249], v[64:67]
	s_waitcnt vmcnt(7)
	ds_write_b128 v253, v[124:127]
	ds_read_b128 v[242:245], v182 offset:13824
	s_waitcnt lgkmcnt(4)
	v_mfma_f32_16x16x32_bf16 v[60:63], v[178:181], v[198:201], v[60:63]
	v_mfma_f32_16x16x32_bf16 v[56:59], v[186:189], v[198:201], v[56:59]
	v_lshl_add_u64 v[124:125], s[52:53], 0, v[168:169]
	s_nop 0
	global_load_dwordx4 v[124:127], v[124:125], off
	v_mfma_f32_16x16x32_bf16 v[52:55], v[190:193], v[198:201], v[52:55]
	v_mfma_f32_16x16x32_bf16 v[48:51], v[194:197], v[198:201], v[48:51]
	ds_read_b128 v[246:249], v182 offset:16128
	s_waitcnt lgkmcnt(3)
	v_mfma_f32_16x16x32_bf16 v[44:47], v[178:181], v[202:205], v[44:47]
	s_waitcnt vmcnt(7)
	ds_write_b128 v250, v[128:131] offset:36864
	v_mfma_f32_16x16x32_bf16 v[40:43], v[186:189], v[202:205], v[40:43]
	v_mfma_f32_16x16x32_bf16 v[36:39], v[190:193], v[202:205], v[36:39]
	s_add_u32 s52, s2, s55
	s_addc_u32 s53, s3, 0
	v_lshl_add_u64 v[128:129], s[52:53], 0, v[162:163]
	s_nop 0
	global_load_dwordx4 v[128:131], v[128:129], off
	v_mfma_f32_16x16x32_bf16 v[32:35], v[194:197], v[202:205], v[32:35]
	ds_read_b128 v[198:201], v182 offset:64
	s_waitcnt lgkmcnt(3)
	v_mfma_f32_16x16x32_bf16 v[28:31], v[178:181], v[242:245], v[28:31]
	v_mfma_f32_16x16x32_bf16 v[24:27], v[186:189], v[242:245], v[24:27]
	s_waitcnt vmcnt(7)
	ds_write_b128 v251, v[132:135] offset:36864
	v_mfma_f32_16x16x32_bf16 v[20:23], v[190:193], v[242:245], v[20:23]
	v_mfma_f32_16x16x32_bf16 v[16:19], v[194:197], v[242:245], v[16:19]
	v_lshl_add_u64 v[132:133], s[52:53], 0, v[164:165]
	s_nop 0
	global_load_dwordx4 v[132:135], v[132:133], off
	ds_read_b128 v[202:205], v182 offset:2368
	s_waitcnt lgkmcnt(4)
; DI f32x4 mfma16(bf16x8 a, bf16x8 b, f32x4 c) { return __builtin_amdgcn_mfma_f32_16x16x32_bf16(a, b, c, 0, 0, 0); }
; template <int MI, int NJ, bool SWAP, class AP, class BP>
; DI void gemm_main(f32x4 (&acc)[MI][NJ], const AP& ap, int a_kstep, const BP& bp, int b_kstep, int nk, bf16_t* smem) {
;     ...
;   auto gload = [&](int kt) {
;     const bf16_t* ab = ap.base + (size_t)kt * a_kstep; const bf16_t* bb = bp.base + (size_t)kt * b_kstep;
; #pragma unroll
;     for (int i = 0; i < CA; ++i) ra[i] = *(const u32x4*)(ab + pa[i]);
; #pragma unroll
;     for (int i = 0; i < CB; ++i) rb[i] = *(const u32x4*)(bb + pb[i]);
;   };
;   auto sstore = [&](int buf) {
;     bf16_t* As = smem + buf * L::STAGE; bf16_t* Bs = As + L::A_ELEMS;
; #pragma unroll
;     for (int i = 0; i < CA; ++i) { const int c = tid + NTHR * i; *(u32x4*)(As + (c >> 3) * LDT + (c & 7) * 8) = oka[i] ? ra[i] : (u32x4){0u, 0u, 0u, 0u}; }
; #pragma unroll
;     for (int i = 0; i < CB; ++i) { const int c = tid + NTHR * i; *(u32x4*)(Bs + (c >> 3) * LDT + (c & 7) * 8) = rb[i]; }
;   };
;   gload(0); sstore(0); gload(nk > 1 ? 1 : 0); __syncthreads();
; #pragma unroll 1
;   for (int kt = 0; kt < nk; ++kt) {
;     const int buf = kt & 1;
;     sstore(buf ^ 1);
;     gload(kt + 2 < nk ? kt + 2 : nk - 1);
;     __builtin_amdgcn_sched_barrier(0);
;     const bf16_t* As = smem + buf * L::STAGE + (wm * 16 * MI + l15) * LDT + quad * 8;
;     const bf16_t* Bs = smem + buf * L::STAGE + L::A_ELEMS + (wn * 16 * NJ + l15) * LDT + quad * 8;
; #pragma unroll
;     for (int ks = 0; ks < 2; ++ks) {
;       if (MI * NJ >= 32 && ks == 1) asm volatile("" ::: "memory");
;       bf16x8 b[NJ];
; #pragma unroll
;       for (int j = 0; j < NJ; ++j) b[j] = *(const bf16x8*)(Bs + j * 16 * LDT + ks * 32);
; #pragma unroll
;       for (int i = 0; i < MI; ++i) {
;         const bf16x8 a = *(const bf16x8*)(As + i * 16 * LDT + ks * 32);
; #pragma unroll
;         for (int j = 0; j < NJ; ++j) acc[i][j] = SWAP ? mfma16(b[j], a, acc[i][j]) : mfma16(a, b[j], acc[i][j]);
;       }
;     }
;     __syncthreads();
	v_mfma_f32_16x16x32_bf16 v[8:11], v[178:181], v[246:249], v[8:11]
	ds_read_b128 v[178:181], v183 offset:36928
	v_mfma_f32_16x16x32_bf16 v[4:7], v[186:189], v[246:249], v[4:7]
	ds_read_b128 v[186:189], v183 offset:39232
	v_mfma_f32_16x16x32_bf16 v[0:3], v[190:193], v[246:249], v[0:3]
	ds_read_b128 v[190:193], v183 offset:41536
	s_waitcnt vmcnt(7)
	ds_write_b128 v252, v[136:139] offset:36864
	v_mfma_f32_16x16x32_bf16 v[12:15], v[194:197], v[246:249], v[12:15]
	ds_read_b128 v[194:197], v183 offset:43840
	ds_read_b128 v[242:245], v182 offset:4672
	s_waitcnt lgkmcnt(5)
	v_mfma_f32_16x16x32_bf16 v[156:159], v[178:181], v[198:201], v[156:159]
	v_lshl_add_u64 v[136:137], s[52:53], 0, v[166:167]
	s_nop 0
	global_load_dwordx4 v[136:139], v[136:137], off
	s_waitcnt lgkmcnt(4)
	v_mfma_f32_16x16x32_bf16 v[152:155], v[186:189], v[198:201], v[152:155]
	s_waitcnt lgkmcnt(3)
	v_mfma_f32_16x16x32_bf16 v[148:151], v[190:193], v[198:201], v[148:151]
	s_waitcnt lgkmcnt(1)
	v_mfma_f32_16x16x32_bf16 v[144:147], v[194:197], v[198:201], v[144:147]
	s_waitcnt vmcnt(7)
	ds_write_b128 v253, v[140:143] offset:36864
	ds_read_b128 v[246:249], v182 offset:6976
	v_mfma_f32_16x16x32_bf16 v[108:111], v[178:181], v[202:205], v[108:111]
	v_mfma_f32_16x16x32_bf16 v[104:107], v[186:189], v[202:205], v[104:107]
	v_lshl_add_u64 v[140:141], s[52:53], 0, v[168:169]
	s_nop 0
	global_load_dwordx4 v[140:143], v[140:141], off
	v_mfma_f32_16x16x32_bf16 v[100:103], v[190:193], v[202:205], v[100:103]
	v_mfma_f32_16x16x32_bf16 v[96:99], v[194:197], v[202:205], v[96:99]
	ds_read_b128 v[198:201], v182 offset:9280
	s_waitcnt lgkmcnt(3)
	v_mfma_f32_16x16x32_bf16 v[92:95], v[178:181], v[242:245], v[92:95]
	v_mfma_f32_16x16x32_bf16 v[88:91], v[186:189], v[242:245], v[88:91]
	v_mfma_f32_16x16x32_bf16 v[84:87], v[190:193], v[242:245], v[84:87]
	v_mfma_f32_16x16x32_bf16 v[80:83], v[194:197], v[242:245], v[80:83]
	ds_read_b128 v[202:205], v182 offset:11584
	s_waitcnt lgkmcnt(2)
	v_mfma_f32_16x16x32_bf16 v[76:79], v[178:181], v[246:249], v[76:79]
	v_mfma_f32_16x16x32_bf16 v[72:75], v[186:189], v[246:249], v[72:75]
	v_mfma_f32_16x16x32_bf16 v[68:71], v[190:193], v[246:249], v[68:71]
	v_mfma_f32_16x16x32_bf16 v[64:67], v[194:197], v[246:249], v[64:67]
	ds_read_b128 v[242:245], v182 offset:13888
	s_waitcnt lgkmcnt(2)
	v_mfma_f32_16x16x32_bf16 v[60:63], v[178:181], v[198:201], v[60:63]
	v_mfma_f32_16x16x32_bf16 v[56:59], v[186:189], v[198:201], v[56:59]
	v_mfma_f32_16x16x32_bf16 v[52:55], v[190:193], v[198:201], v[52:55]
	v_mfma_f32_16x16x32_bf16 v[48:51], v[194:197], v[198:201], v[48:51]
	ds_read_b128 v[246:249], v182 offset:16192
	s_waitcnt lgkmcnt(2)
	v_mfma_f32_16x16x32_bf16 v[44:47], v[178:181], v[202:205], v[44:47]
	v_mfma_f32_16x16x32_bf16 v[40:43], v[186:189], v[202:205], v[40:43]
	v_mfma_f32_16x16x32_bf16 v[36:39], v[190:193], v[202:205], v[36:39]
	v_mfma_f32_16x16x32_bf16 v[32:35], v[194:197], v[202:205], v[32:35]
	s_add_i32 s33, s33, 1
	s_and_b32 s98, s33, 1
	s_mul_i32 s98, s98, 0x12000
	v_add3_u32 v183, s98, v171, v177
	v_add3_u32 v182, s98, v176, v177
	s_cmp_lg_u32 s33, 4
	s_waitcnt lgkmcnt(0)
	s_barrier
	s_cbranch_scc0 .Lgm3_exit
	ds_read_b128 v[198:201], v182
	ds_read_b128 v[202:205], v182 offset:2304
	v_mfma_f32_16x16x32_bf16 v[28:31], v[178:181], v[242:245], v[28:31]
	v_mfma_f32_16x16x32_bf16 v[8:11], v[178:181], v[246:249], v[8:11]
	ds_read_b128 v[178:181], v183 offset:36864
	v_mfma_f32_16x16x32_bf16 v[24:27], v[186:189], v[242:245], v[24:27]
	v_mfma_f32_16x16x32_bf16 v[4:7], v[186:189], v[246:249], v[4:7]
	ds_read_b128 v[186:189], v183 offset:39168
	v_mfma_f32_16x16x32_bf16 v[20:23], v[190:193], v[242:245], v[20:23]
	v_mfma_f32_16x16x32_bf16 v[0:3], v[190:193], v[246:249], v[0:3]
	ds_read_b128 v[190:193], v183 offset:41472
	v_mfma_f32_16x16x32_bf16 v[16:19], v[194:197], v[242:245], v[16:19]
	v_mfma_f32_16x16x32_bf16 v[12:15], v[194:197], v[246:249], v[12:15]
	ds_read_b128 v[194:197], v183 offset:43776
	s_branch .Lgm3_main

; DI f32x4 mfma16(bf16x8 a, bf16x8 b, f32x4 c) { return __builtin_amdgcn_mfma_f32_16x16x32_bf16(a, b, c, 0, 0, 0); }
; template <int MI, int NJ, bool SWAP, class AP, class BP>
; DI void gemm_main(f32x4 (&acc)[MI][NJ], const AP& ap, int a_kstep, const BP& bp, int b_kstep, int nk, bf16_t* smem) {
;     ...
;   auto gload = [&](int kt) {
;     const bf16_t* ab = ap.base + (size_t)kt * a_kstep; const bf16_t* bb = bp.base + (size_t)kt * b_kstep;
; #pragma unroll
;     for (int i = 0; i < CA; ++i) ra[i] = *(const u32x4*)(ab + pa[i]);
; #pragma unroll
;     for (int i = 0; i < CB; ++i) rb[i] = *(const u32x4*)(bb + pb[i]);
;   };
;   auto sstore = [&](int buf) {
;     bf16_t* As = smem + buf * L::STAGE; bf16_t* Bs = As + L::A_ELEMS;
; #pragma unroll
;     for (int i = 0; i < CA; ++i) { const int c = tid + NTHR * i; *(u32x4*)(As + (c >> 3) * LDT + (c & 7) * 8) = oka[i] ? ra[i] : (u32x4){0u, 0u, 0u, 0u}; }
; #pragma unroll
;     for (int i = 0; i < CB; ++i) { const int c = tid + NTHR * i; *(u32x4*)(Bs + (c >> 3) * LDT + (c & 7) * 8) = rb[i]; }
;   };
;   gload(0); sstore(0); gload(nk > 1 ? 1 : 0); __syncthreads();
; #pragma unroll 1
;   for (int kt = 0; kt < nk; ++kt) {
;     const int buf = kt & 1;
;     sstore(buf ^ 1);
;     gload(kt + 2 < nk ? kt + 2 : nk - 1);
;     __builtin_amdgcn_sched_barrier(0);
;     const bf16_t* As = smem + buf * L::STAGE + (wm * 16 * MI + l15) * LDT + quad * 8;
;     const bf16_t* Bs = smem + buf * L::STAGE + L::A_ELEMS + (wn * 16 * NJ + l15) * LDT + quad * 8;
; #pragma unroll
;     for (int ks = 0; ks < 2; ++ks) {
;       if (MI * NJ >= 32 && ks == 1) asm volatile("" ::: "memory");
;       bf16x8 b[NJ];
; #pragma unroll
;       for (int j = 0; j < NJ; ++j) b[j] = *(const bf16x8*)(Bs + j * 16 * LDT + ks * 32);
; #pragma unroll
;       for (int i = 0; i < MI; ++i) {
;         const bf16x8 a = *(const bf16x8*)(As + i * 16 * LDT + ks * 32);
; #pragma unroll
;         for (int j = 0; j < NJ; ++j) acc[i][j] = SWAP ? mfma16(b[j], a, acc[i][j]) : mfma16(a, b[j], acc[i][j]);
;       }
;     }
;     __syncthreads();
.Lgm4_main:
	ds_read_b128 v[242:245], v182 offset:4608
	s_waitcnt lgkmcnt(4)
	v_mfma_f32_16x16x32_bf16 v[140:143], v[198:201], v[178:181], v[140:143]
	v_lshlrev_b32_e32 v250, 1, v160
	s_and_b32 s16, s5, 1
	s_xor_b32 s33, s16, 1
	s_mul_i32 s33, s33, 0x12000
	v_add3_u32 v250, s33, v250, v172
	s_waitcnt vmcnt(7)
	ds_write_b128 v250, v[124:127]
	s_waitcnt lgkmcnt(4)
	v_mfma_f32_16x16x32_bf16 v[120:123], v[198:201], v[186:189], v[120:123]
	s_waitcnt lgkmcnt(3)
	v_mfma_f32_16x16x32_bf16 v[116:119], v[198:201], v[190:193], v[116:119]
	s_cmp_eq_u32 s5, 0
	v_lshlrev_b32_e32 v251, 1, v173
	v_add3_u32 v251, s33, v251, v172
	v_lshlrev_b32_e32 v252, 1, v174
	v_add3_u32 v252, s33, v252, v172
	v_lshlrev_b32_e32 v253, 1, v175
	v_add3_u32 v253, s33, v253, v172
	s_cselect_b32 s33, s48, 0x180
	s_add_u32 s52, s0, s33
	s_addc_u32 s53, s1, 0
	v_lshl_add_u64 v[124:125], s[52:53], 0, v[162:163]
	s_nop 0
	global_load_dwordx4 v[124:127], v[124:125], off
	s_waitcnt lgkmcnt(2)
	v_mfma_f32_16x16x32_bf16 v[112:115], v[198:201], v[194:197], v[112:115]
	ds_read_b128 v[246:249], v182 offset:6912
	v_mfma_f32_16x16x32_bf16 v[108:111], v[202:205], v[178:181], v[108:111]
	v_mfma_f32_16x16x32_bf16 v[104:107], v[202:205], v[186:189], v[104:107]
	s_waitcnt vmcnt(7)
	ds_write_b128 v251, v[128:131]
	v_mfma_f32_16x16x32_bf16 v[100:103], v[202:205], v[190:193], v[100:103]
	v_mfma_f32_16x16x32_bf16 v[96:99], v[202:205], v[194:197], v[96:99]
	v_lshl_add_u64 v[128:129], s[52:53], 0, v[164:165]
	s_nop 0
	global_load_dwordx4 v[128:131], v[128:129], off
	ds_read_b128 v[198:201], v182 offset:9216
	s_waitcnt lgkmcnt(4)
	v_mfma_f32_16x16x32_bf16 v[92:95], v[242:245], v[178:181], v[92:95]
	v_mfma_f32_16x16x32_bf16 v[88:91], v[242:245], v[186:189], v[88:91]
	v_mfma_f32_16x16x32_bf16 v[84:87], v[242:245], v[190:193], v[84:87]
	s_waitcnt vmcnt(7)
	ds_write_b128 v252, v[132:135]
	v_mfma_f32_16x16x32_bf16 v[80:83], v[242:245], v[194:197], v[80:83]
	ds_read_b128 v[202:205], v182 offset:11520
	s_waitcnt lgkmcnt(4)
	v_mfma_f32_16x16x32_bf16 v[76:79], v[246:249], v[178:181], v[76:79]
	v_lshl_add_u64 v[132:133], s[52:53], 0, v[166:167]
	s_nop 0
	global_load_dwordx4 v[132:135], v[132:133], off
	v_mfma_f32_16x16x32_bf16 v[72:75], v[246:249], v[186:189], v[72:75]
	v_mfma_f32_16x16x32_bf16 v[68:71], v[246:249], v[190:193], v[68:71]
	v_mfma_f32_16x16x32_bf16 v[64:67], v[246:249], v[194:197], v[64:67]
	s_waitcnt vmcnt(7)
	ds_write_b128 v253, v[136:139]
	ds_read_b128 v[242:245], v182 offset:13824
	s_waitcnt lgkmcnt(4)
	v_mfma_f32_16x16x32_bf16 v[60:63], v[198:201], v[178:181], v[60:63]
	v_mfma_f32_16x16x32_bf16 v[56:59], v[198:201], v[186:189], v[56:59]
	v_lshl_add_u64 v[136:137], s[52:53], 0, v[168:169]
	s_nop 0
	global_load_dwordx4 v[136:139], v[136:137], off
	v_mfma_f32_16x16x32_bf16 v[52:55], v[198:201], v[190:193], v[52:55]
	v_mfma_f32_16x16x32_bf16 v[48:51], v[198:201], v[194:197], v[48:51]
	ds_read_b128 v[246:249], v182 offset:16128
	s_waitcnt lgkmcnt(3)
	v_mfma_f32_16x16x32_bf16 v[44:47], v[202:205], v[178:181], v[44:47]
	s_waitcnt vmcnt(7)
	ds_write_b128 v250, v[144:147] offset:36864
	v_mfma_f32_16x16x32_bf16 v[40:43], v[202:205], v[186:189], v[40:43]
	v_mfma_f32_16x16x32_bf16 v[36:39], v[202:205], v[190:193], v[36:39]
	s_add_u32 s52, s2, s33
	s_addc_u32 s53, s3, 0
	v_lshl_add_u64 v[144:145], s[52:53], 0, v[162:163]
	s_nop 0
	global_load_dwordx4 v[144:147], v[144:145], off
	v_mfma_f32_16x16x32_bf16 v[32:35], v[202:205], v[194:197], v[32:35]
	ds_read_b128 v[198:201], v182 offset:64
	s_waitcnt lgkmcnt(3)
	v_mfma_f32_16x16x32_bf16 v[28:31], v[242:245], v[178:181], v[28:31]
	v_mfma_f32_16x16x32_bf16 v[24:27], v[242:245], v[186:189], v[24:27]
	s_waitcnt vmcnt(7)
	ds_write_b128 v251, v[148:151] offset:36864
	v_mfma_f32_16x16x32_bf16 v[20:23], v[242:245], v[190:193], v[20:23]
	v_mfma_f32_16x16x32_bf16 v[16:19], v[242:245], v[194:197], v[16:19]
	v_lshl_add_u64 v[148:149], s[52:53], 0, v[164:165]
	s_nop 0
	global_load_dwordx4 v[148:151], v[148:149], off
	ds_read_b128 v[202:205], v182 offset:2368
	s_waitcnt lgkmcnt(4)
; DI f32x4 mfma16(bf16x8 a, bf16x8 b, f32x4 c) { return __builtin_amdgcn_mfma_f32_16x16x32_bf16(a, b, c, 0, 0, 0); }
; template <int MI, int NJ, bool SWAP, class AP, class BP>
; DI void gemm_main(f32x4 (&acc)[MI][NJ], const AP& ap, int a_kstep, const BP& bp, int b_kstep, int nk, bf16_t* smem) {
;     ...
;   auto gload = [&](int kt) {
;     const bf16_t* ab = ap.base + (size_t)kt * a_kstep; const bf16_t* bb = bp.base + (size_t)kt * b_kstep;
; #pragma unroll
;     for (int i = 0; i < CA; ++i) ra[i] = *(const u32x4*)(ab + pa[i]);
; #pragma unroll
;     for (int i = 0; i < CB; ++i) rb[i] = *(const u32x4*)(bb + pb[i]);
;   };
;   auto sstore = [&](int buf) {
;     bf16_t* As = smem + buf * L::STAGE; bf16_t* Bs = As + L::A_ELEMS;
; #pragma unroll
;     for (int i = 0; i < CA; ++i) { const int c = tid + NTHR * i; *(u32x4*)(As + (c >> 3) * LDT + (c & 7) * 8) = oka[i] ? ra[i] : (u32x4){0u, 0u, 0u, 0u}; }
; #pragma unroll
;     for (int i = 0; i < CB; ++i) { const int c = tid + NTHR * i; *(u32x4*)(Bs + (c >> 3) * LDT + (c & 7) * 8) = rb[i]; }
;   };
;   gload(0); sstore(0); gload(nk > 1 ? 1 : 0); __syncthreads();
; #pragma unroll 1
;   for (int kt = 0; kt < nk; ++kt) {
;     const int buf = kt & 1;
;     sstore(buf ^ 1);
;     gload(kt + 2 < nk ? kt + 2 : nk - 1);
;     __builtin_amdgcn_sched_barrier(0);
;     const bf16_t* As = smem + buf * L::STAGE + (wm * 16 * MI + l15) * LDT + quad * 8;
;     const bf16_t* Bs = smem + buf * L::STAGE + L::A_ELEMS + (wn * 16 * NJ + l15) * LDT + quad * 8;
; #pragma unroll
;     for (int ks = 0; ks < 2; ++ks) {
;       if (MI * NJ >= 32 && ks == 1) asm volatile("" ::: "memory");
;       bf16x8 b[NJ];
; #pragma unroll
;       for (int j = 0; j < NJ; ++j) b[j] = *(const bf16x8*)(Bs + j * 16 * LDT + ks * 32);
; #pragma unroll
;       for (int i = 0; i < MI; ++i) {
;         const bf16x8 a = *(const bf16x8*)(As + i * 16 * LDT + ks * 32);
; #pragma unroll
;         for (int j = 0; j < NJ; ++j) acc[i][j] = SWAP ? mfma16(b[j], a, acc[i][j]) : mfma16(a, b[j], acc[i][j]);
;       }
;     }
;     __syncthreads();
	v_mfma_f32_16x16x32_bf16 v[8:11], v[246:249], v[178:181], v[8:11]
	ds_read_b128 v[178:181], v183 offset:36928
	v_mfma_f32_16x16x32_bf16 v[4:7], v[246:249], v[186:189], v[4:7]
	ds_read_b128 v[186:189], v183 offset:39232
	v_mfma_f32_16x16x32_bf16 v[0:3], v[246:249], v[190:193], v[0:3]
	ds_read_b128 v[190:193], v183 offset:41536
	s_waitcnt vmcnt(7)
	ds_write_b128 v252, v[152:155] offset:36864
	v_mfma_f32_16x16x32_bf16 v[12:15], v[246:249], v[194:197], v[12:15]
	ds_read_b128 v[194:197], v183 offset:43840
	ds_read_b128 v[242:245], v182 offset:4672
	s_waitcnt lgkmcnt(5)
	v_mfma_f32_16x16x32_bf16 v[140:143], v[198:201], v[178:181], v[140:143]
	v_lshl_add_u64 v[152:153], s[52:53], 0, v[166:167]
	s_nop 0
	global_load_dwordx4 v[152:155], v[152:153], off
	s_waitcnt lgkmcnt(4)
	v_mfma_f32_16x16x32_bf16 v[120:123], v[198:201], v[186:189], v[120:123]
	s_waitcnt lgkmcnt(3)
	v_mfma_f32_16x16x32_bf16 v[116:119], v[198:201], v[190:193], v[116:119]
	s_waitcnt lgkmcnt(1)
	v_mfma_f32_16x16x32_bf16 v[112:115], v[198:201], v[194:197], v[112:115]
	s_waitcnt vmcnt(7)
	ds_write_b128 v253, v[156:159] offset:36864
	ds_read_b128 v[246:249], v182 offset:6976
	v_mfma_f32_16x16x32_bf16 v[108:111], v[202:205], v[178:181], v[108:111]
	v_mfma_f32_16x16x32_bf16 v[104:107], v[202:205], v[186:189], v[104:107]
	v_lshl_add_u64 v[156:157], s[52:53], 0, v[168:169]
	s_nop 0
	global_load_dwordx4 v[156:159], v[156:157], off
	v_mfma_f32_16x16x32_bf16 v[100:103], v[202:205], v[190:193], v[100:103]
	v_mfma_f32_16x16x32_bf16 v[96:99], v[202:205], v[194:197], v[96:99]
	ds_read_b128 v[198:201], v182 offset:9280
	s_waitcnt lgkmcnt(3)
	v_mfma_f32_16x16x32_bf16 v[92:95], v[242:245], v[178:181], v[92:95]
	v_mfma_f32_16x16x32_bf16 v[88:91], v[242:245], v[186:189], v[88:91]
	v_mfma_f32_16x16x32_bf16 v[84:87], v[242:245], v[190:193], v[84:87]
	v_mfma_f32_16x16x32_bf16 v[80:83], v[242:245], v[194:197], v[80:83]
	ds_read_b128 v[202:205], v182 offset:11584
	s_waitcnt lgkmcnt(2)
	v_mfma_f32_16x16x32_bf16 v[76:79], v[246:249], v[178:181], v[76:79]
	v_mfma_f32_16x16x32_bf16 v[72:75], v[246:249], v[186:189], v[72:75]
	v_mfma_f32_16x16x32_bf16 v[68:71], v[246:249], v[190:193], v[68:71]
	v_mfma_f32_16x16x32_bf16 v[64:67], v[246:249], v[194:197], v[64:67]
	ds_read_b128 v[242:245], v182 offset:13888
	s_waitcnt lgkmcnt(2)
	v_mfma_f32_16x16x32_bf16 v[60:63], v[198:201], v[178:181], v[60:63]
	v_mfma_f32_16x16x32_bf16 v[56:59], v[198:201], v[186:189], v[56:59]
	v_mfma_f32_16x16x32_bf16 v[52:55], v[198:201], v[190:193], v[52:55]
	v_mfma_f32_16x16x32_bf16 v[48:51], v[198:201], v[194:197], v[48:51]
	ds_read_b128 v[246:249], v182 offset:16192
	s_waitcnt lgkmcnt(2)
	v_mfma_f32_16x16x32_bf16 v[44:47], v[202:205], v[178:181], v[44:47]
	v_mfma_f32_16x16x32_bf16 v[40:43], v[202:205], v[186:189], v[40:43]
	v_mfma_f32_16x16x32_bf16 v[36:39], v[202:205], v[190:193], v[36:39]
	v_mfma_f32_16x16x32_bf16 v[32:35], v[202:205], v[194:197], v[32:35]
	s_add_i32 s5, s5, 1
	s_and_b32 s98, s5, 1
	s_mul_i32 s98, s98, 0x12000
	v_add3_u32 v182, s98, v176, v177
	v_add3_u32 v183, s98, v171, v177
	s_cmp_lg_u32 s5, 4
	s_waitcnt lgkmcnt(0)
	s_barrier
	s_cbranch_scc0 .Lgm4_exit
	ds_read_b128 v[198:201], v182
	ds_read_b128 v[202:205], v182 offset:2304
	v_mfma_f32_16x16x32_bf16 v[28:31], v[242:245], v[178:181], v[28:31]
	v_mfma_f32_16x16x32_bf16 v[8:11], v[246:249], v[178:181], v[8:11]
	ds_read_b128 v[178:181], v183 offset:36864
	v_mfma_f32_16x16x32_bf16 v[24:27], v[242:245], v[186:189], v[24:27]
	v_mfma_f32_16x16x32_bf16 v[4:7], v[246:249], v[186:189], v[4:7]
	ds_read_b128 v[186:189], v183 offset:39168
	v_mfma_f32_16x16x32_bf16 v[20:23], v[242:245], v[190:193], v[20:23]
	v_mfma_f32_16x16x32_bf16 v[0:3], v[246:249], v[190:193], v[0:3]
	ds_read_b128 v[190:193], v183 offset:41472
	v_mfma_f32_16x16x32_bf16 v[16:19], v[242:245], v[194:197], v[16:19]
	v_mfma_f32_16x16x32_bf16 v[12:15], v[246:249], v[194:197], v[12:15]
	ds_read_b128 v[194:197], v183 offset:43776
	s_branch .Lgm4_main

; DI f32x4 mfma16(bf16x8 a, bf16x8 b, f32x4 c) { return __builtin_amdgcn_mfma_f32_16x16x32_bf16(a, b, c, 0, 0, 0); }
; template <int MI, int NJ, bool SWAP, class AP, class BP>
; DI void gemm_main(f32x4 (&acc)[MI][NJ], const AP& ap, int a_kstep, const BP& bp, int b_kstep, int nk, bf16_t* smem) {
;     ...
;   auto gload = [&](int kt) {
;     const bf16_t* ab = ap.base + (size_t)kt * a_kstep; const bf16_t* bb = bp.base + (size_t)kt * b_kstep;
; #pragma unroll
;     for (int i = 0; i < CA; ++i) ra[i] = *(const u32x4*)(ab + pa[i]);
; #pragma unroll
;     for (int i = 0; i < CB; ++i) rb[i] = *(const u32x4*)(bb + pb[i]);
;   };
;   auto sstore = [&](int buf) {
;     bf16_t* As = smem + buf * L::STAGE; bf16_t* Bs = As + L::A_ELEMS;
; #pragma unroll
;     for (int i = 0; i < CA; ++i) { const int c = tid + NTHR * i; *(u32x4*)(As + (c >> 3) * LDT + (c & 7) * 8) = oka[i] ? ra[i] : (u32x4){0u, 0u, 0u, 0u}; }
; #pragma unroll
;     for (int i = 0; i < CB; ++i) { const int c = tid + NTHR * i; *(u32x4*)(Bs + (c >> 3) * LDT + (c & 7) * 8) = rb[i]; }
;   };
;   gload(0); sstore(0); gload(nk > 1 ? 1 : 0); __syncthreads();
; #pragma unroll 1
;   for (int kt = 0; kt < nk; ++kt) {
;     const int buf = kt & 1;
;     sstore(buf ^ 1);
;     gload(kt + 2 < nk ? kt + 2 : nk - 1);
;     __builtin_amdgcn_sched_barrier(0);
;     const bf16_t* As = smem + buf * L::STAGE + (wm * 16 * MI + l15) * LDT + quad * 8;
;     const bf16_t* Bs = smem + buf * L::STAGE + L::A_ELEMS + (wn * 16 * NJ + l15) * LDT + quad * 8;
; #pragma unroll
;     for (int ks = 0; ks < 2; ++ks) {
;       if (MI * NJ >= 32 && ks == 1) asm volatile("" ::: "memory");
;       bf16x8 b[NJ];
; #pragma unroll
;       for (int j = 0; j < NJ; ++j) b[j] = *(const bf16x8*)(Bs + j * 16 * LDT + ks * 32);
; #pragma unroll
;       for (int i = 0; i < MI; ++i) {
;         const bf16x8 a = *(const bf16x8*)(As + i * 16 * LDT + ks * 32);
; #pragma unroll
;         for (int j = 0; j < NJ; ++j) acc[i][j] = SWAP ? mfma16(b[j], a, acc[i][j]) : mfma16(a, b[j], acc[i][j]);
;       }
;     }
;     __syncthreads();
.Lgm5_main:
	ds_read_b128 v[242:245], v177 offset:4608
	s_waitcnt lgkmcnt(4)
	v_mfma_f32_16x16x32_bf16 v[156:159], v[178:181], v[194:197], v[156:159]
	s_and_b32 s15, s1, 1
	s_min_u32 s16, s1, 13
	s_xor_b32 s17, s15, 1
	s_mul_i32 s17, s17, 0x12000
	v_add3_u32 v250, s17, v172, v170
	s_waitcnt vmcnt(7)
	ds_write_b128 v250, v[112:115]
	s_waitcnt lgkmcnt(4)
	v_mfma_f32_16x16x32_bf16 v[152:155], v[182:185], v[194:197], v[152:155]
	s_waitcnt lgkmcnt(3)
	v_mfma_f32_16x16x32_bf16 v[148:151], v[186:189], v[194:197], v[148:151]
	s_lshl_b32 s26, s16, 7
	s_add_u32 s16, s2, s26
	v_add3_u32 v251, s17, v174, v170
	v_add3_u32 v252, s17, v175, v170
	v_add3_u32 v253, s17, v176, v170
	s_addc_u32 s17, s3, 0
	v_lshl_add_u64 v[112:113], s[16:17], 0, v[162:163]
	s_nop 0
	global_load_dwordx4 v[112:115], v[112:113], off offset:256
	s_waitcnt lgkmcnt(2)
	v_mfma_f32_16x16x32_bf16 v[128:131], v[190:193], v[194:197], v[128:131]
	ds_read_b128 v[246:249], v177 offset:6912
	v_mfma_f32_16x16x32_bf16 v[108:111], v[178:181], v[198:201], v[108:111]
	v_mfma_f32_16x16x32_bf16 v[104:107], v[182:185], v[198:201], v[104:107]
	s_waitcnt vmcnt(7)
	ds_write_b128 v251, v[116:119]
	v_mfma_f32_16x16x32_bf16 v[100:103], v[186:189], v[198:201], v[100:103]
	v_mfma_f32_16x16x32_bf16 v[96:99], v[190:193], v[198:201], v[96:99]
	v_lshl_add_u64 v[116:117], s[16:17], 0, v[164:165]
	s_nop 0
	global_load_dwordx4 v[116:119], v[116:117], off offset:256
	ds_read_b128 v[194:197], v177 offset:9216
	s_waitcnt lgkmcnt(4)
	v_mfma_f32_16x16x32_bf16 v[92:95], v[178:181], v[242:245], v[92:95]
	v_mfma_f32_16x16x32_bf16 v[88:91], v[182:185], v[242:245], v[88:91]
	v_mfma_f32_16x16x32_bf16 v[84:87], v[186:189], v[242:245], v[84:87]
	s_waitcnt vmcnt(7)
	ds_write_b128 v252, v[120:123]
	v_mfma_f32_16x16x32_bf16 v[80:83], v[190:193], v[242:245], v[80:83]
	ds_read_b128 v[198:201], v177 offset:11520
	s_waitcnt lgkmcnt(4)
	v_mfma_f32_16x16x32_bf16 v[76:79], v[178:181], v[246:249], v[76:79]
	v_lshl_add_u64 v[120:121], s[16:17], 0, v[166:167]
	s_nop 0
	global_load_dwordx4 v[120:123], v[120:121], off offset:256
	v_mfma_f32_16x16x32_bf16 v[72:75], v[182:185], v[246:249], v[72:75]
	v_mfma_f32_16x16x32_bf16 v[68:71], v[186:189], v[246:249], v[68:71]
	v_mfma_f32_16x16x32_bf16 v[64:67], v[190:193], v[246:249], v[64:67]
	s_waitcnt vmcnt(7)
	ds_write_b128 v253, v[124:127]
	ds_read_b128 v[242:245], v177 offset:13824
	s_waitcnt lgkmcnt(4)
	v_mfma_f32_16x16x32_bf16 v[60:63], v[178:181], v[194:197], v[60:63]
	v_mfma_f32_16x16x32_bf16 v[56:59], v[182:185], v[194:197], v[56:59]
	v_lshl_add_u64 v[124:125], s[16:17], 0, v[168:169]
	s_nop 0
	global_load_dwordx4 v[124:127], v[124:125], off offset:256
	v_mfma_f32_16x16x32_bf16 v[52:55], v[186:189], v[194:197], v[52:55]
	v_mfma_f32_16x16x32_bf16 v[48:51], v[190:193], v[194:197], v[48:51]
	ds_read_b128 v[246:249], v177 offset:16128
	s_waitcnt lgkmcnt(3)
	v_mfma_f32_16x16x32_bf16 v[44:47], v[178:181], v[198:201], v[44:47]
	s_waitcnt vmcnt(7)
	ds_write_b128 v250, v[132:135] offset:36864
	v_mfma_f32_16x16x32_bf16 v[40:43], v[182:185], v[198:201], v[40:43]
	v_mfma_f32_16x16x32_bf16 v[36:39], v[186:189], v[198:201], v[36:39]
	s_add_u32 s16, s12, s26
	s_addc_u32 s17, s13, 0
	v_lshl_add_u64 v[132:133], s[16:17], 0, v[162:163]
	s_nop 0
	global_load_dwordx4 v[132:135], v[132:133], off offset:256
	v_mfma_f32_16x16x32_bf16 v[32:35], v[190:193], v[198:201], v[32:35]
	ds_read_b128 v[194:197], v177 offset:64
	s_waitcnt lgkmcnt(3)
	v_mfma_f32_16x16x32_bf16 v[28:31], v[178:181], v[242:245], v[28:31]
	v_mfma_f32_16x16x32_bf16 v[24:27], v[182:185], v[242:245], v[24:27]
	s_waitcnt vmcnt(7)
	ds_write_b128 v251, v[136:139] offset:36864
	v_mfma_f32_16x16x32_bf16 v[20:23], v[186:189], v[242:245], v[20:23]
	v_mfma_f32_16x16x32_bf16 v[16:19], v[190:193], v[242:245], v[16:19]
	v_lshl_add_u64 v[136:137], s[16:17], 0, v[164:165]
	s_nop 0
	global_load_dwordx4 v[136:139], v[136:137], off offset:256
	ds_read_b128 v[198:201], v177 offset:2368
	s_waitcnt lgkmcnt(4)
; DI f32x4 mfma16(bf16x8 a, bf16x8 b, f32x4 c) { return __builtin_amdgcn_mfma_f32_16x16x32_bf16(a, b, c, 0, 0, 0); }
; template <int MI, int NJ, bool SWAP, class AP, class BP>
; DI void gemm_main(f32x4 (&acc)[MI][NJ], const AP& ap, int a_kstep, const BP& bp, int b_kstep, int nk, bf16_t* smem) {
;     ...
;   auto gload = [&](int kt) {
;     const bf16_t* ab = ap.base + (size_t)kt * a_kstep; const bf16_t* bb = bp.base + (size_t)kt * b_kstep;
; #pragma unroll
;     for (int i = 0; i < CA; ++i) ra[i] = *(const u32x4*)(ab + pa[i]);
; #pragma unroll
;     for (int i = 0; i < CB; ++i) rb[i] = *(const u32x4*)(bb + pb[i]);
;   };
;   auto sstore = [&](int buf) {
;     bf16_t* As = smem + buf * L::STAGE; bf16_t* Bs = As + L::A_ELEMS;
; #pragma unroll
;     for (int i = 0; i < CA; ++i) { const int c = tid + NTHR * i; *(u32x4*)(As + (c >> 3) * LDT + (c & 7) * 8) = oka[i] ? ra[i] : (u32x4){0u, 0u, 0u, 0u}; }
; #pragma unroll
;     for (int i = 0; i < CB; ++i) { const int c = tid + NTHR * i; *(u32x4*)(Bs + (c >> 3) * LDT + (c & 7) * 8) = rb[i]; }
;   };
;   gload(0); sstore(0); gload(nk > 1 ? 1 : 0); __syncthreads();
; #pragma unroll 1
;   for (int kt = 0; kt < nk; ++kt) {
;     const int buf = kt & 1;
;     sstore(buf ^ 1);
;     gload(kt + 2 < nk ? kt + 2 : nk - 1);
;     __builtin_amdgcn_sched_barrier(0);
;     const bf16_t* As = smem + buf * L::STAGE + (wm * 16 * MI + l15) * LDT + quad * 8;
;     const bf16_t* Bs = smem + buf * L::STAGE + L::A_ELEMS + (wn * 16 * NJ + l15) * LDT + quad * 8;
; #pragma unroll
;     for (int ks = 0; ks < 2; ++ks) {
;       if (MI * NJ >= 32 && ks == 1) asm volatile("" ::: "memory");
;       bf16x8 b[NJ];
; #pragma unroll
;       for (int j = 0; j < NJ; ++j) b[j] = *(const bf16x8*)(Bs + j * 16 * LDT + ks * 32);
; #pragma unroll
;       for (int i = 0; i < MI; ++i) {
;         const bf16x8 a = *(const bf16x8*)(As + i * 16 * LDT + ks * 32);
; #pragma unroll
;         for (int j = 0; j < NJ; ++j) acc[i][j] = SWAP ? mfma16(b[j], a, acc[i][j]) : mfma16(a, b[j], acc[i][j]);
;       }
;     }
;     __syncthreads();
	v_mfma_f32_16x16x32_bf16 v[8:11], v[178:181], v[246:249], v[8:11]
	ds_read_b128 v[178:181], v202 offset:36928
	v_mfma_f32_16x16x32_bf16 v[4:7], v[182:185], v[246:249], v[4:7]
	ds_read_b128 v[182:185], v202 offset:39232
	v_mfma_f32_16x16x32_bf16 v[0:3], v[186:189], v[246:249], v[0:3]
	ds_read_b128 v[186:189], v202 offset:41536
	s_waitcnt vmcnt(7)
	ds_write_b128 v252, v[140:143] offset:36864
	v_mfma_f32_16x16x32_bf16 v[12:15], v[190:193], v[246:249], v[12:15]
	ds_read_b128 v[190:193], v202 offset:43840
	ds_read_b128 v[242:245], v177 offset:4672
	s_waitcnt lgkmcnt(5)
	v_mfma_f32_16x16x32_bf16 v[156:159], v[178:181], v[194:197], v[156:159]
	v_lshl_add_u64 v[140:141], s[16:17], 0, v[166:167]
	s_nop 0
	global_load_dwordx4 v[140:143], v[140:141], off offset:256
	s_waitcnt lgkmcnt(4)
	v_mfma_f32_16x16x32_bf16 v[152:155], v[182:185], v[194:197], v[152:155]
	s_waitcnt lgkmcnt(3)
	v_mfma_f32_16x16x32_bf16 v[148:151], v[186:189], v[194:197], v[148:151]
	s_waitcnt lgkmcnt(1)
	v_mfma_f32_16x16x32_bf16 v[128:131], v[190:193], v[194:197], v[128:131]
	s_waitcnt vmcnt(7)
	ds_write_b128 v253, v[144:147] offset:36864
	ds_read_b128 v[246:249], v177 offset:6976
	v_mfma_f32_16x16x32_bf16 v[108:111], v[178:181], v[198:201], v[108:111]
	v_mfma_f32_16x16x32_bf16 v[104:107], v[182:185], v[198:201], v[104:107]
	v_lshl_add_u64 v[144:145], s[16:17], 0, v[168:169]
	s_nop 0
	global_load_dwordx4 v[144:147], v[144:145], off offset:256
	v_mfma_f32_16x16x32_bf16 v[100:103], v[186:189], v[198:201], v[100:103]
	v_mfma_f32_16x16x32_bf16 v[96:99], v[190:193], v[198:201], v[96:99]
	ds_read_b128 v[194:197], v177 offset:9280
	s_waitcnt lgkmcnt(3)
	v_mfma_f32_16x16x32_bf16 v[92:95], v[178:181], v[242:245], v[92:95]
	v_mfma_f32_16x16x32_bf16 v[88:91], v[182:185], v[242:245], v[88:91]
	v_mfma_f32_16x16x32_bf16 v[84:87], v[186:189], v[242:245], v[84:87]
	v_mfma_f32_16x16x32_bf16 v[80:83], v[190:193], v[242:245], v[80:83]
	ds_read_b128 v[198:201], v177 offset:11584
	s_waitcnt lgkmcnt(2)
	v_mfma_f32_16x16x32_bf16 v[76:79], v[178:181], v[246:249], v[76:79]
	v_mfma_f32_16x16x32_bf16 v[72:75], v[182:185], v[246:249], v[72:75]
	v_mfma_f32_16x16x32_bf16 v[68:71], v[186:189], v[246:249], v[68:71]
	v_mfma_f32_16x16x32_bf16 v[64:67], v[190:193], v[246:249], v[64:67]
	ds_read_b128 v[242:245], v177 offset:13888
	s_waitcnt lgkmcnt(2)
	v_mfma_f32_16x16x32_bf16 v[60:63], v[178:181], v[194:197], v[60:63]
	v_mfma_f32_16x16x32_bf16 v[56:59], v[182:185], v[194:197], v[56:59]
	v_mfma_f32_16x16x32_bf16 v[52:55], v[186:189], v[194:197], v[52:55]
	v_mfma_f32_16x16x32_bf16 v[48:51], v[190:193], v[194:197], v[48:51]
	ds_read_b128 v[246:249], v177 offset:16192
	s_waitcnt lgkmcnt(2)
	v_mfma_f32_16x16x32_bf16 v[44:47], v[178:181], v[198:201], v[44:47]
	v_mfma_f32_16x16x32_bf16 v[40:43], v[182:185], v[198:201], v[40:43]
	v_mfma_f32_16x16x32_bf16 v[36:39], v[186:189], v[198:201], v[36:39]
	v_mfma_f32_16x16x32_bf16 v[32:35], v[190:193], v[198:201], v[32:35]
	s_add_i32 s1, s1, 1
	s_and_b32 s98, s1, 1
	s_mul_i32 s98, s98, 0x12000
	v_add3_u32 v202, s98, v160, v173
	v_add3_u32 v177, s98, v171, v173
	s_cmp_lg_u32 s1, 16
	s_waitcnt lgkmcnt(0)
	s_barrier
	s_cbranch_scc0 .Lgm5_exit
	ds_read_b128 v[194:197], v177
	ds_read_b128 v[198:201], v177 offset:2304
	v_mfma_f32_16x16x32_bf16 v[28:31], v[178:181], v[242:245], v[28:31]
	v_mfma_f32_16x16x32_bf16 v[8:11], v[178:181], v[246:249], v[8:11]
	ds_read_b128 v[178:181], v202 offset:36864
	v_mfma_f32_16x16x32_bf16 v[24:27], v[182:185], v[242:245], v[24:27]
	v_mfma_f32_16x16x32_bf16 v[4:7], v[182:185], v[246:249], v[4:7]
	ds_read_b128 v[182:185], v202 offset:39168
	v_mfma_f32_16x16x32_bf16 v[20:23], v[186:189], v[242:245], v[20:23]
	v_mfma_f32_16x16x32_bf16 v[0:3], v[186:189], v[246:249], v[0:3]
	ds_read_b128 v[186:189], v202 offset:41472
	v_mfma_f32_16x16x32_bf16 v[16:19], v[190:193], v[242:245], v[16:19]
	v_mfma_f32_16x16x32_bf16 v[12:15], v[190:193], v[246:249], v[12:15]
	ds_read_b128 v[190:193], v202 offset:43776
	s_branch .Lgm5_main

; DI f32x4 mfma16(bf16x8 a, bf16x8 b, f32x4 c) { return __builtin_amdgcn_mfma_f32_16x16x32_bf16(a, b, c, 0, 0, 0); }
; template <int MI, int NJ, bool SWAP, class AP, class BP>
; DI void gemm_main(f32x4 (&acc)[MI][NJ], const AP& ap, int a_kstep, const BP& bp, int b_kstep, int nk, bf16_t* smem) {
;     ...
;   auto gload = [&](int kt) {
;     const bf16_t* ab = ap.base + (size_t)kt * a_kstep; const bf16_t* bb = bp.base + (size_t)kt * b_kstep;
; #pragma unroll
;     for (int i = 0; i < CA; ++i) ra[i] = *(const u32x4*)(ab + pa[i]);
; #pragma unroll
;     for (int i = 0; i < CB; ++i) rb[i] = *(const u32x4*)(bb + pb[i]);
;   };
;   auto sstore = [&](int buf) {
;     bf16_t* As = smem + buf * L::STAGE; bf16_t* Bs = As + L::A_ELEMS;
; #pragma unroll
;     for (int i = 0; i < CA; ++i) { const int c = tid + NTHR * i; *(u32x4*)(As + (c >> 3) * LDT + (c & 7) * 8) = oka[i] ? ra[i] : (u32x4){0u, 0u, 0u, 0u}; }
; #pragma unroll
;     for (int i = 0; i < CB; ++i) { const int c = tid + NTHR * i; *(u32x4*)(Bs + (c >> 3) * LDT + (c & 7) * 8) = rb[i]; }
;   };
;   gload(0); sstore(0); gload(nk > 1 ? 1 : 0); __syncthreads();
; #pragma unroll 1
;   for (int kt = 0; kt < nk; ++kt) {
;     const int buf = kt & 1;
;     sstore(buf ^ 1);
;     gload(kt + 2 < nk ? kt + 2 : nk - 1);
;     __builtin_amdgcn_sched_barrier(0);
;     const bf16_t* As = smem + buf * L::STAGE + (wm * 16 * MI + l15) * LDT + quad * 8;
;     const bf16_t* Bs = smem + buf * L::STAGE + L::A_ELEMS + (wn * 16 * NJ + l15) * LDT + quad * 8;
; #pragma unroll
;     for (int ks = 0; ks < 2; ++ks) {
;       if (MI * NJ >= 32 && ks == 1) asm volatile("" ::: "memory");
;       bf16x8 b[NJ];
; #pragma unroll
;       for (int j = 0; j < NJ; ++j) b[j] = *(const bf16x8*)(Bs + j * 16 * LDT + ks * 32);
; #pragma unroll
;       for (int i = 0; i < MI; ++i) {
;         const bf16x8 a = *(const bf16x8*)(As + i * 16 * LDT + ks * 32);
; #pragma unroll
;         for (int j = 0; j < NJ; ++j) acc[i][j] = SWAP ? mfma16(b[j], a, acc[i][j]) : mfma16(a, b[j], acc[i][j]);
;       }
;     }
;     __syncthreads();
.Lgm6_main:
	ds_read_b128 v[246:249], v181 offset:4608
	s_waitcnt lgkmcnt(4)
	v_mfma_f32_16x16x32_bf16 v[156:159], v[182:185], v[198:201], v[156:159]
	s_waitcnt vmcnt(7)
	v_cndmask_b32_e32 v139, 0, v139, vcc
	v_cndmask_b32_e32 v138, 0, v138, vcc
	v_cndmask_b32_e32 v137, 0, v137, vcc
	v_cndmask_b32_e32 v136, 0, v136, vcc
	s_and_b32 s31, s30, 1
	s_xor_b32 s33, s31, 1
	s_mul_i32 s33, s33, 0x12000
	v_add3_u32 v254, s33, v172, v169
	ds_write_b128 v254, v[136:139]
	s_waitcnt lgkmcnt(4)
	v_mfma_f32_16x16x32_bf16 v[152:155], v[186:189], v[198:201], v[152:155]
	s_waitcnt lgkmcnt(3)
	v_mfma_f32_16x16x32_bf16 v[148:151], v[190:193], v[198:201], v[148:151]
	v_add3_u32 v238, s33, v173, v169
	v_add3_u32 v239, s33, v174, v169
	v_add3_u32 v255, s33, v175, v169
	s_min_u32 s33, s30, 13
	s_lshl_b32 s33, s33, 7
	s_add_u32 s34, s12, s33
	s_addc_u32 s35, s13, 0
	s_nop 0
	global_load_dwordx4 v[136:139], v176, s[34:35] offset:256
	s_waitcnt lgkmcnt(2)
	v_mfma_f32_16x16x32_bf16 v[144:147], v[194:197], v[198:201], v[144:147]
	ds_read_b128 v[250:253], v181 offset:6912
	v_mfma_f32_16x16x32_bf16 v[108:111], v[182:185], v[242:245], v[108:111]
	v_mfma_f32_16x16x32_bf16 v[104:107], v[186:189], v[242:245], v[104:107]
	s_waitcnt vmcnt(7)
	v_cndmask_b32_e64 v127, 0, v127, s[0:1]
	v_cndmask_b32_e64 v126, 0, v126, s[0:1]
	v_cndmask_b32_e64 v125, 0, v125, s[0:1]
	v_cndmask_b32_e64 v124, 0, v124, s[0:1]
	ds_write_b128 v238, v[124:127]
	v_mfma_f32_16x16x32_bf16 v[100:103], v[190:193], v[242:245], v[100:103]
	v_mfma_f32_16x16x32_bf16 v[96:99], v[194:197], v[242:245], v[96:99]
	s_nop 0
	global_load_dwordx4 v[124:127], v177, s[34:35] offset:256
	ds_read_b128 v[198:201], v181 offset:9216
	s_waitcnt lgkmcnt(4)
	v_mfma_f32_16x16x32_bf16 v[92:95], v[182:185], v[246:249], v[92:95]
	v_mfma_f32_16x16x32_bf16 v[88:91], v[186:189], v[246:249], v[88:91]
	v_mfma_f32_16x16x32_bf16 v[84:87], v[190:193], v[246:249], v[84:87]
	s_waitcnt vmcnt(7)
	v_cndmask_b32_e64 v115, 0, v115, s[2:3]
	v_cndmask_b32_e64 v114, 0, v114, s[2:3]
	v_cndmask_b32_e64 v113, 0, v113, s[2:3]
	v_cndmask_b32_e64 v112, 0, v112, s[2:3]
	ds_write_b128 v239, v[112:115]
	v_mfma_f32_16x16x32_bf16 v[80:83], v[194:197], v[246:249], v[80:83]
	ds_read_b128 v[242:245], v181 offset:11520
	s_waitcnt lgkmcnt(4)
	v_mfma_f32_16x16x32_bf16 v[76:79], v[182:185], v[250:253], v[76:79]
	v_mfma_f32_16x16x32_bf16 v[72:75], v[186:189], v[250:253], v[72:75]
	v_mfma_f32_16x16x32_bf16 v[68:71], v[190:193], v[250:253], v[68:71]
	v_mfma_f32_16x16x32_bf16 v[64:67], v[194:197], v[250:253], v[64:67]
	s_waitcnt vmcnt(6)
	v_cndmask_b32_e64 v112, 0, v116, s[4:5]
	v_cndmask_b32_e64 v115, 0, v119, s[4:5]
	v_cndmask_b32_e64 v114, 0, v118, s[4:5]
	v_cndmask_b32_e64 v113, 0, v117, s[4:5]
	ds_write_b128 v255, v[112:115]
	ds_read_b128 v[246:249], v181 offset:13824
	s_waitcnt lgkmcnt(4)
	v_mfma_f32_16x16x32_bf16 v[60:63], v[182:185], v[198:201], v[60:63]
	v_mfma_f32_16x16x32_bf16 v[56:59], v[186:189], v[198:201], v[56:59]
	s_nop 0
	global_load_dwordx4 v[112:115], v178, s[34:35] offset:256
	s_nop 0
	global_load_dwordx4 v[116:119], v179, s[34:35] offset:256
	v_mfma_f32_16x16x32_bf16 v[52:55], v[190:193], v[198:201], v[52:55]
	v_mfma_f32_16x16x32_bf16 v[48:51], v[194:197], v[198:201], v[48:51]
	ds_read_b128 v[250:253], v181 offset:16128
	s_waitcnt lgkmcnt(3)
	v_mfma_f32_16x16x32_bf16 v[44:47], v[182:185], v[242:245], v[44:47]
	s_waitcnt vmcnt(7)
	ds_write_b128 v254, v[120:123] offset:36864
	v_mfma_f32_16x16x32_bf16 v[40:43], v[186:189], v[242:245], v[40:43]
	v_mfma_f32_16x16x32_bf16 v[36:39], v[190:193], v[242:245], v[36:39]
	s_add_u32 s34, s14, s33
	s_addc_u32 s35, s15, 0
	v_lshl_add_u64 v[120:121], v[160:161], 1, s[34:35]
	s_nop 0
	global_load_dwordx4 v[120:123], v[120:121], off offset:256
	v_mfma_f32_16x16x32_bf16 v[32:35], v[194:197], v[242:245], v[32:35]
	ds_read_b128 v[198:201], v181 offset:64
	s_waitcnt lgkmcnt(3)
	v_mfma_f32_16x16x32_bf16 v[28:31], v[182:185], v[246:249], v[28:31]
	v_mfma_f32_16x16x32_bf16 v[24:27], v[186:189], v[246:249], v[24:27]
	s_waitcnt vmcnt(7)
; DI f32x4 mfma16(bf16x8 a, bf16x8 b, f32x4 c) { return __builtin_amdgcn_mfma_f32_16x16x32_bf16(a, b, c, 0, 0, 0); }
; template <int MI, int NJ, bool SWAP, class AP, class BP>
; DI void gemm_main(f32x4 (&acc)[MI][NJ], const AP& ap, int a_kstep, const BP& bp, int b_kstep, int nk, bf16_t* smem) {
;     ...
;   auto gload = [&](int kt) {
;     const bf16_t* ab = ap.base + (size_t)kt * a_kstep; const bf16_t* bb = bp.base + (size_t)kt * b_kstep;
; #pragma unroll
;     for (int i = 0; i < CA; ++i) ra[i] = *(const u32x4*)(ab + pa[i]);
; #pragma unroll
;     for (int i = 0; i < CB; ++i) rb[i] = *(const u32x4*)(bb + pb[i]);
;   };
;   auto sstore = [&](int buf) {
;     bf16_t* As = smem + buf * L::STAGE; bf16_t* Bs = As + L::A_ELEMS;
; #pragma unroll
;     for (int i = 0; i < CA; ++i) { const int c = tid + NTHR * i; *(u32x4*)(As + (c >> 3) * LDT + (c & 7) * 8) = oka[i] ? ra[i] : (u32x4){0u, 0u, 0u, 0u}; }
; #pragma unroll
;     for (int i = 0; i < CB; ++i) { const int c = tid + NTHR * i; *(u32x4*)(Bs + (c >> 3) * LDT + (c & 7) * 8) = rb[i]; }
;   };
;   gload(0); sstore(0); gload(nk > 1 ? 1 : 0); __syncthreads();
; #pragma unroll 1
;   for (int kt = 0; kt < nk; ++kt) {
;     const int buf = kt & 1;
;     sstore(buf ^ 1);
;     gload(kt + 2 < nk ? kt + 2 : nk - 1);
;     __builtin_amdgcn_sched_barrier(0);
;     const bf16_t* As = smem + buf * L::STAGE + (wm * 16 * MI + l15) * LDT + quad * 8;
;     const bf16_t* Bs = smem + buf * L::STAGE + L::A_ELEMS + (wn * 16 * NJ + l15) * LDT + quad * 8;
; #pragma unroll
;     for (int ks = 0; ks < 2; ++ks) {
;       if (MI * NJ >= 32 && ks == 1) asm volatile("" ::: "memory");
;       bf16x8 b[NJ];
; #pragma unroll
;       for (int j = 0; j < NJ; ++j) b[j] = *(const bf16x8*)(Bs + j * 16 * LDT + ks * 32);
; #pragma unroll
;       for (int i = 0; i < MI; ++i) {
;         const bf16x8 a = *(const bf16x8*)(As + i * 16 * LDT + ks * 32);
; #pragma unroll
;         for (int j = 0; j < NJ; ++j) acc[i][j] = SWAP ? mfma16(b[j], a, acc[i][j]) : mfma16(a, b[j], acc[i][j]);
;       }
;     }
;     __syncthreads();
	ds_write_b128 v238, v[128:131] offset:36864
	v_mfma_f32_16x16x32_bf16 v[20:23], v[190:193], v[246:249], v[20:23]
	v_mfma_f32_16x16x32_bf16 v[16:19], v[194:197], v[246:249], v[16:19]
	v_lshl_add_u64 v[128:129], v[162:163], 1, s[34:35]
	s_nop 0
	global_load_dwordx4 v[128:131], v[128:129], off offset:256
	ds_read_b128 v[242:245], v181 offset:2368
	s_waitcnt lgkmcnt(4)
	v_mfma_f32_16x16x32_bf16 v[12:15], v[182:185], v[250:253], v[12:15]
	ds_read_b128 v[182:185], v202 offset:36928
	v_mfma_f32_16x16x32_bf16 v[8:11], v[186:189], v[250:253], v[8:11]
	ds_read_b128 v[186:189], v202 offset:39232
	v_mfma_f32_16x16x32_bf16 v[4:7], v[190:193], v[250:253], v[4:7]
	ds_read_b128 v[190:193], v202 offset:41536
	s_waitcnt vmcnt(7)
	ds_write_b128 v239, v[132:135] offset:36864
	v_mfma_f32_16x16x32_bf16 v[0:3], v[194:197], v[250:253], v[0:3]
	ds_read_b128 v[194:197], v202 offset:43840
	ds_read_b128 v[246:249], v181 offset:4672
	s_waitcnt lgkmcnt(5)
	v_mfma_f32_16x16x32_bf16 v[156:159], v[182:185], v[198:201], v[156:159]
	v_lshl_add_u64 v[132:133], v[164:165], 1, s[34:35]
	s_nop 0
	global_load_dwordx4 v[132:135], v[132:133], off offset:256
	s_waitcnt lgkmcnt(4)
	v_mfma_f32_16x16x32_bf16 v[152:155], v[186:189], v[198:201], v[152:155]
	s_waitcnt lgkmcnt(3)
	v_mfma_f32_16x16x32_bf16 v[148:151], v[190:193], v[198:201], v[148:151]
	s_waitcnt lgkmcnt(1)
	v_mfma_f32_16x16x32_bf16 v[144:147], v[194:197], v[198:201], v[144:147]
	s_waitcnt vmcnt(7)
	ds_write_b128 v255, v[140:143] offset:36864
	ds_read_b128 v[250:253], v181 offset:6976
	v_mfma_f32_16x16x32_bf16 v[108:111], v[182:185], v[242:245], v[108:111]
	v_mfma_f32_16x16x32_bf16 v[104:107], v[186:189], v[242:245], v[104:107]
	v_lshl_add_u64 v[140:141], v[166:167], 1, s[34:35]
	s_nop 0
	global_load_dwordx4 v[140:143], v[140:141], off offset:256
	v_mfma_f32_16x16x32_bf16 v[100:103], v[190:193], v[242:245], v[100:103]
	v_mfma_f32_16x16x32_bf16 v[96:99], v[194:197], v[242:245], v[96:99]
	ds_read_b128 v[198:201], v181 offset:9280
	s_waitcnt lgkmcnt(3)
	v_mfma_f32_16x16x32_bf16 v[92:95], v[182:185], v[246:249], v[92:95]
	v_mfma_f32_16x16x32_bf16 v[88:91], v[186:189], v[246:249], v[88:91]
	v_mfma_f32_16x16x32_bf16 v[84:87], v[190:193], v[246:249], v[84:87]
	v_mfma_f32_16x16x32_bf16 v[80:83], v[194:197], v[246:249], v[80:83]
	ds_read_b128 v[242:245], v181 offset:11584
	s_waitcnt lgkmcnt(2)
	v_mfma_f32_16x16x32_bf16 v[76:79], v[182:185], v[250:253], v[76:79]
	v_mfma_f32_16x16x32_bf16 v[72:75], v[186:189], v[250:253], v[72:75]
	v_mfma_f32_16x16x32_bf16 v[68:71], v[190:193], v[250:253], v[68:71]
	v_mfma_f32_16x16x32_bf16 v[64:67], v[194:197], v[250:253], v[64:67]
	ds_read_b128 v[246:249], v181 offset:13888
	s_waitcnt lgkmcnt(2)
	v_mfma_f32_16x16x32_bf16 v[60:63], v[182:185], v[198:201], v[60:63]
	v_mfma_f32_16x16x32_bf16 v[56:59], v[186:189], v[198:201], v[56:59]
	v_mfma_f32_16x16x32_bf16 v[52:55], v[190:193], v[198:201], v[52:55]
	v_mfma_f32_16x16x32_bf16 v[48:51], v[194:197], v[198:201], v[48:51]
	ds_read_b128 v[250:253], v181 offset:16192
	s_waitcnt lgkmcnt(2)
	v_mfma_f32_16x16x32_bf16 v[44:47], v[182:185], v[242:245], v[44:47]
	v_mfma_f32_16x16x32_bf16 v[40:43], v[186:189], v[242:245], v[40:43]
	v_mfma_f32_16x16x32_bf16 v[36:39], v[190:193], v[242:245], v[36:39]
	v_mfma_f32_16x16x32_bf16 v[32:35], v[194:197], v[242:245], v[32:35]
	s_add_i32 s30, s30, 1
	s_and_b32 s98, s30, 1
	s_mul_i32 s98, s98, 0x12000
	v_add3_u32 v181, s98, v170, v180
	v_add3_u32 v202, s98, v171, v180
	s_cmp_lg_u32 s30, 16
	s_waitcnt lgkmcnt(0)
	s_barrier
	s_cbranch_scc0 .Lgm6_exit
	ds_read_b128 v[198:201], v181
	ds_read_b128 v[242:245], v181 offset:2304
	v_mfma_f32_16x16x32_bf16 v[28:31], v[182:185], v[246:249], v[28:31]
	v_mfma_f32_16x16x32_bf16 v[12:15], v[182:185], v[250:253], v[12:15]
	ds_read_b128 v[182:185], v202 offset:36864
	v_mfma_f32_16x16x32_bf16 v[24:27], v[186:189], v[246:249], v[24:27]
	v_mfma_f32_16x16x32_bf16 v[8:11], v[186:189], v[250:253], v[8:11]
	ds_read_b128 v[186:189], v202 offset:39168
	v_mfma_f32_16x16x32_bf16 v[20:23], v[190:193], v[246:249], v[20:23]
	v_mfma_f32_16x16x32_bf16 v[4:7], v[190:193], v[250:253], v[4:7]
	ds_read_b128 v[190:193], v202 offset:41472
	v_mfma_f32_16x16x32_bf16 v[16:19], v[194:197], v[246:249], v[16:19]
	v_mfma_f32_16x16x32_bf16 v[0:3], v[194:197], v[250:253], v[0:3]
	ds_read_b128 v[194:197], v202 offset:43776
	s_branch .Lgm6_main

; DI f32x4 mfma16(bf16x8 a, bf16x8 b, f32x4 c) { return __builtin_amdgcn_mfma_f32_16x16x32_bf16(a, b, c, 0, 0, 0); }
; template <int MI, int NJ, bool SWAP, class AP, class BP>
; DI void gemm_main(f32x4 (&acc)[MI][NJ], const AP& ap, int a_kstep, const BP& bp, int b_kstep, int nk, bf16_t* smem) {
;     ...
;   auto gload = [&](int kt) {
;     const bf16_t* ab = ap.base + (size_t)kt * a_kstep; const bf16_t* bb = bp.base + (size_t)kt * b_kstep;
; #pragma unroll
;     for (int i = 0; i < CA; ++i) ra[i] = *(const u32x4*)(ab + pa[i]);
; #pragma unroll
;     for (int i = 0; i < CB; ++i) rb[i] = *(const u32x4*)(bb + pb[i]);
;   };
;   auto sstore = [&](int buf) {
;     bf16_t* As = smem + buf * L::STAGE; bf16_t* Bs = As + L::A_ELEMS;
; #pragma unroll
;     for (int i = 0; i < CA; ++i) { const int c = tid + NTHR * i; *(u32x4*)(As + (c >> 3) * LDT + (c & 7) * 8) = oka[i] ? ra[i] : (u32x4){0u, 0u, 0u, 0u}; }
; #pragma unroll
;     for (int i = 0; i < CB; ++i) { const int c = tid + NTHR * i; *(u32x4*)(Bs + (c >> 3) * LDT + (c & 7) * 8) = rb[i]; }
;   };
;   gload(0); sstore(0); gload(nk > 1 ? 1 : 0); __syncthreads();
; #pragma unroll 1
;   for (int kt = 0; kt < nk; ++kt) {
;     const int buf = kt & 1;
;     sstore(buf ^ 1);
;     gload(kt + 2 < nk ? kt + 2 : nk - 1);
;     __builtin_amdgcn_sched_barrier(0);
;     const bf16_t* As = smem + buf * L::STAGE + (wm * 16 * MI + l15) * LDT + quad * 8;
;     const bf16_t* Bs = smem + buf * L::STAGE + L::A_ELEMS + (wn * 16 * NJ + l15) * LDT + quad * 8;
; #pragma unroll
;     for (int ks = 0; ks < 2; ++ks) {
;       if (MI * NJ >= 32 && ks == 1) asm volatile("" ::: "memory");
;       bf16x8 b[NJ];
; #pragma unroll
;       for (int j = 0; j < NJ; ++j) b[j] = *(const bf16x8*)(Bs + j * 16 * LDT + ks * 32);
; #pragma unroll
;       for (int i = 0; i < MI; ++i) {
;         const bf16x8 a = *(const bf16x8*)(As + i * 16 * LDT + ks * 32);
; #pragma unroll
;         for (int j = 0; j < NJ; ++j) acc[i][j] = SWAP ? mfma16(b[j], a, acc[i][j]) : mfma16(a, b[j], acc[i][j]);
;       }
;     }
;     __syncthreads();
.Lgm7_main:
	ds_read_b128 v[242:245], v177 offset:4608
	s_waitcnt lgkmcnt(4)
	v_mfma_f32_16x16x32_bf16 v[156:159], v[178:181], v[194:197], v[156:159]
	s_and_b32 s24, s21, 1
	s_min_u32 s22, s21, 41
	s_xor_b32 s23, s24, 1
	s_mul_i32 s23, s23, 0x12000
	v_add3_u32 v250, s23, v172, v170
	s_waitcnt vmcnt(7)
	ds_write_b128 v250, v[112:115]
	s_waitcnt lgkmcnt(4)
	v_mfma_f32_16x16x32_bf16 v[152:155], v[182:185], v[194:197], v[152:155]
	s_waitcnt lgkmcnt(3)
	v_mfma_f32_16x16x32_bf16 v[148:151], v[186:189], v[194:197], v[148:151]
	s_lshl_b32 s25, s22, 7
	s_add_u32 s22, s6, s25
	v_add3_u32 v251, s23, v173, v170
	v_add3_u32 v252, s23, v174, v170
	v_add3_u32 v253, s23, v175, v170
	s_addc_u32 s23, s7, 0
	v_lshl_add_u64 v[112:113], s[22:23], 0, v[162:163]
	s_nop 0
	global_load_dwordx4 v[112:115], v[112:113], off offset:256
	s_waitcnt lgkmcnt(2)
	v_mfma_f32_16x16x32_bf16 v[144:147], v[190:193], v[194:197], v[144:147]
	ds_read_b128 v[246:249], v177 offset:6912
	v_mfma_f32_16x16x32_bf16 v[108:111], v[178:181], v[198:201], v[108:111]
	v_mfma_f32_16x16x32_bf16 v[104:107], v[182:185], v[198:201], v[104:107]
	s_waitcnt vmcnt(7)
	ds_write_b128 v251, v[116:119]
	v_mfma_f32_16x16x32_bf16 v[100:103], v[186:189], v[198:201], v[100:103]
	v_mfma_f32_16x16x32_bf16 v[96:99], v[190:193], v[198:201], v[96:99]
	v_lshl_add_u64 v[116:117], s[22:23], 0, v[164:165]
	s_nop 0
	global_load_dwordx4 v[116:119], v[116:117], off offset:256
	ds_read_b128 v[194:197], v177 offset:9216
	s_waitcnt lgkmcnt(4)
	v_mfma_f32_16x16x32_bf16 v[92:95], v[178:181], v[242:245], v[92:95]
	v_mfma_f32_16x16x32_bf16 v[88:91], v[182:185], v[242:245], v[88:91]
	v_mfma_f32_16x16x32_bf16 v[84:87], v[186:189], v[242:245], v[84:87]
	s_waitcnt vmcnt(7)
	ds_write_b128 v252, v[120:123]
	v_mfma_f32_16x16x32_bf16 v[80:83], v[190:193], v[242:245], v[80:83]
	ds_read_b128 v[198:201], v177 offset:11520
	s_waitcnt lgkmcnt(4)
	v_mfma_f32_16x16x32_bf16 v[76:79], v[178:181], v[246:249], v[76:79]
	v_lshl_add_u64 v[120:121], s[22:23], 0, v[166:167]
	s_nop 0
	global_load_dwordx4 v[120:123], v[120:121], off offset:256
	v_mfma_f32_16x16x32_bf16 v[72:75], v[182:185], v[246:249], v[72:75]
	v_mfma_f32_16x16x32_bf16 v[68:71], v[186:189], v[246:249], v[68:71]
	v_mfma_f32_16x16x32_bf16 v[64:67], v[190:193], v[246:249], v[64:67]
	s_waitcnt vmcnt(7)
	ds_write_b128 v253, v[124:127]
	ds_read_b128 v[242:245], v177 offset:13824
	s_waitcnt lgkmcnt(4)
	v_mfma_f32_16x16x32_bf16 v[60:63], v[178:181], v[194:197], v[60:63]
	v_mfma_f32_16x16x32_bf16 v[56:59], v[182:185], v[194:197], v[56:59]
	v_lshl_add_u64 v[124:125], s[22:23], 0, v[168:169]
	s_nop 0
	global_load_dwordx4 v[124:127], v[124:125], off offset:256
	v_mfma_f32_16x16x32_bf16 v[52:55], v[186:189], v[194:197], v[52:55]
	v_mfma_f32_16x16x32_bf16 v[48:51], v[190:193], v[194:197], v[48:51]
	ds_read_b128 v[246:249], v177 offset:16128
	s_waitcnt lgkmcnt(3)
	v_mfma_f32_16x16x32_bf16 v[44:47], v[178:181], v[198:201], v[44:47]
	s_waitcnt vmcnt(7)
	ds_write_b128 v250, v[128:131] offset:36864
	v_mfma_f32_16x16x32_bf16 v[40:43], v[182:185], v[198:201], v[40:43]
	v_mfma_f32_16x16x32_bf16 v[36:39], v[186:189], v[198:201], v[36:39]
	s_add_u32 s22, s8, s25
	s_addc_u32 s23, s9, 0
	v_lshl_add_u64 v[128:129], s[22:23], 0, v[162:163]
	s_nop 0
	global_load_dwordx4 v[128:131], v[128:129], off offset:256
	v_mfma_f32_16x16x32_bf16 v[32:35], v[190:193], v[198:201], v[32:35]
	ds_read_b128 v[194:197], v177 offset:64
	s_waitcnt lgkmcnt(3)
	v_mfma_f32_16x16x32_bf16 v[28:31], v[178:181], v[242:245], v[28:31]
	v_mfma_f32_16x16x32_bf16 v[24:27], v[182:185], v[242:245], v[24:27]
	s_waitcnt vmcnt(7)
	ds_write_b128 v251, v[132:135] offset:36864
	v_mfma_f32_16x16x32_bf16 v[20:23], v[186:189], v[242:245], v[20:23]
	v_mfma_f32_16x16x32_bf16 v[16:19], v[190:193], v[242:245], v[16:19]
	v_lshl_add_u64 v[132:133], s[22:23], 0, v[164:165]
	s_nop 0
	global_load_dwordx4 v[132:135], v[132:133], off offset:256
	ds_read_b128 v[198:201], v177 offset:2368
	s_waitcnt lgkmcnt(4)
; DI f32x4 mfma16(bf16x8 a, bf16x8 b, f32x4 c) { return __builtin_amdgcn_mfma_f32_16x16x32_bf16(a, b, c, 0, 0, 0); }
; template <int MI, int NJ, bool SWAP, class AP, class BP>
; DI void gemm_main(f32x4 (&acc)[MI][NJ], const AP& ap, int a_kstep, const BP& bp, int b_kstep, int nk, bf16_t* smem) {
;     ...
;   auto gload = [&](int kt) {
;     const bf16_t* ab = ap.base + (size_t)kt * a_kstep; const bf16_t* bb = bp.base + (size_t)kt * b_kstep;
; #pragma unroll
;     for (int i = 0; i < CA; ++i) ra[i] = *(const u32x4*)(ab + pa[i]);
; #pragma unroll
;     for (int i = 0; i < CB; ++i) rb[i] = *(const u32x4*)(bb + pb[i]);
;   };
;   auto sstore = [&](int buf) {
;     bf16_t* As = smem + buf * L::STAGE; bf16_t* Bs = As + L::A_ELEMS;
; #pragma unroll
;     for (int i = 0; i < CA; ++i) { const int c = tid + NTHR * i; *(u32x4*)(As + (c >> 3) * LDT + (c & 7) * 8) = oka[i] ? ra[i] : (u32x4){0u, 0u, 0u, 0u}; }
; #pragma unroll
;     for (int i = 0; i < CB; ++i) { const int c = tid + NTHR * i; *(u32x4*)(Bs + (c >> 3) * LDT + (c & 7) * 8) = rb[i]; }
;   };
;   gload(0); sstore(0); gload(nk > 1 ? 1 : 0); __syncthreads();
; #pragma unroll 1
;   for (int kt = 0; kt < nk; ++kt) {
;     const int buf = kt & 1;
;     sstore(buf ^ 1);
;     gload(kt + 2 < nk ? kt + 2 : nk - 1);
;     __builtin_amdgcn_sched_barrier(0);
;     const bf16_t* As = smem + buf * L::STAGE + (wm * 16 * MI + l15) * LDT + quad * 8;
;     const bf16_t* Bs = smem + buf * L::STAGE + L::A_ELEMS + (wn * 16 * NJ + l15) * LDT + quad * 8;
; #pragma unroll
;     for (int ks = 0; ks < 2; ++ks) {
;       if (MI * NJ >= 32 && ks == 1) asm volatile("" ::: "memory");
;       bf16x8 b[NJ];
; #pragma unroll
;       for (int j = 0; j < NJ; ++j) b[j] = *(const bf16x8*)(Bs + j * 16 * LDT + ks * 32);
; #pragma unroll
;       for (int i = 0; i < MI; ++i) {
;         const bf16x8 a = *(const bf16x8*)(As + i * 16 * LDT + ks * 32);
; #pragma unroll
;         for (int j = 0; j < NJ; ++j) acc[i][j] = SWAP ? mfma16(b[j], a, acc[i][j]) : mfma16(a, b[j], acc[i][j]);
;       }
;     }
;     __syncthreads();
	v_mfma_f32_16x16x32_bf16 v[8:11], v[178:181], v[246:249], v[8:11]
	ds_read_b128 v[178:181], v202 offset:36928
	v_mfma_f32_16x16x32_bf16 v[4:7], v[182:185], v[246:249], v[4:7]
	ds_read_b128 v[182:185], v202 offset:39232
	v_mfma_f32_16x16x32_bf16 v[0:3], v[186:189], v[246:249], v[0:3]
	ds_read_b128 v[186:189], v202 offset:41536
	s_waitcnt vmcnt(7)
	ds_write_b128 v252, v[136:139] offset:36864
	v_mfma_f32_16x16x32_bf16 v[12:15], v[190:193], v[246:249], v[12:15]
	ds_read_b128 v[190:193], v202 offset:43840
	ds_read_b128 v[242:245], v177 offset:4672
	s_waitcnt lgkmcnt(5)
	v_mfma_f32_16x16x32_bf16 v[156:159], v[178:181], v[194:197], v[156:159]
	v_lshl_add_u64 v[136:137], s[22:23], 0, v[166:167]
	s_nop 0
	global_load_dwordx4 v[136:139], v[136:137], off offset:256
	s_waitcnt lgkmcnt(4)
	v_mfma_f32_16x16x32_bf16 v[152:155], v[182:185], v[194:197], v[152:155]
	s_waitcnt lgkmcnt(3)
	v_mfma_f32_16x16x32_bf16 v[148:151], v[186:189], v[194:197], v[148:151]
	s_waitcnt lgkmcnt(1)
	v_mfma_f32_16x16x32_bf16 v[144:147], v[190:193], v[194:197], v[144:147]
	s_waitcnt vmcnt(7)
	ds_write_b128 v253, v[140:143] offset:36864
	ds_read_b128 v[246:249], v177 offset:6976
	v_mfma_f32_16x16x32_bf16 v[108:111], v[178:181], v[198:201], v[108:111]
	v_mfma_f32_16x16x32_bf16 v[104:107], v[182:185], v[198:201], v[104:107]
	v_lshl_add_u64 v[140:141], s[22:23], 0, v[168:169]
	s_nop 0
	global_load_dwordx4 v[140:143], v[140:141], off offset:256
	v_mfma_f32_16x16x32_bf16 v[100:103], v[186:189], v[198:201], v[100:103]
	v_mfma_f32_16x16x32_bf16 v[96:99], v[190:193], v[198:201], v[96:99]
	ds_read_b128 v[194:197], v177 offset:9280
	s_waitcnt lgkmcnt(3)
	v_mfma_f32_16x16x32_bf16 v[92:95], v[178:181], v[242:245], v[92:95]
	v_mfma_f32_16x16x32_bf16 v[88:91], v[182:185], v[242:245], v[88:91]
	v_mfma_f32_16x16x32_bf16 v[84:87], v[186:189], v[242:245], v[84:87]
	v_mfma_f32_16x16x32_bf16 v[80:83], v[190:193], v[242:245], v[80:83]
	ds_read_b128 v[198:201], v177 offset:11584
	s_waitcnt lgkmcnt(2)
	v_mfma_f32_16x16x32_bf16 v[76:79], v[178:181], v[246:249], v[76:79]
	v_mfma_f32_16x16x32_bf16 v[72:75], v[182:185], v[246:249], v[72:75]
	v_mfma_f32_16x16x32_bf16 v[68:71], v[186:189], v[246:249], v[68:71]
	v_mfma_f32_16x16x32_bf16 v[64:67], v[190:193], v[246:249], v[64:67]
	ds_read_b128 v[242:245], v177 offset:13888
	s_waitcnt lgkmcnt(2)
	v_mfma_f32_16x16x32_bf16 v[60:63], v[178:181], v[194:197], v[60:63]
	v_mfma_f32_16x16x32_bf16 v[56:59], v[182:185], v[194:197], v[56:59]
	v_mfma_f32_16x16x32_bf16 v[52:55], v[186:189], v[194:197], v[52:55]
	v_mfma_f32_16x16x32_bf16 v[48:51], v[190:193], v[194:197], v[48:51]
	ds_read_b128 v[246:249], v177 offset:16192
	s_waitcnt lgkmcnt(2)
	v_mfma_f32_16x16x32_bf16 v[44:47], v[178:181], v[198:201], v[44:47]
	v_mfma_f32_16x16x32_bf16 v[40:43], v[182:185], v[198:201], v[40:43]
	v_mfma_f32_16x16x32_bf16 v[36:39], v[186:189], v[198:201], v[36:39]
	v_mfma_f32_16x16x32_bf16 v[32:35], v[190:193], v[198:201], v[32:35]
	s_add_i32 s21, s21, 1
	s_and_b32 s98, s21, 1
	s_mul_i32 s98, s98, 0x12000
	v_add3_u32 v202, s98, v160, v176
	v_add3_u32 v177, s98, v171, v176
	s_cmp_lg_u32 s21, 44
	s_waitcnt lgkmcnt(0)
	s_barrier
	s_cbranch_scc0 .Lgm7_exit
	ds_read_b128 v[194:197], v177
	ds_read_b128 v[198:201], v177 offset:2304
	v_mfma_f32_16x16x32_bf16 v[28:31], v[178:181], v[242:245], v[28:31]
	v_mfma_f32_16x16x32_bf16 v[8:11], v[178:181], v[246:249], v[8:11]
	ds_read_b128 v[178:181], v202 offset:36864
	v_mfma_f32_16x16x32_bf16 v[24:27], v[182:185], v[242:245], v[24:27]
	v_mfma_f32_16x16x32_bf16 v[4:7], v[182:185], v[246:249], v[4:7]
	ds_read_b128 v[182:185], v202 offset:39168
	v_mfma_f32_16x16x32_bf16 v[20:23], v[186:189], v[242:245], v[20:23]
	v_mfma_f32_16x16x32_bf16 v[0:3], v[186:189], v[246:249], v[0:3]
	ds_read_b128 v[186:189], v202 offset:41472
	v_mfma_f32_16x16x32_bf16 v[16:19], v[190:193], v[242:245], v[16:19]
	v_mfma_f32_16x16x32_bf16 v[12:15], v[190:193], v[246:249], v[12:15]
	ds_read_b128 v[190:193], v202 offset:43776
	s_branch .Lgm7_main

; DI f32x4 mfma16(bf16x8 a, bf16x8 b, f32x4 c) { return __builtin_amdgcn_mfma_f32_16x16x32_bf16(a, b, c, 0, 0, 0); }
; template <int MI, int NJ, bool SWAP, class AP, class BP>
; DI void gemm_main(f32x4 (&acc)[MI][NJ], const AP& ap, int a_kstep, const BP& bp, int b_kstep, int nk, bf16_t* smem) {
;     ...
;   auto gload = [&](int kt) {
;     const bf16_t* ab = ap.base + (size_t)kt * a_kstep; const bf16_t* bb = bp.base + (size_t)kt * b_kstep;
; #pragma unroll
;     for (int i = 0; i < CA; ++i) ra[i] = *(const u32x4*)(ab + pa[i]);
; #pragma unroll
;     for (int i = 0; i < CB; ++i) rb[i] = *(const u32x4*)(bb + pb[i]);
;   };
;   auto sstore = [&](int buf) {
;     bf16_t* As = smem + buf * L::STAGE; bf16_t* Bs = As + L::A_ELEMS;
; #pragma unroll
;     for (int i = 0; i < CA; ++i) { const int c = tid + NTHR * i; *(u32x4*)(As + (c >> 3) * LDT + (c & 7) * 8) = oka[i] ? ra[i] : (u32x4){0u, 0u, 0u, 0u}; }
; #pragma unroll
;     for (int i = 0; i < CB; ++i) { const int c = tid + NTHR * i; *(u32x4*)(Bs + (c >> 3) * LDT + (c & 7) * 8) = rb[i]; }
;   };
;   gload(0); sstore(0); gload(nk > 1 ? 1 : 0); __syncthreads();
; #pragma unroll 1
;   for (int kt = 0; kt < nk; ++kt) {
;     const int buf = kt & 1;
;     sstore(buf ^ 1);
;     gload(kt + 2 < nk ? kt + 2 : nk - 1);
;     __builtin_amdgcn_sched_barrier(0);
;     const bf16_t* As = smem + buf * L::STAGE + (wm * 16 * MI + l15) * LDT + quad * 8;
;     const bf16_t* Bs = smem + buf * L::STAGE + L::A_ELEMS + (wn * 16 * NJ + l15) * LDT + quad * 8;
; #pragma unroll
;     for (int ks = 0; ks < 2; ++ks) {
;       if (MI * NJ >= 32 && ks == 1) asm volatile("" ::: "memory");
;       bf16x8 b[NJ];
; #pragma unroll
;       for (int j = 0; j < NJ; ++j) b[j] = *(const bf16x8*)(Bs + j * 16 * LDT + ks * 32);
; #pragma unroll
;       for (int i = 0; i < MI; ++i) {
;         const bf16x8 a = *(const bf16x8*)(As + i * 16 * LDT + ks * 32);
; #pragma unroll
;         for (int j = 0; j < NJ; ++j) acc[i][j] = SWAP ? mfma16(b[j], a, acc[i][j]) : mfma16(a, b[j], acc[i][j]);
;       }
;     }
;     __syncthreads();
.Lgm8_main:
	ds_read_b128 v[246:249], v210 offset:4608
	s_waitcnt lgkmcnt(4)
	v_mfma_f32_16x16x32_bf16 v[124:127], v[190:193], v[206:209], v[124:127]
	s_and_b32 s5, s4, 1
	s_xor_b32 s23, s5, 1
	s_mul_i32 s23, s23, 0x12000
	v_add3_u32 v254, s23, v185, v183
	s_waitcnt vmcnt(7)
	ds_write_b128 v254, v[128:131]
	s_waitcnt lgkmcnt(4)
	v_mfma_f32_16x16x32_bf16 v[120:123], v[194:197], v[206:209], v[120:123]
	s_waitcnt lgkmcnt(3)
	v_mfma_f32_16x16x32_bf16 v[116:119], v[198:201], v[206:209], v[116:119]
	s_min_u32 s99, s4, 13
	s_lshl_b32 s99, s99, 7
	s_add_u32 s26, s0, s99
	s_addc_u32 s27, s1, 0
	v_lshl_add_u64 v[128:129], s[26:27], 0, v[162:163]
	s_nop 0
	global_load_dwordx4 v[128:131], v[128:129], off offset:256
	s_waitcnt lgkmcnt(2)
	v_mfma_f32_16x16x32_bf16 v[112:115], v[202:205], v[206:209], v[112:115]
	ds_read_b128 v[250:253], v210 offset:6912
	v_mfma_f32_16x16x32_bf16 v[108:111], v[190:193], v[242:245], v[108:111]
	v_mfma_f32_16x16x32_bf16 v[104:107], v[194:197], v[242:245], v[104:107]
	v_add3_u32 v238, s23, v187, v183
	s_waitcnt vmcnt(7)
	ds_write_b128 v238, v[132:135]
	v_mfma_f32_16x16x32_bf16 v[100:103], v[198:201], v[242:245], v[100:103]
	v_mfma_f32_16x16x32_bf16 v[96:99], v[202:205], v[242:245], v[96:99]
	v_lshl_add_u64 v[132:133], s[26:27], 0, v[164:165]
	s_nop 0
	global_load_dwordx4 v[132:135], v[132:133], off offset:256
	ds_read_b128 v[206:209], v210 offset:9216
	s_waitcnt lgkmcnt(4)
	v_mfma_f32_16x16x32_bf16 v[92:95], v[190:193], v[246:249], v[92:95]
	v_mfma_f32_16x16x32_bf16 v[88:91], v[194:197], v[246:249], v[88:91]
	v_mfma_f32_16x16x32_bf16 v[84:87], v[198:201], v[246:249], v[84:87]
	v_add3_u32 v239, s23, v188, v183
	s_waitcnt vmcnt(7)
	ds_write_b128 v239, v[136:139]
	v_mfma_f32_16x16x32_bf16 v[80:83], v[202:205], v[246:249], v[80:83]
	ds_read_b128 v[242:245], v210 offset:11520
	s_waitcnt lgkmcnt(4)
	v_mfma_f32_16x16x32_bf16 v[76:79], v[190:193], v[250:253], v[76:79]
	v_lshl_add_u64 v[136:137], s[26:27], 0, v[166:167]
	s_nop 0
	global_load_dwordx4 v[136:139], v[136:137], off offset:256
	v_mfma_f32_16x16x32_bf16 v[72:75], v[194:197], v[250:253], v[72:75]
	v_mfma_f32_16x16x32_bf16 v[68:71], v[198:201], v[250:253], v[68:71]
	v_mfma_f32_16x16x32_bf16 v[64:67], v[202:205], v[250:253], v[64:67]
	v_add3_u32 v255, s23, v189, v183
	s_waitcnt vmcnt(7)
	ds_write_b128 v255, v[140:143]
	ds_read_b128 v[246:249], v210 offset:13824
	s_waitcnt lgkmcnt(4)
	v_mfma_f32_16x16x32_bf16 v[60:63], v[190:193], v[206:209], v[60:63]
	v_mfma_f32_16x16x32_bf16 v[56:59], v[194:197], v[206:209], v[56:59]
	v_lshl_add_u64 v[140:141], s[26:27], 0, v[168:169]
	s_nop 0
	global_load_dwordx4 v[140:143], v[140:141], off offset:256
	v_mfma_f32_16x16x32_bf16 v[52:55], v[198:201], v[206:209], v[52:55]
	v_mfma_f32_16x16x32_bf16 v[48:51], v[202:205], v[206:209], v[48:51]
	ds_read_b128 v[250:253], v210 offset:16128
	s_waitcnt lgkmcnt(3)
	v_mfma_f32_16x16x32_bf16 v[44:47], v[190:193], v[242:245], v[44:47]
	s_waitcnt vmcnt(7)
	ds_write_b128 v254, v[144:147] offset:36864
	v_mfma_f32_16x16x32_bf16 v[40:43], v[194:197], v[242:245], v[40:43]
	v_mfma_f32_16x16x32_bf16 v[36:39], v[198:201], v[242:245], v[36:39]
	s_add_u32 s26, s2, s99
	s_addc_u32 s27, s3, 0
	v_lshl_add_u64 v[144:145], s[26:27], 0, v[162:163]
	s_nop 0
	global_load_dwordx4 v[144:147], v[144:145], off offset:256
	v_mfma_f32_16x16x32_bf16 v[32:35], v[202:205], v[242:245], v[32:35]
	ds_read_b128 v[206:209], v210 offset:64
	s_waitcnt lgkmcnt(3)
	v_mfma_f32_16x16x32_bf16 v[28:31], v[190:193], v[246:249], v[28:31]
	v_mfma_f32_16x16x32_bf16 v[24:27], v[194:197], v[246:249], v[24:27]
	s_waitcnt vmcnt(7)
	ds_write_b128 v238, v[148:151] offset:36864
	v_mfma_f32_16x16x32_bf16 v[20:23], v[198:201], v[246:249], v[20:23]
	v_mfma_f32_16x16x32_bf16 v[16:19], v[202:205], v[246:249], v[16:19]
	v_lshl_add_u64 v[148:149], s[26:27], 0, v[164:165]
	s_nop 0
	global_load_dwordx4 v[148:151], v[148:149], off offset:256
	ds_read_b128 v[242:245], v210 offset:2368
	s_waitcnt lgkmcnt(4)
; DI f32x4 mfma16(bf16x8 a, bf16x8 b, f32x4 c) { return __builtin_amdgcn_mfma_f32_16x16x32_bf16(a, b, c, 0, 0, 0); }
; template <int MI, int NJ, bool SWAP, class AP, class BP>
; DI void gemm_main(f32x4 (&acc)[MI][NJ], const AP& ap, int a_kstep, const BP& bp, int b_kstep, int nk, bf16_t* smem) {
;     ...
;   auto gload = [&](int kt) {
;     const bf16_t* ab = ap.base + (size_t)kt * a_kstep; const bf16_t* bb = bp.base + (size_t)kt * b_kstep;
; #pragma unroll
;     for (int i = 0; i < CA; ++i) ra[i] = *(const u32x4*)(ab + pa[i]);
; #pragma unroll
;     for (int i = 0; i < CB; ++i) rb[i] = *(const u32x4*)(bb + pb[i]);
;   };
;   auto sstore = [&](int buf) {
;     bf16_t* As = smem + buf * L::STAGE; bf16_t* Bs = As + L::A_ELEMS;
; #pragma unroll
;     for (int i = 0; i < CA; ++i) { const int c = tid + NTHR * i; *(u32x4*)(As + (c >> 3) * LDT + (c & 7) * 8) = oka[i] ? ra[i] : (u32x4){0u, 0u, 0u, 0u}; }
; #pragma unroll
;     for (int i = 0; i < CB; ++i) { const int c = tid + NTHR * i; *(u32x4*)(Bs + (c >> 3) * LDT + (c & 7) * 8) = rb[i]; }
;   };
;   gload(0); sstore(0); gload(nk > 1 ? 1 : 0); __syncthreads();
; #pragma unroll 1
;   for (int kt = 0; kt < nk; ++kt) {
;     const int buf = kt & 1;
;     sstore(buf ^ 1);
;     gload(kt + 2 < nk ? kt + 2 : nk - 1);
;     __builtin_amdgcn_sched_barrier(0);
;     const bf16_t* As = smem + buf * L::STAGE + (wm * 16 * MI + l15) * LDT + quad * 8;
;     const bf16_t* Bs = smem + buf * L::STAGE + L::A_ELEMS + (wn * 16 * NJ + l15) * LDT + quad * 8;
; #pragma unroll
;     for (int ks = 0; ks < 2; ++ks) {
;       if (MI * NJ >= 32 && ks == 1) asm volatile("" ::: "memory");
;       bf16x8 b[NJ];
; #pragma unroll
;       for (int j = 0; j < NJ; ++j) b[j] = *(const bf16x8*)(Bs + j * 16 * LDT + ks * 32);
; #pragma unroll
;       for (int i = 0; i < MI; ++i) {
;         const bf16x8 a = *(const bf16x8*)(As + i * 16 * LDT + ks * 32);
; #pragma unroll
;         for (int j = 0; j < NJ; ++j) acc[i][j] = SWAP ? mfma16(b[j], a, acc[i][j]) : mfma16(a, b[j], acc[i][j]);
;       }
;     }
;     __syncthreads();
	v_mfma_f32_16x16x32_bf16 v[12:15], v[190:193], v[250:253], v[12:15]
	ds_read_b128 v[190:193], v211 offset:36928
	v_mfma_f32_16x16x32_bf16 v[8:11], v[194:197], v[250:253], v[8:11]
	ds_read_b128 v[194:197], v211 offset:39232
	v_mfma_f32_16x16x32_bf16 v[4:7], v[198:201], v[250:253], v[4:7]
	ds_read_b128 v[198:201], v211 offset:41536
	s_waitcnt vmcnt(7)
	ds_write_b128 v239, v[152:155] offset:36864
	v_mfma_f32_16x16x32_bf16 v[0:3], v[202:205], v[250:253], v[0:3]
	ds_read_b128 v[202:205], v211 offset:43840
	ds_read_b128 v[246:249], v210 offset:4672
	s_waitcnt lgkmcnt(5)
	v_mfma_f32_16x16x32_bf16 v[124:127], v[190:193], v[206:209], v[124:127]
	v_lshl_add_u64 v[152:153], s[26:27], 0, v[166:167]
	s_nop 0
	global_load_dwordx4 v[152:155], v[152:153], off offset:256
	s_waitcnt lgkmcnt(4)
	v_mfma_f32_16x16x32_bf16 v[120:123], v[194:197], v[206:209], v[120:123]
	s_waitcnt lgkmcnt(3)
	v_mfma_f32_16x16x32_bf16 v[116:119], v[198:201], v[206:209], v[116:119]
	s_waitcnt lgkmcnt(1)
	v_mfma_f32_16x16x32_bf16 v[112:115], v[202:205], v[206:209], v[112:115]
	s_waitcnt vmcnt(7)
	ds_write_b128 v255, v[156:159] offset:36864
	ds_read_b128 v[250:253], v210 offset:6976
	v_mfma_f32_16x16x32_bf16 v[108:111], v[190:193], v[242:245], v[108:111]
	v_mfma_f32_16x16x32_bf16 v[104:107], v[194:197], v[242:245], v[104:107]
	v_lshl_add_u64 v[156:157], s[26:27], 0, v[168:169]
	s_nop 0
	global_load_dwordx4 v[156:159], v[156:157], off offset:256
	v_mfma_f32_16x16x32_bf16 v[100:103], v[198:201], v[242:245], v[100:103]
	v_mfma_f32_16x16x32_bf16 v[96:99], v[202:205], v[242:245], v[96:99]
	ds_read_b128 v[206:209], v210 offset:9280
	s_waitcnt lgkmcnt(3)
	v_mfma_f32_16x16x32_bf16 v[92:95], v[190:193], v[246:249], v[92:95]
	v_mfma_f32_16x16x32_bf16 v[88:91], v[194:197], v[246:249], v[88:91]
	v_mfma_f32_16x16x32_bf16 v[84:87], v[198:201], v[246:249], v[84:87]
	v_mfma_f32_16x16x32_bf16 v[80:83], v[202:205], v[246:249], v[80:83]
	ds_read_b128 v[242:245], v210 offset:11584
	s_waitcnt lgkmcnt(2)
	v_mfma_f32_16x16x32_bf16 v[76:79], v[190:193], v[250:253], v[76:79]
	v_mfma_f32_16x16x32_bf16 v[72:75], v[194:197], v[250:253], v[72:75]
	v_mfma_f32_16x16x32_bf16 v[68:71], v[198:201], v[250:253], v[68:71]
	v_mfma_f32_16x16x32_bf16 v[64:67], v[202:205], v[250:253], v[64:67]
	ds_read_b128 v[246:249], v210 offset:13888
	s_waitcnt lgkmcnt(2)
	v_mfma_f32_16x16x32_bf16 v[60:63], v[190:193], v[206:209], v[60:63]
	v_mfma_f32_16x16x32_bf16 v[56:59], v[194:197], v[206:209], v[56:59]
	v_mfma_f32_16x16x32_bf16 v[52:55], v[198:201], v[206:209], v[52:55]
	v_mfma_f32_16x16x32_bf16 v[48:51], v[202:205], v[206:209], v[48:51]
	ds_read_b128 v[250:253], v210 offset:16192
	s_waitcnt lgkmcnt(2)
	v_mfma_f32_16x16x32_bf16 v[44:47], v[190:193], v[242:245], v[44:47]
	v_mfma_f32_16x16x32_bf16 v[40:43], v[194:197], v[242:245], v[40:43]
	v_mfma_f32_16x16x32_bf16 v[36:39], v[198:201], v[242:245], v[36:39]
	v_mfma_f32_16x16x32_bf16 v[32:35], v[202:205], v[242:245], v[32:35]
	s_add_i32 s4, s4, 1
	s_and_b32 s98, s4, 1
	s_mul_i32 s98, s98, 0x12000
	v_add3_u32 v210, s98, v184, v186
	v_add3_u32 v211, s98, v160, v186
	s_cmp_lg_u32 s4, 16
	s_waitcnt lgkmcnt(0)
	s_barrier
	s_cbranch_scc0 .Lgm8_exit
	ds_read_b128 v[206:209], v210
	ds_read_b128 v[242:245], v210 offset:2304
	v_mfma_f32_16x16x32_bf16 v[28:31], v[190:193], v[246:249], v[28:31]
	v_mfma_f32_16x16x32_bf16 v[12:15], v[190:193], v[250:253], v[12:15]
	ds_read_b128 v[190:193], v211 offset:36864
	v_mfma_f32_16x16x32_bf16 v[24:27], v[194:197], v[246:249], v[24:27]
	v_mfma_f32_16x16x32_bf16 v[8:11], v[194:197], v[250:253], v[8:11]
	ds_read_b128 v[194:197], v211 offset:39168
	v_mfma_f32_16x16x32_bf16 v[20:23], v[198:201], v[246:249], v[20:23]
	v_mfma_f32_16x16x32_bf16 v[4:7], v[198:201], v[250:253], v[4:7]
	ds_read_b128 v[198:201], v211 offset:41472
	v_mfma_f32_16x16x32_bf16 v[16:19], v[202:205], v[246:249], v[16:19]
	v_mfma_f32_16x16x32_bf16 v[0:3], v[202:205], v[250:253], v[0:3]
	ds_read_b128 v[202:205], v211 offset:43776
	s_branch .Lgm8_main

; DI f32x4 mfma16(bf16x8 a, bf16x8 b, f32x4 c) { return __builtin_amdgcn_mfma_f32_16x16x32_bf16(a, b, c, 0, 0, 0); }
; template <int MI, int NJ, bool SWAP, class AP, class BP>
; DI void gemm_main(f32x4 (&acc)[MI][NJ], const AP& ap, int a_kstep, const BP& bp, int b_kstep, int nk, bf16_t* smem) {
;     ...
;   auto gload = [&](int kt) {
;     const bf16_t* ab = ap.base + (size_t)kt * a_kstep; const bf16_t* bb = bp.base + (size_t)kt * b_kstep;
; #pragma unroll
;     for (int i = 0; i < CA; ++i) ra[i] = *(const u32x4*)(ab + pa[i]);
; #pragma unroll
;     for (int i = 0; i < CB; ++i) rb[i] = *(const u32x4*)(bb + pb[i]);
;   };
;   auto sstore = [&](int buf) {
;     bf16_t* As = smem + buf * L::STAGE; bf16_t* Bs = As + L::A_ELEMS;
; #pragma unroll
;     for (int i = 0; i < CA; ++i) { const int c = tid + NTHR * i; *(u32x4*)(As + (c >> 3) * LDT + (c & 7) * 8) = oka[i] ? ra[i] : (u32x4){0u, 0u, 0u, 0u}; }
; #pragma unroll
;     for (int i = 0; i < CB; ++i) { const int c = tid + NTHR * i; *(u32x4*)(Bs + (c >> 3) * LDT + (c & 7) * 8) = rb[i]; }
;   };
;   gload(0); sstore(0); gload(nk > 1 ? 1 : 0); __syncthreads();
; #pragma unroll 1
;   for (int kt = 0; kt < nk; ++kt) {
;     const int buf = kt & 1;
;     sstore(buf ^ 1);
;     gload(kt + 2 < nk ? kt + 2 : nk - 1);
;     __builtin_amdgcn_sched_barrier(0);
;     const bf16_t* As = smem + buf * L::STAGE + (wm * 16 * MI + l15) * LDT + quad * 8;
;     const bf16_t* Bs = smem + buf * L::STAGE + L::A_ELEMS + (wn * 16 * NJ + l15) * LDT + quad * 8;
; #pragma unroll
;     for (int ks = 0; ks < 2; ++ks) {
;       if (MI * NJ >= 32 && ks == 1) asm volatile("" ::: "memory");
;       bf16x8 b[NJ];
; #pragma unroll
;       for (int j = 0; j < NJ; ++j) b[j] = *(const bf16x8*)(Bs + j * 16 * LDT + ks * 32);
; #pragma unroll
;       for (int i = 0; i < MI; ++i) {
;         const bf16x8 a = *(const bf16x8*)(As + i * 16 * LDT + ks * 32);
; #pragma unroll
;         for (int j = 0; j < NJ; ++j) acc[i][j] = SWAP ? mfma16(b[j], a, acc[i][j]) : mfma16(a, b[j], acc[i][j]);
;       }
;     }
;     __syncthreads();
.Lgm10_main:
	ds_read_b128 v[246:249], v198 offset:4608
	s_waitcnt lgkmcnt(4)
	v_mfma_f32_16x16x32_bf16 v[156:159], v[178:181], v[194:197], v[156:159]
	s_and_b32 s33, s8, 1
	s_xor_b32 s37, s33, 1
	s_mul_i32 s37, s37, 0x12000
	v_add3_u32 v254, s37, v173, v171
	s_waitcnt vmcnt(7)
	ds_write_b128 v254, v[112:115]
	s_waitcnt lgkmcnt(4)
	v_mfma_f32_16x16x32_bf16 v[152:155], v[182:185], v[194:197], v[152:155]
	s_waitcnt lgkmcnt(3)
	v_mfma_f32_16x16x32_bf16 v[148:151], v[186:189], v[194:197], v[148:151]
	s_min_u32 s99, s8, 3
	s_lshl_b32 s99, s99, 7
	s_add_u32 s38, s0, s99
	s_addc_u32 s39, s1, 0
	v_lshl_add_u64 v[112:113], s[38:39], 0, v[162:163]
	s_nop 0
	global_load_dwordx4 v[112:115], v[112:113], off offset:256
	s_waitcnt lgkmcnt(2)
	v_mfma_f32_16x16x32_bf16 v[144:147], v[190:193], v[194:197], v[144:147]
	ds_read_b128 v[250:253], v198 offset:6912
	v_mfma_f32_16x16x32_bf16 v[108:111], v[178:181], v[242:245], v[108:111]
	v_mfma_f32_16x16x32_bf16 v[104:107], v[182:185], v[242:245], v[104:107]
	v_add3_u32 v238, s37, v174, v171
	s_waitcnt vmcnt(6)
	ds_write_b128 v238, v[116:119]
	v_mfma_f32_16x16x32_bf16 v[100:103], v[186:189], v[242:245], v[100:103]
	v_mfma_f32_16x16x32_bf16 v[96:99], v[190:193], v[242:245], v[96:99]
	v_lshl_add_u64 v[116:117], s[38:39], 0, v[164:165]
	s_nop 0
	global_load_dwordx4 v[116:119], v[116:117], off offset:256
	ds_read_b128 v[194:197], v198 offset:9216
	s_waitcnt lgkmcnt(4)
	v_mfma_f32_16x16x32_bf16 v[92:95], v[178:181], v[246:249], v[92:95]
	v_mfma_f32_16x16x32_bf16 v[88:91], v[182:185], v[246:249], v[88:91]
	v_mfma_f32_16x16x32_bf16 v[84:87], v[186:189], v[246:249], v[84:87]
	v_add3_u32 v239, s37, v175, v171
	s_waitcnt vmcnt(6)
	ds_write_b128 v239, v[120:123]
	v_mfma_f32_16x16x32_bf16 v[80:83], v[190:193], v[246:249], v[80:83]
	ds_read_b128 v[242:245], v198 offset:11520
	s_waitcnt lgkmcnt(4)
	v_mfma_f32_16x16x32_bf16 v[76:79], v[178:181], v[250:253], v[76:79]
	v_lshl_add_u64 v[120:121], s[38:39], 0, v[166:167]
	s_nop 0
	global_load_dwordx4 v[120:123], v[120:121], off offset:256
	v_mfma_f32_16x16x32_bf16 v[72:75], v[182:185], v[250:253], v[72:75]
	v_mfma_f32_16x16x32_bf16 v[68:71], v[186:189], v[250:253], v[68:71]
	v_mfma_f32_16x16x32_bf16 v[64:67], v[190:193], v[250:253], v[64:67]
	v_add3_u32 v255, s37, v176, v171
	s_waitcnt vmcnt(6)
	ds_write_b128 v255, v[124:127]
	ds_read_b128 v[246:249], v198 offset:13824
	s_waitcnt lgkmcnt(4)
	v_mfma_f32_16x16x32_bf16 v[60:63], v[178:181], v[194:197], v[60:63]
	v_mfma_f32_16x16x32_bf16 v[56:59], v[182:185], v[194:197], v[56:59]
	v_lshl_add_u64 v[124:125], s[38:39], 0, v[168:169]
	s_nop 0
	global_load_dwordx4 v[124:127], v[124:125], off offset:256
	v_mfma_f32_16x16x32_bf16 v[52:55], v[186:189], v[194:197], v[52:55]
	v_mfma_f32_16x16x32_bf16 v[48:51], v[190:193], v[194:197], v[48:51]
	ds_read_b128 v[250:253], v198 offset:16128
	s_waitcnt lgkmcnt(3)
	v_mfma_f32_16x16x32_bf16 v[44:47], v[178:181], v[242:245], v[44:47]
	ds_write_b128 v254, v[128:131] offset:36864
	v_mfma_f32_16x16x32_bf16 v[40:43], v[182:185], v[242:245], v[40:43]
	v_mfma_f32_16x16x32_bf16 v[36:39], v[186:189], v[242:245], v[36:39]
	s_add_u32 s38, s2, s99
	s_addc_u32 s39, s3, 0
	v_lshl_add_u64 v[128:129], s[38:39], 0, v[162:163]
	s_nop 0
	global_load_dwordx4 v[128:131], v[128:129], off offset:256
	v_mfma_f32_16x16x32_bf16 v[32:35], v[190:193], v[242:245], v[32:35]
	ds_read_b128 v[194:197], v198 offset:64
	s_waitcnt lgkmcnt(3)
	v_mfma_f32_16x16x32_bf16 v[28:31], v[178:181], v[246:249], v[28:31]
	v_mfma_f32_16x16x32_bf16 v[24:27], v[182:185], v[246:249], v[24:27]
	s_waitcnt vmcnt(7)
	ds_write_b128 v238, v[132:135] offset:36864
	v_mfma_f32_16x16x32_bf16 v[20:23], v[186:189], v[246:249], v[20:23]
	v_mfma_f32_16x16x32_bf16 v[16:19], v[190:193], v[246:249], v[16:19]
	v_lshl_add_u64 v[132:133], s[38:39], 0, v[164:165]
	s_nop 0
	global_load_dwordx4 v[132:135], v[132:133], off offset:256
	ds_read_b128 v[242:245], v198 offset:2368
	s_waitcnt lgkmcnt(4)
; DI f32x4 mfma16(bf16x8 a, bf16x8 b, f32x4 c) { return __builtin_amdgcn_mfma_f32_16x16x32_bf16(a, b, c, 0, 0, 0); }
; template <int MI, int NJ, bool SWAP, class AP, class BP>
; DI void gemm_main(f32x4 (&acc)[MI][NJ], const AP& ap, int a_kstep, const BP& bp, int b_kstep, int nk, bf16_t* smem) {
;     ...
;   auto gload = [&](int kt) {
;     const bf16_t* ab = ap.base + (size_t)kt * a_kstep; const bf16_t* bb = bp.base + (size_t)kt * b_kstep;
; #pragma unroll
;     for (int i = 0; i < CA; ++i) ra[i] = *(const u32x4*)(ab + pa[i]);
; #pragma unroll
;     for (int i = 0; i < CB; ++i) rb[i] = *(const u32x4*)(bb + pb[i]);
;   };
;   auto sstore = [&](int buf) {
;     bf16_t* As = smem + buf * L::STAGE; bf16_t* Bs = As + L::A_ELEMS;
; #pragma unroll
;     for (int i = 0; i < CA; ++i) { const int c = tid + NTHR * i; *(u32x4*)(As + (c >> 3) * LDT + (c & 7) * 8) = oka[i] ? ra[i] : (u32x4){0u, 0u, 0u, 0u}; }
; #pragma unroll
;     for (int i = 0; i < CB; ++i) { const int c = tid + NTHR * i; *(u32x4*)(Bs + (c >> 3) * LDT + (c & 7) * 8) = rb[i]; }
;   };
;   gload(0); sstore(0); gload(nk > 1 ? 1 : 0); __syncthreads();
; #pragma unroll 1
;   for (int kt = 0; kt < nk; ++kt) {
;     const int buf = kt & 1;
;     sstore(buf ^ 1);
;     gload(kt + 2 < nk ? kt + 2 : nk - 1);
;     __builtin_amdgcn_sched_barrier(0);
;     const bf16_t* As = smem + buf * L::STAGE + (wm * 16 * MI + l15) * LDT + quad * 8;
;     const bf16_t* Bs = smem + buf * L::STAGE + L::A_ELEMS + (wn * 16 * NJ + l15) * LDT + quad * 8;
; #pragma unroll
;     for (int ks = 0; ks < 2; ++ks) {
;       if (MI * NJ >= 32 && ks == 1) asm volatile("" ::: "memory");
;       bf16x8 b[NJ];
; #pragma unroll
;       for (int j = 0; j < NJ; ++j) b[j] = *(const bf16x8*)(Bs + j * 16 * LDT + ks * 32);
; #pragma unroll
;       for (int i = 0; i < MI; ++i) {
;         const bf16x8 a = *(const bf16x8*)(As + i * 16 * LDT + ks * 32);
; #pragma unroll
;         for (int j = 0; j < NJ; ++j) acc[i][j] = SWAP ? mfma16(b[j], a, acc[i][j]) : mfma16(a, b[j], acc[i][j]);
;       }
;     }
;     __syncthreads();
	v_mfma_f32_16x16x32_bf16 v[12:15], v[178:181], v[250:253], v[12:15]
	ds_read_b128 v[178:181], v199 offset:36928
	v_mfma_f32_16x16x32_bf16 v[8:11], v[182:185], v[250:253], v[8:11]
	ds_read_b128 v[182:185], v199 offset:39232
	v_mfma_f32_16x16x32_bf16 v[4:7], v[186:189], v[250:253], v[4:7]
	ds_read_b128 v[186:189], v199 offset:41536
	s_waitcnt vmcnt(7)
	ds_write_b128 v239, v[136:139] offset:36864
	v_mfma_f32_16x16x32_bf16 v[0:3], v[190:193], v[250:253], v[0:3]
	ds_read_b128 v[190:193], v199 offset:43840
	ds_read_b128 v[246:249], v198 offset:4672
	s_waitcnt lgkmcnt(5)
	v_mfma_f32_16x16x32_bf16 v[156:159], v[178:181], v[194:197], v[156:159]
	v_lshl_add_u64 v[136:137], s[38:39], 0, v[166:167]
	s_nop 0
	global_load_dwordx4 v[136:139], v[136:137], off offset:256
	s_waitcnt lgkmcnt(4)
	v_mfma_f32_16x16x32_bf16 v[152:155], v[182:185], v[194:197], v[152:155]
	s_waitcnt lgkmcnt(3)
	v_mfma_f32_16x16x32_bf16 v[148:151], v[186:189], v[194:197], v[148:151]
	s_waitcnt lgkmcnt(1)
	v_mfma_f32_16x16x32_bf16 v[144:147], v[190:193], v[194:197], v[144:147]
	s_waitcnt vmcnt(7)
	ds_write_b128 v255, v[140:143] offset:36864
	ds_read_b128 v[250:253], v198 offset:6976
	v_mfma_f32_16x16x32_bf16 v[108:111], v[178:181], v[242:245], v[108:111]
	v_mfma_f32_16x16x32_bf16 v[104:107], v[182:185], v[242:245], v[104:107]
	v_lshl_add_u64 v[140:141], s[38:39], 0, v[168:169]
	s_nop 0
	global_load_dwordx4 v[140:143], v[140:141], off offset:256
	v_mfma_f32_16x16x32_bf16 v[100:103], v[186:189], v[242:245], v[100:103]
	v_mfma_f32_16x16x32_bf16 v[96:99], v[190:193], v[242:245], v[96:99]
	ds_read_b128 v[194:197], v198 offset:9280
	s_waitcnt lgkmcnt(3)
	v_mfma_f32_16x16x32_bf16 v[92:95], v[178:181], v[246:249], v[92:95]
	v_mfma_f32_16x16x32_bf16 v[88:91], v[182:185], v[246:249], v[88:91]
	v_mfma_f32_16x16x32_bf16 v[84:87], v[186:189], v[246:249], v[84:87]
	v_mfma_f32_16x16x32_bf16 v[80:83], v[190:193], v[246:249], v[80:83]
	ds_read_b128 v[242:245], v198 offset:11584
	s_waitcnt lgkmcnt(2)
	v_mfma_f32_16x16x32_bf16 v[76:79], v[178:181], v[250:253], v[76:79]
	v_mfma_f32_16x16x32_bf16 v[72:75], v[182:185], v[250:253], v[72:75]
	v_mfma_f32_16x16x32_bf16 v[68:71], v[186:189], v[250:253], v[68:71]
	v_mfma_f32_16x16x32_bf16 v[64:67], v[190:193], v[250:253], v[64:67]
	ds_read_b128 v[246:249], v198 offset:13888
	s_waitcnt lgkmcnt(2)
	v_mfma_f32_16x16x32_bf16 v[60:63], v[178:181], v[194:197], v[60:63]
	v_mfma_f32_16x16x32_bf16 v[56:59], v[182:185], v[194:197], v[56:59]
	v_mfma_f32_16x16x32_bf16 v[52:55], v[186:189], v[194:197], v[52:55]
	v_mfma_f32_16x16x32_bf16 v[48:51], v[190:193], v[194:197], v[48:51]
	ds_read_b128 v[250:253], v198 offset:16192
	s_waitcnt lgkmcnt(2)
	v_mfma_f32_16x16x32_bf16 v[44:47], v[178:181], v[242:245], v[44:47]
	v_mfma_f32_16x16x32_bf16 v[40:43], v[182:185], v[242:245], v[40:43]
	v_mfma_f32_16x16x32_bf16 v[36:39], v[186:189], v[242:245], v[36:39]
	v_mfma_f32_16x16x32_bf16 v[32:35], v[190:193], v[242:245], v[32:35]
	s_add_i32 s8, s8, 1
	s_and_b32 s98, s8, 1
	s_mul_i32 s98, s98, 0x12000
	v_add3_u32 v198, s98, v172, v177
	v_add3_u32 v199, s98, v160, v177
	s_cmp_lg_u32 s8, 6
	s_waitcnt lgkmcnt(0)
	s_barrier
	s_cbranch_scc0 .Lgm10_exit
	ds_read_b128 v[194:197], v198
	ds_read_b128 v[242:245], v198 offset:2304
	v_mfma_f32_16x16x32_bf16 v[28:31], v[178:181], v[246:249], v[28:31]
	v_mfma_f32_16x16x32_bf16 v[12:15], v[178:181], v[250:253], v[12:15]
	ds_read_b128 v[178:181], v199 offset:36864
	v_mfma_f32_16x16x32_bf16 v[24:27], v[182:185], v[246:249], v[24:27]
	v_mfma_f32_16x16x32_bf16 v[8:11], v[182:185], v[250:253], v[8:11]
	ds_read_b128 v[182:185], v199 offset:39168
	v_mfma_f32_16x16x32_bf16 v[20:23], v[186:189], v[246:249], v[20:23]
	v_mfma_f32_16x16x32_bf16 v[4:7], v[186:189], v[250:253], v[4:7]
	ds_read_b128 v[186:189], v199 offset:41472
	v_mfma_f32_16x16x32_bf16 v[16:19], v[190:193], v[246:249], v[16:19]
	v_mfma_f32_16x16x32_bf16 v[0:3], v[190:193], v[250:253], v[0:3]
	ds_read_b128 v[190:193], v199 offset:43776
	s_branch .Lgm10_main

; DI f32x4 mfma16(bf16x8 a, bf16x8 b, f32x4 c) { return __builtin_amdgcn_mfma_f32_16x16x32_bf16(a, b, c, 0, 0, 0); }
; template <int MI, int NJ, bool SWAP, class AP, class BP>
; DI void gemm_main(f32x4 (&acc)[MI][NJ], const AP& ap, int a_kstep, const BP& bp, int b_kstep, int nk, bf16_t* smem) {
;     ...
;   auto gload = [&](int kt) {
;     const bf16_t* ab = ap.base + (size_t)kt * a_kstep; const bf16_t* bb = bp.base + (size_t)kt * b_kstep;
; #pragma unroll
;     for (int i = 0; i < CA; ++i) ra[i] = *(const u32x4*)(ab + pa[i]);
; #pragma unroll
;     for (int i = 0; i < CB; ++i) rb[i] = *(const u32x4*)(bb + pb[i]);
;   };
;   auto sstore = [&](int buf) {
;     bf16_t* As = smem + buf * L::STAGE; bf16_t* Bs = As + L::A_ELEMS;
; #pragma unroll
;     for (int i = 0; i < CA; ++i) { const int c = tid + NTHR * i; *(u32x4*)(As + (c >> 3) * LDT + (c & 7) * 8) = oka[i] ? ra[i] : (u32x4){0u, 0u, 0u, 0u}; }
; #pragma unroll
;     for (int i = 0; i < CB; ++i) { const int c = tid + NTHR * i; *(u32x4*)(Bs + (c >> 3) * LDT + (c & 7) * 8) = rb[i]; }
;   };
;   gload(0); sstore(0); gload(nk > 1 ? 1 : 0); __syncthreads();
; #pragma unroll 1
;   for (int kt = 0; kt < nk; ++kt) {
;     const int buf = kt & 1;
;     sstore(buf ^ 1);
;     gload(kt + 2 < nk ? kt + 2 : nk - 1);
;     __builtin_amdgcn_sched_barrier(0);
;     const bf16_t* As = smem + buf * L::STAGE + (wm * 16 * MI + l15) * LDT + quad * 8;
;     const bf16_t* Bs = smem + buf * L::STAGE + L::A_ELEMS + (wn * 16 * NJ + l15) * LDT + quad * 8;
; #pragma unroll
;     for (int ks = 0; ks < 2; ++ks) {
;       if (MI * NJ >= 32 && ks == 1) asm volatile("" ::: "memory");
;       bf16x8 b[NJ];
; #pragma unroll
;       for (int j = 0; j < NJ; ++j) b[j] = *(const bf16x8*)(Bs + j * 16 * LDT + ks * 32);
; #pragma unroll
;       for (int i = 0; i < MI; ++i) {
;         const bf16x8 a = *(const bf16x8*)(As + i * 16 * LDT + ks * 32);
; #pragma unroll
;         for (int j = 0; j < NJ; ++j) acc[i][j] = SWAP ? mfma16(b[j], a, acc[i][j]) : mfma16(a, b[j], acc[i][j]);
;       }
;     }
;     __syncthreads();
.Lgm13_main:
	ds_read_b128 v[242:245], v177 offset:4608
	s_waitcnt lgkmcnt(4)
	v_mfma_f32_16x16x32_bf16 v[156:159], v[178:181], v[194:197], v[156:159]
	s_and_b32 s15, s1, 1
	s_min_u32 s16, s1, 13
	s_xor_b32 s17, s15, 1
	s_mul_i32 s17, s17, 0x12000
	v_add3_u32 v250, s17, v172, v170
	s_waitcnt vmcnt(7)
	ds_write_b128 v250, v[112:115]
	s_waitcnt lgkmcnt(4)
	v_mfma_f32_16x16x32_bf16 v[152:155], v[182:185], v[194:197], v[152:155]
	s_waitcnt lgkmcnt(3)
	v_mfma_f32_16x16x32_bf16 v[148:151], v[186:189], v[194:197], v[148:151]
	s_lshl_b32 s26, s16, 7
	s_add_u32 s16, s2, s26
	v_add3_u32 v251, s17, v174, v170
	v_add3_u32 v252, s17, v175, v170
	v_add3_u32 v253, s17, v176, v170
	s_addc_u32 s17, s3, 0
	v_lshl_add_u64 v[112:113], s[16:17], 0, v[162:163]
	s_nop 0
	global_load_dwordx4 v[112:115], v[112:113], off offset:256
	s_waitcnt lgkmcnt(2)
	v_mfma_f32_16x16x32_bf16 v[144:147], v[190:193], v[194:197], v[144:147]
	ds_read_b128 v[246:249], v177 offset:6912
	v_mfma_f32_16x16x32_bf16 v[108:111], v[178:181], v[198:201], v[108:111]
	v_mfma_f32_16x16x32_bf16 v[104:107], v[182:185], v[198:201], v[104:107]
	s_waitcnt vmcnt(7)
	ds_write_b128 v251, v[116:119]
	v_mfma_f32_16x16x32_bf16 v[100:103], v[186:189], v[198:201], v[100:103]
	v_mfma_f32_16x16x32_bf16 v[96:99], v[190:193], v[198:201], v[96:99]
	v_lshl_add_u64 v[116:117], s[16:17], 0, v[164:165]
	s_nop 0
	global_load_dwordx4 v[116:119], v[116:117], off offset:256
	ds_read_b128 v[194:197], v177 offset:9216
	s_waitcnt lgkmcnt(4)
	v_mfma_f32_16x16x32_bf16 v[92:95], v[178:181], v[242:245], v[92:95]
	v_mfma_f32_16x16x32_bf16 v[88:91], v[182:185], v[242:245], v[88:91]
	v_mfma_f32_16x16x32_bf16 v[84:87], v[186:189], v[242:245], v[84:87]
	s_waitcnt vmcnt(7)
	ds_write_b128 v252, v[120:123]
	v_mfma_f32_16x16x32_bf16 v[80:83], v[190:193], v[242:245], v[80:83]
	ds_read_b128 v[198:201], v177 offset:11520
	s_waitcnt lgkmcnt(4)
	v_mfma_f32_16x16x32_bf16 v[76:79], v[178:181], v[246:249], v[76:79]
	v_lshl_add_u64 v[120:121], s[16:17], 0, v[166:167]
	s_nop 0
	global_load_dwordx4 v[120:123], v[120:121], off offset:256
	v_mfma_f32_16x16x32_bf16 v[72:75], v[182:185], v[246:249], v[72:75]
	v_mfma_f32_16x16x32_bf16 v[68:71], v[186:189], v[246:249], v[68:71]
	v_mfma_f32_16x16x32_bf16 v[64:67], v[190:193], v[246:249], v[64:67]
	s_waitcnt vmcnt(7)
	ds_write_b128 v253, v[124:127]
	ds_read_b128 v[242:245], v177 offset:13824
	s_waitcnt lgkmcnt(4)
	v_mfma_f32_16x16x32_bf16 v[60:63], v[178:181], v[194:197], v[60:63]
	v_mfma_f32_16x16x32_bf16 v[56:59], v[182:185], v[194:197], v[56:59]
	v_lshl_add_u64 v[124:125], s[16:17], 0, v[168:169]
	s_nop 0
	global_load_dwordx4 v[124:127], v[124:125], off offset:256
	v_mfma_f32_16x16x32_bf16 v[52:55], v[186:189], v[194:197], v[52:55]
	v_mfma_f32_16x16x32_bf16 v[48:51], v[190:193], v[194:197], v[48:51]
	ds_read_b128 v[246:249], v177 offset:16128
	s_waitcnt lgkmcnt(3)
	v_mfma_f32_16x16x32_bf16 v[44:47], v[178:181], v[198:201], v[44:47]
	s_waitcnt vmcnt(7)
	ds_write_b128 v250, v[128:131] offset:36864
	v_mfma_f32_16x16x32_bf16 v[40:43], v[182:185], v[198:201], v[40:43]
	v_mfma_f32_16x16x32_bf16 v[36:39], v[186:189], v[198:201], v[36:39]
	s_add_u32 s16, s12, s26
	s_addc_u32 s17, s13, 0
	v_lshl_add_u64 v[128:129], s[16:17], 0, v[162:163]
	s_nop 0
	global_load_dwordx4 v[128:131], v[128:129], off offset:256
	v_mfma_f32_16x16x32_bf16 v[32:35], v[190:193], v[198:201], v[32:35]
	ds_read_b128 v[194:197], v177 offset:64
	s_waitcnt lgkmcnt(3)
	v_mfma_f32_16x16x32_bf16 v[28:31], v[178:181], v[242:245], v[28:31]
	v_mfma_f32_16x16x32_bf16 v[24:27], v[182:185], v[242:245], v[24:27]
	s_waitcnt vmcnt(7)
	ds_write_b128 v251, v[132:135] offset:36864
	v_mfma_f32_16x16x32_bf16 v[20:23], v[186:189], v[242:245], v[20:23]
	v_mfma_f32_16x16x32_bf16 v[16:19], v[190:193], v[242:245], v[16:19]
	v_lshl_add_u64 v[132:133], s[16:17], 0, v[164:165]
	s_nop 0
	global_load_dwordx4 v[132:135], v[132:133], off offset:256
	ds_read_b128 v[198:201], v177 offset:2368
	s_waitcnt lgkmcnt(4)
; DI f32x4 mfma16(bf16x8 a, bf16x8 b, f32x4 c) { return __builtin_amdgcn_mfma_f32_16x16x32_bf16(a, b, c, 0, 0, 0); }
; template <int MI, int NJ, bool SWAP, class AP, class BP>
; DI void gemm_main(f32x4 (&acc)[MI][NJ], const AP& ap, int a_kstep, const BP& bp, int b_kstep, int nk, bf16_t* smem) {
;     ...
;   auto gload = [&](int kt) {
;     const bf16_t* ab = ap.base + (size_t)kt * a_kstep; const bf16_t* bb = bp.base + (size_t)kt * b_kstep;
; #pragma unroll
;     for (int i = 0; i < CA; ++i) ra[i] = *(const u32x4*)(ab + pa[i]);
; #pragma unroll
;     for (int i = 0; i < CB; ++i) rb[i] = *(const u32x4*)(bb + pb[i]);
;   };
;   auto sstore = [&](int buf) {
;     bf16_t* As = smem + buf * L::STAGE; bf16_t* Bs = As + L::A_ELEMS;
; #pragma unroll
;     for (int i = 0; i < CA; ++i) { const int c = tid + NTHR * i; *(u32x4*)(As + (c >> 3) * LDT + (c & 7) * 8) = oka[i] ? ra[i] : (u32x4){0u, 0u, 0u, 0u}; }
; #pragma unroll
;     for (int i = 0; i < CB; ++i) { const int c = tid + NTHR * i; *(u32x4*)(Bs + (c >> 3) * LDT + (c & 7) * 8) = rb[i]; }
;   };
;   gload(0); sstore(0); gload(nk > 1 ? 1 : 0); __syncthreads();
; #pragma unroll 1
;   for (int kt = 0; kt < nk; ++kt) {
;     const int buf = kt & 1;
;     sstore(buf ^ 1);
;     gload(kt + 2 < nk ? kt + 2 : nk - 1);
;     __builtin_amdgcn_sched_barrier(0);
;     const bf16_t* As = smem + buf * L::STAGE + (wm * 16 * MI + l15) * LDT + quad * 8;
;     const bf16_t* Bs = smem + buf * L::STAGE + L::A_ELEMS + (wn * 16 * NJ + l15) * LDT + quad * 8;
; #pragma unroll
;     for (int ks = 0; ks < 2; ++ks) {
;       if (MI * NJ >= 32 && ks == 1) asm volatile("" ::: "memory");
;       bf16x8 b[NJ];
; #pragma unroll
;       for (int j = 0; j < NJ; ++j) b[j] = *(const bf16x8*)(Bs + j * 16 * LDT + ks * 32);
; #pragma unroll
;       for (int i = 0; i < MI; ++i) {
;         const bf16x8 a = *(const bf16x8*)(As + i * 16 * LDT + ks * 32);
; #pragma unroll
;         for (int j = 0; j < NJ; ++j) acc[i][j] = SWAP ? mfma16(b[j], a, acc[i][j]) : mfma16(a, b[j], acc[i][j]);
;       }
;     }
;     __syncthreads();
	v_mfma_f32_16x16x32_bf16 v[8:11], v[178:181], v[246:249], v[8:11]
	ds_read_b128 v[178:181], v202 offset:36928
	v_mfma_f32_16x16x32_bf16 v[4:7], v[182:185], v[246:249], v[4:7]
	ds_read_b128 v[182:185], v202 offset:39232
	v_mfma_f32_16x16x32_bf16 v[0:3], v[186:189], v[246:249], v[0:3]
	ds_read_b128 v[186:189], v202 offset:41536
	s_waitcnt vmcnt(7)
	ds_write_b128 v252, v[136:139] offset:36864
	v_mfma_f32_16x16x32_bf16 v[12:15], v[190:193], v[246:249], v[12:15]
	ds_read_b128 v[190:193], v202 offset:43840
	ds_read_b128 v[242:245], v177 offset:4672
	s_waitcnt lgkmcnt(5)
	v_mfma_f32_16x16x32_bf16 v[156:159], v[178:181], v[194:197], v[156:159]
	v_lshl_add_u64 v[136:137], s[16:17], 0, v[166:167]
	s_nop 0
	global_load_dwordx4 v[136:139], v[136:137], off offset:256
	s_waitcnt lgkmcnt(4)
	v_mfma_f32_16x16x32_bf16 v[152:155], v[182:185], v[194:197], v[152:155]
	s_waitcnt lgkmcnt(3)
	v_mfma_f32_16x16x32_bf16 v[148:151], v[186:189], v[194:197], v[148:151]
	s_waitcnt lgkmcnt(1)
	v_mfma_f32_16x16x32_bf16 v[144:147], v[190:193], v[194:197], v[144:147]
	s_waitcnt vmcnt(7)
	ds_write_b128 v253, v[140:143] offset:36864
	ds_read_b128 v[246:249], v177 offset:6976
	v_mfma_f32_16x16x32_bf16 v[108:111], v[178:181], v[198:201], v[108:111]
	v_mfma_f32_16x16x32_bf16 v[104:107], v[182:185], v[198:201], v[104:107]
	v_lshl_add_u64 v[140:141], s[16:17], 0, v[168:169]
	s_nop 0
	global_load_dwordx4 v[140:143], v[140:141], off offset:256
	v_mfma_f32_16x16x32_bf16 v[100:103], v[186:189], v[198:201], v[100:103]
	v_mfma_f32_16x16x32_bf16 v[96:99], v[190:193], v[198:201], v[96:99]
	ds_read_b128 v[194:197], v177 offset:9280
	s_waitcnt lgkmcnt(3)
	v_mfma_f32_16x16x32_bf16 v[92:95], v[178:181], v[242:245], v[92:95]
	v_mfma_f32_16x16x32_bf16 v[88:91], v[182:185], v[242:245], v[88:91]
	v_mfma_f32_16x16x32_bf16 v[84:87], v[186:189], v[242:245], v[84:87]
	v_mfma_f32_16x16x32_bf16 v[80:83], v[190:193], v[242:245], v[80:83]
	ds_read_b128 v[198:201], v177 offset:11584
	s_waitcnt lgkmcnt(2)
	v_mfma_f32_16x16x32_bf16 v[76:79], v[178:181], v[246:249], v[76:79]
	v_mfma_f32_16x16x32_bf16 v[72:75], v[182:185], v[246:249], v[72:75]
	v_mfma_f32_16x16x32_bf16 v[68:71], v[186:189], v[246:249], v[68:71]
	v_mfma_f32_16x16x32_bf16 v[64:67], v[190:193], v[246:249], v[64:67]
	ds_read_b128 v[242:245], v177 offset:13888
	s_waitcnt lgkmcnt(2)
	v_mfma_f32_16x16x32_bf16 v[60:63], v[178:181], v[194:197], v[60:63]
	v_mfma_f32_16x16x32_bf16 v[56:59], v[182:185], v[194:197], v[56:59]
	v_mfma_f32_16x16x32_bf16 v[52:55], v[186:189], v[194:197], v[52:55]
	v_mfma_f32_16x16x32_bf16 v[48:51], v[190:193], v[194:197], v[48:51]
	ds_read_b128 v[246:249], v177 offset:16192
	s_waitcnt lgkmcnt(2)
	v_mfma_f32_16x16x32_bf16 v[44:47], v[178:181], v[198:201], v[44:47]
	v_mfma_f32_16x16x32_bf16 v[40:43], v[182:185], v[198:201], v[40:43]
	v_mfma_f32_16x16x32_bf16 v[36:39], v[186:189], v[198:201], v[36:39]
	v_mfma_f32_16x16x32_bf16 v[32:35], v[190:193], v[198:201], v[32:35]
	s_add_i32 s1, s1, 1
	s_and_b32 s98, s1, 1
	s_mul_i32 s98, s98, 0x12000
	v_add3_u32 v202, s98, v160, v173
	v_add3_u32 v177, s98, v171, v173
	s_cmp_lg_u32 s1, 16
	s_waitcnt lgkmcnt(0)
	s_barrier
	s_cbranch_scc0 .Lgm13_exit
	ds_read_b128 v[194:197], v177
	ds_read_b128 v[198:201], v177 offset:2304
	v_mfma_f32_16x16x32_bf16 v[28:31], v[178:181], v[242:245], v[28:31]
	v_mfma_f32_16x16x32_bf16 v[8:11], v[178:181], v[246:249], v[8:11]
	ds_read_b128 v[178:181], v202 offset:36864
	v_mfma_f32_16x16x32_bf16 v[24:27], v[182:185], v[242:245], v[24:27]
	v_mfma_f32_16x16x32_bf16 v[4:7], v[182:185], v[246:249], v[4:7]
	ds_read_b128 v[182:185], v202 offset:39168
	v_mfma_f32_16x16x32_bf16 v[20:23], v[186:189], v[242:245], v[20:23]
	v_mfma_f32_16x16x32_bf16 v[0:3], v[186:189], v[246:249], v[0:3]
	ds_read_b128 v[186:189], v202 offset:41472
	v_mfma_f32_16x16x32_bf16 v[16:19], v[190:193], v[242:245], v[16:19]
	v_mfma_f32_16x16x32_bf16 v[12:15], v[190:193], v[246:249], v[12:15]
	ds_read_b128 v[190:193], v202 offset:43776
	s_branch .Lgm13_main

; DI f32x4 mfma16(bf16x8 a, bf16x8 b, f32x4 c) { return __builtin_amdgcn_mfma_f32_16x16x32_bf16(a, b, c, 0, 0, 0); }
; template <int MI, int NJ, bool SWAP, class AP, class BP>
; DI void gemm_main(f32x4 (&acc)[MI][NJ], const AP& ap, int a_kstep, const BP& bp, int b_kstep, int nk, bf16_t* smem) {
;     ...
;   auto gload = [&](int kt) {
;     const bf16_t* ab = ap.base + (size_t)kt * a_kstep; const bf16_t* bb = bp.base + (size_t)kt * b_kstep;
; #pragma unroll
;     for (int i = 0; i < CA; ++i) ra[i] = *(const u32x4*)(ab + pa[i]);
; #pragma unroll
;     for (int i = 0; i < CB; ++i) rb[i] = *(const u32x4*)(bb + pb[i]);
;   };
;   auto sstore = [&](int buf) {
;     bf16_t* As = smem + buf * L::STAGE; bf16_t* Bs = As + L::A_ELEMS;
; #pragma unroll
;     for (int i = 0; i < CA; ++i) { const int c = tid + NTHR * i; *(u32x4*)(As + (c >> 3) * LDT + (c & 7) * 8) = oka[i] ? ra[i] : (u32x4){0u, 0u, 0u, 0u}; }
; #pragma unroll
;     for (int i = 0; i < CB; ++i) { const int c = tid + NTHR * i; *(u32x4*)(Bs + (c >> 3) * LDT + (c & 7) * 8) = rb[i]; }
;   };
;   gload(0); sstore(0); gload(nk > 1 ? 1 : 0); __syncthreads();
; #pragma unroll 1
;   for (int kt = 0; kt < nk; ++kt) {
;     const int buf = kt & 1;
;     sstore(buf ^ 1);
;     gload(kt + 2 < nk ? kt + 2 : nk - 1);
;     __builtin_amdgcn_sched_barrier(0);
;     const bf16_t* As = smem + buf * L::STAGE + (wm * 16 * MI + l15) * LDT + quad * 8;
;     const bf16_t* Bs = smem + buf * L::STAGE + L::A_ELEMS + (wn * 16 * NJ + l15) * LDT + quad * 8;
; #pragma unroll
;     for (int ks = 0; ks < 2; ++ks) {
;       if (MI * NJ >= 32 && ks == 1) asm volatile("" ::: "memory");
;       bf16x8 b[NJ];
; #pragma unroll
;       for (int j = 0; j < NJ; ++j) b[j] = *(const bf16x8*)(Bs + j * 16 * LDT + ks * 32);
; #pragma unroll
;       for (int i = 0; i < MI; ++i) {
;         const bf16x8 a = *(const bf16x8*)(As + i * 16 * LDT + ks * 32);
; #pragma unroll
;         for (int j = 0; j < NJ; ++j) acc[i][j] = SWAP ? mfma16(b[j], a, acc[i][j]) : mfma16(a, b[j], acc[i][j]);
;       }
;     }
;     __syncthreads();
.Lgm14_main:
	ds_read_b128 v[242:245], v181 offset:4608
	s_waitcnt lgkmcnt(4)
	v_mfma_f32_16x16x32_bf16 v[156:159], v[182:185], v[198:201], v[156:159]
	s_waitcnt vmcnt(7)
	v_cndmask_b32_e32 v143, 0, v143, vcc
	v_cndmask_b32_e32 v142, 0, v142, vcc
	v_cndmask_b32_e32 v141, 0, v141, vcc
	v_cndmask_b32_e32 v140, 0, v140, vcc
	s_and_b32 s46, s43, 1
	s_min_u32 s44, s43, 13
	s_xor_b32 s45, s46, 1
	s_mul_i32 s45, s45, 0x12000
	v_add3_u32 v250, s45, v172, v169
	ds_write_b128 v250, v[140:143]
	s_waitcnt lgkmcnt(4)
	v_mfma_f32_16x16x32_bf16 v[152:155], v[186:189], v[198:201], v[152:155]
	s_waitcnt lgkmcnt(3)
	v_mfma_f32_16x16x32_bf16 v[148:151], v[190:193], v[198:201], v[148:151]
	s_lshl_b32 s47, s44, 7
	s_add_u32 s44, s18, s47
	v_add3_u32 v251, s45, v173, v169
	v_add3_u32 v252, s45, v174, v169
	v_add3_u32 v253, s45, v175, v169
	s_addc_u32 s45, s19, 0
	s_nop 0
	global_load_dwordx4 v[140:143], v176, s[44:45] offset:256
	s_waitcnt lgkmcnt(2)
	v_mfma_f32_16x16x32_bf16 v[144:147], v[194:197], v[198:201], v[144:147]
	ds_read_b128 v[246:249], v181 offset:6912
	v_mfma_f32_16x16x32_bf16 v[108:111], v[182:185], v[202:205], v[108:111]
	v_mfma_f32_16x16x32_bf16 v[104:107], v[186:189], v[202:205], v[104:107]
	s_waitcnt vmcnt(7)
	v_cndmask_b32_e64 v131, 0, v131, s[0:1]
	v_cndmask_b32_e64 v130, 0, v130, s[0:1]
	v_cndmask_b32_e64 v129, 0, v129, s[0:1]
	v_cndmask_b32_e64 v128, 0, v128, s[0:1]
	ds_write_b128 v251, v[128:131]
	v_mfma_f32_16x16x32_bf16 v[100:103], v[190:193], v[202:205], v[100:103]
	v_mfma_f32_16x16x32_bf16 v[96:99], v[194:197], v[202:205], v[96:99]
	s_nop 0
	global_load_dwordx4 v[128:131], v177, s[44:45] offset:256
	ds_read_b128 v[198:201], v181 offset:9216
	s_waitcnt lgkmcnt(4)
	v_mfma_f32_16x16x32_bf16 v[92:95], v[182:185], v[242:245], v[92:95]
	v_mfma_f32_16x16x32_bf16 v[88:91], v[186:189], v[242:245], v[88:91]
	v_mfma_f32_16x16x32_bf16 v[84:87], v[190:193], v[242:245], v[84:87]
	s_waitcnt vmcnt(7)
	v_cndmask_b32_e64 v115, 0, v115, s[2:3]
	v_cndmask_b32_e64 v114, 0, v114, s[2:3]
	v_cndmask_b32_e64 v113, 0, v113, s[2:3]
	v_cndmask_b32_e64 v112, 0, v112, s[2:3]
	ds_write_b128 v252, v[112:115]
	v_mfma_f32_16x16x32_bf16 v[80:83], v[194:197], v[242:245], v[80:83]
	ds_read_b128 v[202:205], v181 offset:11520
	s_waitcnt lgkmcnt(4)
	v_mfma_f32_16x16x32_bf16 v[76:79], v[182:185], v[246:249], v[76:79]
	s_nop 0
	global_load_dwordx4 v[112:115], v178, s[44:45] offset:256
	v_mfma_f32_16x16x32_bf16 v[72:75], v[186:189], v[246:249], v[72:75]
	v_mfma_f32_16x16x32_bf16 v[68:71], v[190:193], v[246:249], v[68:71]
	v_mfma_f32_16x16x32_bf16 v[64:67], v[194:197], v[246:249], v[64:67]
	s_waitcnt vmcnt(7)
	v_cndmask_b32_e64 v135, 0, v135, s[4:5]
	v_cndmask_b32_e64 v134, 0, v134, s[4:5]
	v_cndmask_b32_e64 v133, 0, v133, s[4:5]
	v_cndmask_b32_e64 v132, 0, v132, s[4:5]
	ds_write_b128 v253, v[132:135]
	ds_read_b128 v[242:245], v181 offset:13824
	s_waitcnt lgkmcnt(4)
	v_mfma_f32_16x16x32_bf16 v[60:63], v[182:185], v[198:201], v[60:63]
	v_mfma_f32_16x16x32_bf16 v[56:59], v[186:189], v[198:201], v[56:59]
	s_nop 0
	global_load_dwordx4 v[132:135], v179, s[44:45] offset:256
	v_mfma_f32_16x16x32_bf16 v[52:55], v[190:193], v[198:201], v[52:55]
	v_mfma_f32_16x16x32_bf16 v[48:51], v[194:197], v[198:201], v[48:51]
	ds_read_b128 v[246:249], v181 offset:16128
	s_waitcnt lgkmcnt(3)
	v_mfma_f32_16x16x32_bf16 v[44:47], v[182:185], v[202:205], v[44:47]
	s_waitcnt vmcnt(7)
	ds_write_b128 v250, v[116:119] offset:36864
	v_mfma_f32_16x16x32_bf16 v[40:43], v[186:189], v[202:205], v[40:43]
	v_mfma_f32_16x16x32_bf16 v[36:39], v[190:193], v[202:205], v[36:39]
	s_add_u32 s44, s20, s47
	s_addc_u32 s45, s21, 0
	v_lshl_add_u64 v[116:117], v[160:161], 1, s[44:45]
	s_nop 0
	global_load_dwordx4 v[116:119], v[116:117], off offset:256
	v_mfma_f32_16x16x32_bf16 v[32:35], v[194:197], v[202:205], v[32:35]
	ds_read_b128 v[198:201], v181 offset:64
	s_waitcnt lgkmcnt(3)
	v_mfma_f32_16x16x32_bf16 v[28:31], v[182:185], v[242:245], v[28:31]
	v_mfma_f32_16x16x32_bf16 v[24:27], v[186:189], v[242:245], v[24:27]
	s_waitcnt vmcnt(7)
; DI f32x4 mfma16(bf16x8 a, bf16x8 b, f32x4 c) { return __builtin_amdgcn_mfma_f32_16x16x32_bf16(a, b, c, 0, 0, 0); }
; template <int MI, int NJ, bool SWAP, class AP, class BP>
; DI void gemm_main(f32x4 (&acc)[MI][NJ], const AP& ap, int a_kstep, const BP& bp, int b_kstep, int nk, bf16_t* smem) {
;     ...
;   auto gload = [&](int kt) {
;     const bf16_t* ab = ap.base + (size_t)kt * a_kstep; const bf16_t* bb = bp.base + (size_t)kt * b_kstep;
; #pragma unroll
;     for (int i = 0; i < CA; ++i) ra[i] = *(const u32x4*)(ab + pa[i]);
; #pragma unroll
;     for (int i = 0; i < CB; ++i) rb[i] = *(const u32x4*)(bb + pb[i]);
;   };
;   auto sstore = [&](int buf) {
;     bf16_t* As = smem + buf * L::STAGE; bf16_t* Bs = As + L::A_ELEMS;
; #pragma unroll
;     for (int i = 0; i < CA; ++i) { const int c = tid + NTHR * i; *(u32x4*)(As + (c >> 3) * LDT + (c & 7) * 8) = oka[i] ? ra[i] : (u32x4){0u, 0u, 0u, 0u}; }
; #pragma unroll
;     for (int i = 0; i < CB; ++i) { const int c = tid + NTHR * i; *(u32x4*)(Bs + (c >> 3) * LDT + (c & 7) * 8) = rb[i]; }
;     ...
;   for (int kt = 0; kt < nk; ++kt) {
;     const int buf = kt & 1;
;     sstore(buf ^ 1);
;     gload(kt + 2 < nk ? kt + 2 : nk - 1);
;     __builtin_amdgcn_sched_barrier(0);
;     const bf16_t* As = smem + buf * L::STAGE + (wm * 16 * MI + l15) * LDT + quad * 8;
;     const bf16_t* Bs = smem + buf * L::STAGE + L::A_ELEMS + (wn * 16 * NJ + l15) * LDT + quad * 8;
; #pragma unroll
;     for (int ks = 0; ks < 2; ++ks) {
;       if (MI * NJ >= 32 && ks == 1) asm volatile("" ::: "memory");
;       bf16x8 b[NJ];
; #pragma unroll
;       for (int j = 0; j < NJ; ++j) b[j] = *(const bf16x8*)(Bs + j * 16 * LDT + ks * 32);
; #pragma unroll
;       for (int i = 0; i < MI; ++i) {
;         const bf16x8 a = *(const bf16x8*)(As + i * 16 * LDT + ks * 32);
; #pragma unroll
;         for (int j = 0; j < NJ; ++j) acc[i][j] = SWAP ? mfma16(b[j], a, acc[i][j]) : mfma16(a, b[j], acc[i][j]);
;       }
;     }
	ds_write_b128 v251, v[120:123] offset:36864
	v_mfma_f32_16x16x32_bf16 v[20:23], v[190:193], v[242:245], v[20:23]
	v_mfma_f32_16x16x32_bf16 v[12:15], v[194:197], v[242:245], v[12:15]
	v_lshl_add_u64 v[120:121], v[162:163], 1, s[44:45]
	s_nop 0
	global_load_dwordx4 v[120:123], v[120:121], off offset:256
	ds_read_b128 v[202:205], v181 offset:2368
	s_waitcnt lgkmcnt(4)
	v_mfma_f32_16x16x32_bf16 v[8:11], v[182:185], v[246:249], v[8:11]
	ds_read_b128 v[182:185], v206 offset:36928
	v_mfma_f32_16x16x32_bf16 v[4:7], v[186:189], v[246:249], v[4:7]
	ds_read_b128 v[186:189], v206 offset:39232
	v_mfma_f32_16x16x32_bf16 v[0:3], v[190:193], v[246:249], v[0:3]
	ds_read_b128 v[190:193], v206 offset:41536
	s_waitcnt vmcnt(7)
	ds_write_b128 v252, v[124:127] offset:36864
	v_mfma_f32_16x16x32_bf16 v[16:19], v[194:197], v[246:249], v[16:19]
	ds_read_b128 v[194:197], v206 offset:43840
	ds_read_b128 v[242:245], v181 offset:4672
	s_waitcnt lgkmcnt(5)
	v_mfma_f32_16x16x32_bf16 v[156:159], v[182:185], v[198:201], v[156:159]
	v_lshl_add_u64 v[124:125], v[164:165], 1, s[44:45]
	s_nop 0
	global_load_dwordx4 v[124:127], v[124:125], off offset:256
	s_waitcnt lgkmcnt(4)
	v_mfma_f32_16x16x32_bf16 v[152:155], v[186:189], v[198:201], v[152:155]
	s_waitcnt lgkmcnt(3)
	v_mfma_f32_16x16x32_bf16 v[148:151], v[190:193], v[198:201], v[148:151]
	s_waitcnt lgkmcnt(1)
	v_mfma_f32_16x16x32_bf16 v[144:147], v[194:197], v[198:201], v[144:147]
	s_waitcnt vmcnt(7)
	ds_write_b128 v253, v[136:139] offset:36864
	ds_read_b128 v[246:249], v181 offset:6976
	v_mfma_f32_16x16x32_bf16 v[108:111], v[182:185], v[202:205], v[108:111]
	v_mfma_f32_16x16x32_bf16 v[104:107], v[186:189], v[202:205], v[104:107]
	v_lshl_add_u64 v[136:137], v[166:167], 1, s[44:45]
	s_nop 0
	global_load_dwordx4 v[136:139], v[136:137], off offset:256
	v_mfma_f32_16x16x32_bf16 v[100:103], v[190:193], v[202:205], v[100:103]
	v_mfma_f32_16x16x32_bf16 v[96:99], v[194:197], v[202:205], v[96:99]
	ds_read_b128 v[198:201], v181 offset:9280
	s_waitcnt lgkmcnt(3)
	v_mfma_f32_16x16x32_bf16 v[92:95], v[182:185], v[242:245], v[92:95]
	v_mfma_f32_16x16x32_bf16 v[88:91], v[186:189], v[242:245], v[88:91]
	v_mfma_f32_16x16x32_bf16 v[84:87], v[190:193], v[242:245], v[84:87]
	v_mfma_f32_16x16x32_bf16 v[80:83], v[194:197], v[242:245], v[80:83]
	ds_read_b128 v[202:205], v181 offset:11584
	s_waitcnt lgkmcnt(2)
	v_mfma_f32_16x16x32_bf16 v[76:79], v[182:185], v[246:249], v[76:79]
	v_mfma_f32_16x16x32_bf16 v[72:75], v[186:189], v[246:249], v[72:75]
	v_mfma_f32_16x16x32_bf16 v[68:71], v[190:193], v[246:249], v[68:71]
	v_mfma_f32_16x16x32_bf16 v[64:67], v[194:197], v[246:249], v[64:67]
	ds_read_b128 v[242:245], v181 offset:13888
	s_waitcnt lgkmcnt(2)
	v_mfma_f32_16x16x32_bf16 v[60:63], v[182:185], v[198:201], v[60:63]
	v_mfma_f32_16x16x32_bf16 v[56:59], v[186:189], v[198:201], v[56:59]
	v_mfma_f32_16x16x32_bf16 v[52:55], v[190:193], v[198:201], v[52:55]
	v_mfma_f32_16x16x32_bf16 v[48:51], v[194:197], v[198:201], v[48:51]
	ds_read_b128 v[246:249], v181 offset:16192
	s_waitcnt lgkmcnt(2)
	v_mfma_f32_16x16x32_bf16 v[44:47], v[182:185], v[202:205], v[44:47]
	v_mfma_f32_16x16x32_bf16 v[40:43], v[186:189], v[202:205], v[40:43]
	v_mfma_f32_16x16x32_bf16 v[36:39], v[190:193], v[202:205], v[36:39]
	v_mfma_f32_16x16x32_bf16 v[32:35], v[194:197], v[202:205], v[32:35]
	s_add_i32 s43, s43, 1
	s_and_b32 s98, s43, 1
	s_mul_i32 s98, s98, 0x12000
	v_add3_u32 v206, s98, v171, v180
	v_add3_u32 v181, s98, v170, v180
	s_cmp_lg_u32 s43, 16
	s_waitcnt lgkmcnt(0)
	s_barrier
	s_cbranch_scc0 .Lgm14_exit
	ds_read_b128 v[198:201], v181
	ds_read_b128 v[202:205], v181 offset:2304
	v_mfma_f32_16x16x32_bf16 v[28:31], v[182:185], v[242:245], v[28:31]
	v_mfma_f32_16x16x32_bf16 v[8:11], v[182:185], v[246:249], v[8:11]
	ds_read_b128 v[182:185], v206 offset:36864
	v_mfma_f32_16x16x32_bf16 v[24:27], v[186:189], v[242:245], v[24:27]
	v_mfma_f32_16x16x32_bf16 v[4:7], v[186:189], v[246:249], v[4:7]
	ds_read_b128 v[186:189], v206 offset:39168
	v_mfma_f32_16x16x32_bf16 v[20:23], v[190:193], v[242:245], v[20:23]
	v_mfma_f32_16x16x32_bf16 v[0:3], v[190:193], v[246:249], v[0:3]
	ds_read_b128 v[190:193], v206 offset:41472
	v_mfma_f32_16x16x32_bf16 v[12:15], v[194:197], v[242:245], v[12:15]
	v_mfma_f32_16x16x32_bf16 v[16:19], v[194:197], v[246:249], v[16:19]
	ds_read_b128 v[194:197], v206 offset:43776
	s_branch .Lgm14_main

; DI f32x4 mfma16(bf16x8 a, bf16x8 b, f32x4 c) { return __builtin_amdgcn_mfma_f32_16x16x32_bf16(a, b, c, 0, 0, 0); }
; template <int MI, int NJ, bool SWAP, class AP, class BP>
; DI void gemm_main(f32x4 (&acc)[MI][NJ], const AP& ap, int a_kstep, const BP& bp, int b_kstep, int nk, bf16_t* smem) {
;     ...
;   auto gload = [&](int kt) {
;     const bf16_t* ab = ap.base + (size_t)kt * a_kstep; const bf16_t* bb = bp.base + (size_t)kt * b_kstep;
; #pragma unroll
;     for (int i = 0; i < CA; ++i) ra[i] = *(const u32x4*)(ab + pa[i]);
; #pragma unroll
;     for (int i = 0; i < CB; ++i) rb[i] = *(const u32x4*)(bb + pb[i]);
;   };
;   auto sstore = [&](int buf) {
;     bf16_t* As = smem + buf * L::STAGE; bf16_t* Bs = As + L::A_ELEMS;
; #pragma unroll
;     for (int i = 0; i < CA; ++i) { const int c = tid + NTHR * i; *(u32x4*)(As + (c >> 3) * LDT + (c & 7) * 8) = oka[i] ? ra[i] : (u32x4){0u, 0u, 0u, 0u}; }
; #pragma unroll
;     for (int i = 0; i < CB; ++i) { const int c = tid + NTHR * i; *(u32x4*)(Bs + (c >> 3) * LDT + (c & 7) * 8) = rb[i]; }
;     ...
;   for (int kt = 0; kt < nk; ++kt) {
;     const int buf = kt & 1;
;     sstore(buf ^ 1);
;     gload(kt + 2 < nk ? kt + 2 : nk - 1);
;     __builtin_amdgcn_sched_barrier(0);
;     const bf16_t* As = smem + buf * L::STAGE + (wm * 16 * MI + l15) * LDT + quad * 8;
;     const bf16_t* Bs = smem + buf * L::STAGE + L::A_ELEMS + (wn * 16 * NJ + l15) * LDT + quad * 8;
; #pragma unroll
;     for (int ks = 0; ks < 2; ++ks) {
;       if (MI * NJ >= 32 && ks == 1) asm volatile("" ::: "memory");
;       bf16x8 b[NJ];
; #pragma unroll
;       for (int j = 0; j < NJ; ++j) b[j] = *(const bf16x8*)(Bs + j * 16 * LDT + ks * 32);
; #pragma unroll
;       for (int i = 0; i < MI; ++i) {
;         const bf16x8 a = *(const bf16x8*)(As + i * 16 * LDT + ks * 32);
; #pragma unroll
;         for (int j = 0; j < NJ; ++j) acc[i][j] = SWAP ? mfma16(b[j], a, acc[i][j]) : mfma16(a, b[j], acc[i][j]);
;       }
;     }
.Lgm15_main:
	ds_read_b128 v[242:245], v177 offset:4608
	s_waitcnt lgkmcnt(4)
	v_mfma_f32_16x16x32_bf16 v[156:159], v[178:181], v[194:197], v[156:159]
	s_and_b32 s17, s16, 1
	s_min_u32 s18, s16, 41
	s_xor_b32 s19, s17, 1
	s_mul_i32 s19, s19, 0x12000
	v_add3_u32 v250, s19, v172, v170
	s_waitcnt vmcnt(7)
	ds_write_b128 v250, v[112:115]
	s_waitcnt lgkmcnt(4)
	v_mfma_f32_16x16x32_bf16 v[152:155], v[182:185], v[194:197], v[152:155]
	s_waitcnt lgkmcnt(3)
	v_mfma_f32_16x16x32_bf16 v[148:151], v[186:189], v[194:197], v[148:151]
	s_lshl_b32 s20, s18, 7
	s_add_u32 s18, s2, s20
	v_add3_u32 v251, s19, v173, v170
	v_add3_u32 v252, s19, v174, v170
	v_add3_u32 v253, s19, v175, v170
	s_addc_u32 s19, s3, 0
	v_lshl_add_u64 v[112:113], s[18:19], 0, v[162:163]
	s_nop 0
	global_load_dwordx4 v[112:115], v[112:113], off offset:256
	s_waitcnt lgkmcnt(2)
	v_mfma_f32_16x16x32_bf16 v[144:147], v[190:193], v[194:197], v[144:147]
	ds_read_b128 v[246:249], v177 offset:6912
	v_mfma_f32_16x16x32_bf16 v[108:111], v[178:181], v[198:201], v[108:111]
	v_mfma_f32_16x16x32_bf16 v[104:107], v[182:185], v[198:201], v[104:107]
	s_waitcnt vmcnt(7)
	ds_write_b128 v251, v[116:119]
	v_mfma_f32_16x16x32_bf16 v[100:103], v[186:189], v[198:201], v[100:103]
	v_mfma_f32_16x16x32_bf16 v[96:99], v[190:193], v[198:201], v[96:99]
	v_lshl_add_u64 v[116:117], s[18:19], 0, v[164:165]
	s_nop 0
	global_load_dwordx4 v[116:119], v[116:117], off offset:256
	ds_read_b128 v[194:197], v177 offset:9216
	s_waitcnt lgkmcnt(4)
	v_mfma_f32_16x16x32_bf16 v[92:95], v[178:181], v[242:245], v[92:95]
	v_mfma_f32_16x16x32_bf16 v[88:91], v[182:185], v[242:245], v[88:91]
	v_mfma_f32_16x16x32_bf16 v[84:87], v[186:189], v[242:245], v[84:87]
	s_waitcnt vmcnt(7)
	ds_write_b128 v252, v[120:123]
	v_mfma_f32_16x16x32_bf16 v[80:83], v[190:193], v[242:245], v[80:83]
	ds_read_b128 v[198:201], v177 offset:11520
	s_waitcnt lgkmcnt(4)
	v_mfma_f32_16x16x32_bf16 v[76:79], v[178:181], v[246:249], v[76:79]
	v_lshl_add_u64 v[120:121], s[18:19], 0, v[166:167]
	s_nop 0
	global_load_dwordx4 v[120:123], v[120:121], off offset:256
	v_mfma_f32_16x16x32_bf16 v[72:75], v[182:185], v[246:249], v[72:75]
	v_mfma_f32_16x16x32_bf16 v[68:71], v[186:189], v[246:249], v[68:71]
	v_mfma_f32_16x16x32_bf16 v[64:67], v[190:193], v[246:249], v[64:67]
	s_waitcnt vmcnt(7)
	ds_write_b128 v253, v[124:127]
	ds_read_b128 v[242:245], v177 offset:13824
	s_waitcnt lgkmcnt(4)
	v_mfma_f32_16x16x32_bf16 v[60:63], v[178:181], v[194:197], v[60:63]
	v_mfma_f32_16x16x32_bf16 v[56:59], v[182:185], v[194:197], v[56:59]
	v_lshl_add_u64 v[124:125], s[18:19], 0, v[168:169]
	s_nop 0
	global_load_dwordx4 v[124:127], v[124:125], off offset:256
	v_mfma_f32_16x16x32_bf16 v[52:55], v[186:189], v[194:197], v[52:55]
	v_mfma_f32_16x16x32_bf16 v[48:51], v[190:193], v[194:197], v[48:51]
	ds_read_b128 v[246:249], v177 offset:16128
	s_waitcnt lgkmcnt(3)
	v_mfma_f32_16x16x32_bf16 v[44:47], v[178:181], v[198:201], v[44:47]
	s_waitcnt vmcnt(7)
	ds_write_b128 v250, v[128:131] offset:36864
	v_mfma_f32_16x16x32_bf16 v[40:43], v[182:185], v[198:201], v[40:43]
	v_mfma_f32_16x16x32_bf16 v[36:39], v[186:189], v[198:201], v[36:39]
	s_add_u32 s18, s4, s20
	s_addc_u32 s19, s5, 0
	v_lshl_add_u64 v[128:129], s[18:19], 0, v[162:163]
	s_nop 0
	global_load_dwordx4 v[128:131], v[128:129], off offset:256
	v_mfma_f32_16x16x32_bf16 v[32:35], v[190:193], v[198:201], v[32:35]
	ds_read_b128 v[194:197], v177 offset:64
	s_waitcnt lgkmcnt(3)
	v_mfma_f32_16x16x32_bf16 v[28:31], v[178:181], v[242:245], v[28:31]
	v_mfma_f32_16x16x32_bf16 v[24:27], v[182:185], v[242:245], v[24:27]
	s_waitcnt vmcnt(7)
	ds_write_b128 v251, v[132:135] offset:36864
	v_mfma_f32_16x16x32_bf16 v[20:23], v[186:189], v[242:245], v[20:23]
	v_mfma_f32_16x16x32_bf16 v[16:19], v[190:193], v[242:245], v[16:19]
	v_lshl_add_u64 v[132:133], s[18:19], 0, v[164:165]
	s_nop 0
	global_load_dwordx4 v[132:135], v[132:133], off offset:256
	ds_read_b128 v[198:201], v177 offset:2368
	s_waitcnt lgkmcnt(4)
; DI f32x4 mfma16(bf16x8 a, bf16x8 b, f32x4 c) { return __builtin_amdgcn_mfma_f32_16x16x32_bf16(a, b, c, 0, 0, 0); }
; template <int MI, int NJ, bool SWAP, class AP, class BP>
; DI void gemm_main(f32x4 (&acc)[MI][NJ], const AP& ap, int a_kstep, const BP& bp, int b_kstep, int nk, bf16_t* smem) {
;     ...
;   auto gload = [&](int kt) {
;     const bf16_t* ab = ap.base + (size_t)kt * a_kstep; const bf16_t* bb = bp.base + (size_t)kt * b_kstep;
; #pragma unroll
;     for (int i = 0; i < CA; ++i) ra[i] = *(const u32x4*)(ab + pa[i]);
; #pragma unroll
;     for (int i = 0; i < CB; ++i) rb[i] = *(const u32x4*)(bb + pb[i]);
;   };
;   auto sstore = [&](int buf) {
;     bf16_t* As = smem + buf * L::STAGE; bf16_t* Bs = As + L::A_ELEMS;
; #pragma unroll
;     for (int i = 0; i < CA; ++i) { const int c = tid + NTHR * i; *(u32x4*)(As + (c >> 3) * LDT + (c & 7) * 8) = oka[i] ? ra[i] : (u32x4){0u, 0u, 0u, 0u}; }
; #pragma unroll
;     for (int i = 0; i < CB; ++i) { const int c = tid + NTHR * i; *(u32x4*)(Bs + (c >> 3) * LDT + (c & 7) * 8) = rb[i]; }
;     ...
;   for (int kt = 0; kt < nk; ++kt) {
;     const int buf = kt & 1;
;     sstore(buf ^ 1);
;     gload(kt + 2 < nk ? kt + 2 : nk - 1);
;     __builtin_amdgcn_sched_barrier(0);
;     const bf16_t* As = smem + buf * L::STAGE + (wm * 16 * MI + l15) * LDT + quad * 8;
;     const bf16_t* Bs = smem + buf * L::STAGE + L::A_ELEMS + (wn * 16 * NJ + l15) * LDT + quad * 8;
; #pragma unroll
;     for (int ks = 0; ks < 2; ++ks) {
;       if (MI * NJ >= 32 && ks == 1) asm volatile("" ::: "memory");
;       bf16x8 b[NJ];
; #pragma unroll
;       for (int j = 0; j < NJ; ++j) b[j] = *(const bf16x8*)(Bs + j * 16 * LDT + ks * 32);
; #pragma unroll
;       for (int i = 0; i < MI; ++i) {
;         const bf16x8 a = *(const bf16x8*)(As + i * 16 * LDT + ks * 32);
; #pragma unroll
;         for (int j = 0; j < NJ; ++j) acc[i][j] = SWAP ? mfma16(b[j], a, acc[i][j]) : mfma16(a, b[j], acc[i][j]);
;       }
;     }
;     __syncthreads();
;   }
	v_mfma_f32_16x16x32_bf16 v[8:11], v[178:181], v[246:249], v[8:11]
	ds_read_b128 v[178:181], v202 offset:36928
	v_mfma_f32_16x16x32_bf16 v[4:7], v[182:185], v[246:249], v[4:7]
	ds_read_b128 v[182:185], v202 offset:39232
	v_mfma_f32_16x16x32_bf16 v[0:3], v[186:189], v[246:249], v[0:3]
	ds_read_b128 v[186:189], v202 offset:41536
	s_waitcnt vmcnt(7)
	ds_write_b128 v252, v[136:139] offset:36864
	v_mfma_f32_16x16x32_bf16 v[12:15], v[190:193], v[246:249], v[12:15]
	ds_read_b128 v[190:193], v202 offset:43840
	ds_read_b128 v[242:245], v177 offset:4672
	s_waitcnt lgkmcnt(5)
	v_mfma_f32_16x16x32_bf16 v[156:159], v[178:181], v[194:197], v[156:159]
	v_lshl_add_u64 v[136:137], s[18:19], 0, v[166:167]
	s_nop 0
	global_load_dwordx4 v[136:139], v[136:137], off offset:256
	s_waitcnt lgkmcnt(4)
	v_mfma_f32_16x16x32_bf16 v[152:155], v[182:185], v[194:197], v[152:155]
	s_waitcnt lgkmcnt(3)
	v_mfma_f32_16x16x32_bf16 v[148:151], v[186:189], v[194:197], v[148:151]
	s_waitcnt lgkmcnt(1)
	v_mfma_f32_16x16x32_bf16 v[144:147], v[190:193], v[194:197], v[144:147]
	s_waitcnt vmcnt(7)
	ds_write_b128 v253, v[140:143] offset:36864
	ds_read_b128 v[246:249], v177 offset:6976
	v_mfma_f32_16x16x32_bf16 v[108:111], v[178:181], v[198:201], v[108:111]
	v_mfma_f32_16x16x32_bf16 v[104:107], v[182:185], v[198:201], v[104:107]
	v_lshl_add_u64 v[140:141], s[18:19], 0, v[168:169]
	s_nop 0
	global_load_dwordx4 v[140:143], v[140:141], off offset:256
	v_mfma_f32_16x16x32_bf16 v[100:103], v[186:189], v[198:201], v[100:103]
	v_mfma_f32_16x16x32_bf16 v[96:99], v[190:193], v[198:201], v[96:99]
	ds_read_b128 v[194:197], v177 offset:9280
	s_waitcnt lgkmcnt(3)
	v_mfma_f32_16x16x32_bf16 v[92:95], v[178:181], v[242:245], v[92:95]
	v_mfma_f32_16x16x32_bf16 v[88:91], v[182:185], v[242:245], v[88:91]
	v_mfma_f32_16x16x32_bf16 v[84:87], v[186:189], v[242:245], v[84:87]
	v_mfma_f32_16x16x32_bf16 v[80:83], v[190:193], v[242:245], v[80:83]
	ds_read_b128 v[198:201], v177 offset:11584
	s_waitcnt lgkmcnt(2)
	v_mfma_f32_16x16x32_bf16 v[76:79], v[178:181], v[246:249], v[76:79]
	v_mfma_f32_16x16x32_bf16 v[72:75], v[182:185], v[246:249], v[72:75]
	v_mfma_f32_16x16x32_bf16 v[68:71], v[186:189], v[246:249], v[68:71]
	v_mfma_f32_16x16x32_bf16 v[64:67], v[190:193], v[246:249], v[64:67]
	ds_read_b128 v[242:245], v177 offset:13888
	s_waitcnt lgkmcnt(2)
	v_mfma_f32_16x16x32_bf16 v[60:63], v[178:181], v[194:197], v[60:63]
	v_mfma_f32_16x16x32_bf16 v[56:59], v[182:185], v[194:197], v[56:59]
	v_mfma_f32_16x16x32_bf16 v[52:55], v[186:189], v[194:197], v[52:55]
	v_mfma_f32_16x16x32_bf16 v[48:51], v[190:193], v[194:197], v[48:51]
	ds_read_b128 v[246:249], v177 offset:16192
	s_waitcnt lgkmcnt(2)
	v_mfma_f32_16x16x32_bf16 v[44:47], v[178:181], v[198:201], v[44:47]
	v_mfma_f32_16x16x32_bf16 v[40:43], v[182:185], v[198:201], v[40:43]
	v_mfma_f32_16x16x32_bf16 v[36:39], v[186:189], v[198:201], v[36:39]
	v_mfma_f32_16x16x32_bf16 v[32:35], v[190:193], v[198:201], v[32:35]
	s_add_i32 s16, s16, 1
	s_and_b32 s98, s16, 1
	s_mul_i32 s98, s98, 0x12000
	v_add3_u32 v202, s98, v160, v176
	v_add3_u32 v177, s98, v171, v176
	s_cmp_lg_u32 s16, 44
	s_waitcnt lgkmcnt(0)
	s_barrier
	s_cbranch_scc0 .Lgm15_exit
	ds_read_b128 v[194:197], v177
	ds_read_b128 v[198:201], v177 offset:2304
	v_mfma_f32_16x16x32_bf16 v[28:31], v[178:181], v[242:245], v[28:31]
	v_mfma_f32_16x16x32_bf16 v[8:11], v[178:181], v[246:249], v[8:11]
	ds_read_b128 v[178:181], v202 offset:36864
	v_mfma_f32_16x16x32_bf16 v[24:27], v[182:185], v[242:245], v[24:27]
	v_mfma_f32_16x16x32_bf16 v[4:7], v[182:185], v[246:249], v[4:7]
	ds_read_b128 v[182:185], v202 offset:39168
	v_mfma_f32_16x16x32_bf16 v[20:23], v[186:189], v[242:245], v[20:23]
	v_mfma_f32_16x16x32_bf16 v[0:3], v[186:189], v[246:249], v[0:3]
	ds_read_b128 v[186:189], v202 offset:41472
	v_mfma_f32_16x16x32_bf16 v[16:19], v[190:193], v[242:245], v[16:19]
	v_mfma_f32_16x16x32_bf16 v[12:15], v[190:193], v[246:249], v[12:15]
	ds_read_b128 v[190:193], v202 offset:43776
	s_branch .Lgm15_main
